# GEMM K-loops: removed s_setprio toggles and the redundant post-barrier lgkmcnt(0) wait (shorter barrier-to-first-MFMA handoff)
# speedup vs baseline: 1.0170x; 1.0006x over previous
; #define PG8_STAGE(bufoff, gbase, voff) do { _Pragma("unroll") for (int _i = 0; _i < 2; ++_i) \
;         __builtin_amdgcn_global_load_lds((const unsigned*)((const char*)(gbase) + (voff)[_i]), (PG8_LAS unsigned*)(lds + (bufoff) + ldsw + _i * 8192), 16, 0, 0); } while (0)
; #define PG8_LDA(dst, b, h) do { _Pragma("unroll") for (int m = 0; m < 4; ++m) _Pragma("unroll") for (int k = 0; k < 2; ++k) dst[m][k] = *(const PG8_LAS bf16x8*)(lds + PG8_SA(b, h) + aoff + m * 2048 + k * 1024); } while (0)
; #define PG8_LDB(dst, b, h) do { _Pragma("unroll") for (int n = 0; n < 2; ++n) _Pragma("unroll") for (int k = 0; k < 2; ++k) dst[n][k] = *(const PG8_LAS bf16x8*)(lds + PG8_SB(b, h) + boff + n * 2048 + k * 1024); } while (0)
; #define PG8_MMA(ai, bj, At, Bt) do { __builtin_amdgcn_s_setprio(1); _Pragma("unroll") for (int m = 0; m < 4; ++m) _Pragma("unroll") for (int n = 0; n < 2; ++n) _Pragma("unroll") for (int k = 0; k < 2; ++k) \
;         acc[ai][bj][m][n] = __builtin_amdgcn_mfma_f32_16x16x32_bf16(Bt[n][k], At[m][k], acc[ai][bj][m][n], 0, 0, 0); __builtin_amdgcn_s_setprio(0); } while (0)
; #define PG8_WAIT_V(n) asm volatile("s_waitcnt vmcnt(" #n ")" ::: "memory")
; #define PG8_WAIT_L(n) asm volatile("s_waitcnt lgkmcnt(" #n ")" ::: "memory")
; template <class Epi, class Sched, bool ALIGN_EPI = false, bool SP2 = false>
; __device__ __forceinline__ void gemm_phase(PG8_LAS unsigned char* lds, const Gemm g, const Sched& S, const Epi& E) {
;     ...
;             const bool last = (t == nt - 2);
;             const char* a1 = cA + (size_t)(t + 1) * kstep;
;             const char* a2 = last ? nA : cA + (size_t)(t + 2) * kstep; const char* b2 = last ? nB : cB + (size_t)(t + 2) * kstep;
;             const char* a3 = a2 + kstep; const char* b3 = b2 + kstep;
;             if (last && has_next) S.a_ready(nxt);
;             if constexpr (SP2) {
;             PG8_LDB(B0, 0, 0); PG8_LDB(B1, 0, 1); PG8_SCHED; PG8_LDA(At, 0, 0); PG8_STAGE(PG8_SA(1, 1), a1 + hstep, voffA);
;             PG8_WAIT_V(8); PG8_WAIT_L(0); PG8_BAR; PG8_MMA(0, 0, At, B0); PG8_MMA(0, 1, At, B1); PG8_BAR; PG8_SCHED;
;             PG8_LDA(At, 0, 1); PG8_STAGE(PG8_SB(0, 0), b2, voffB); PG8_STAGE(PG8_SB(0, 1), b2 + hstep, voffB); PG8_STAGE(PG8_SA(0, 0), a2, voffA);
;             PG8_WAIT_V(8); PG8_WAIT_L(0); PG8_BAR; PG8_MMA(1, 0, At, B0); PG8_MMA(1, 1, At, B1); PG8_BAR; PG8_SCHED;
.LBB0_66:
	s_add_u32 s61, s90, 0xfffc0080
	s_addc_u32 s72, s91, -1
	s_add_i32 s73, 0, 0x10000
	s_cmp_eq_u32 s80, 12
	s_cselect_b32 s95, s47, s72
	s_cselect_b32 s94, vcc_lo, s61
	v_add_u32_e32 v147, s73, v139
	s_cselect_b32 s93, s45, s7
	s_cselect_b32 s92, vcc_hi, s4
	s_add_i32 s61, 0, 0x14000
	ds_read_b128 v[170:173], v147
	ds_read_b128 v[174:177], v147 offset:1024
	ds_read_b128 v[178:181], v147 offset:2048
	ds_read_b128 v[182:185], v147 offset:3072
	v_add_u32_e32 v147, s61, v139
	ds_read_b128 v[196:199], v147
	ds_read_b128 v[200:203], v147 offset:1024
	ds_read_b128 v[204:207], v147 offset:2048
	ds_read_b128 v[208:211], v147 offset:3072
	v_lshl_add_u64 v[160:161], s[90:91], 0, v[150:151]
	s_add_i32 m0, s8, 0xc000
	ds_read_b128 v[212:215], v143
	ds_read_b128 v[216:219], v143 offset:1024
	ds_read_b128 v[220:223], v143 offset:2048
	ds_read_b128 v[224:227], v143 offset:3072
	ds_read_b128 v[228:231], v143 offset:4096
	ds_read_b128 v[232:235], v143 offset:5120
	ds_read_b128 v[236:239], v143 offset:6144
	ds_read_b128 v[240:243], v143 offset:7168
	global_load_lds_dwordx4 v[160:161], off
	v_lshl_add_u64 v[160:161], s[90:91], 0, v[148:149]
	s_add_i32 m0, s8, 0xe000
	s_nop 0
	global_load_lds_dwordx4 v[160:161], off
	s_waitcnt vmcnt(8)
	s_waitcnt lgkmcnt(0)
	s_barrier
	v_mfma_f32_16x16x32_bf16 v[126:129], v[170:173], v[212:215], v[126:129]
	v_mfma_f32_16x16x32_bf16 v[122:125], v[178:181], v[212:215], v[122:125]
	v_mfma_f32_16x16x32_bf16 v[110:113], v[170:173], v[220:223], v[110:113]
	v_mfma_f32_16x16x32_bf16 v[106:109], v[178:181], v[220:223], v[106:109]
	v_mfma_f32_16x16x32_bf16 v[94:97], v[170:173], v[228:231], v[94:97]
	v_mfma_f32_16x16x32_bf16 v[90:93], v[178:181], v[228:231], v[90:93]
	v_mfma_f32_16x16x32_bf16 v[78:81], v[170:173], v[236:239], v[78:81]
	v_mfma_f32_16x16x32_bf16 v[74:77], v[178:181], v[236:239], v[74:77]
	v_mfma_f32_16x16x32_bf16 v[126:129], v[174:177], v[216:219], v[126:129]
	v_mfma_f32_16x16x32_bf16 v[122:125], v[182:185], v[216:219], v[122:125]
	v_mfma_f32_16x16x32_bf16 v[110:113], v[174:177], v[224:227], v[110:113]
	v_mfma_f32_16x16x32_bf16 v[106:109], v[182:185], v[224:227], v[106:109]
	v_mfma_f32_16x16x32_bf16 v[94:97], v[174:177], v[232:235], v[94:97]
	v_mfma_f32_16x16x32_bf16 v[90:93], v[182:185], v[232:235], v[90:93]
	v_mfma_f32_16x16x32_bf16 v[78:81], v[174:177], v[240:243], v[78:81]
	v_mfma_f32_16x16x32_bf16 v[74:77], v[182:185], v[240:243], v[74:77]
	v_mfma_f32_16x16x32_bf16 v[118:121], v[196:199], v[212:215], v[118:121]
	v_mfma_f32_16x16x32_bf16 v[114:117], v[204:207], v[212:215], v[114:117]
	v_mfma_f32_16x16x32_bf16 v[102:105], v[196:199], v[220:223], v[102:105]
	v_mfma_f32_16x16x32_bf16 v[98:101], v[204:207], v[220:223], v[98:101]
	v_mfma_f32_16x16x32_bf16 v[86:89], v[196:199], v[228:231], v[86:89]
	v_mfma_f32_16x16x32_bf16 v[82:85], v[204:207], v[228:231], v[82:85]
	v_mfma_f32_16x16x32_bf16 v[70:73], v[196:199], v[236:239], v[70:73]
	v_mfma_f32_16x16x32_bf16 v[66:69], v[204:207], v[236:239], v[66:69]
	v_mfma_f32_16x16x32_bf16 v[118:121], v[200:203], v[216:219], v[118:121]
	v_mfma_f32_16x16x32_bf16 v[114:117], v[208:211], v[216:219], v[114:117]
	v_mfma_f32_16x16x32_bf16 v[102:105], v[200:203], v[224:227], v[102:105]
	v_mfma_f32_16x16x32_bf16 v[98:101], v[208:211], v[224:227], v[98:101]
	v_mfma_f32_16x16x32_bf16 v[86:89], v[200:203], v[232:235], v[86:89]
	v_mfma_f32_16x16x32_bf16 v[82:85], v[208:211], v[232:235], v[82:85]
	v_mfma_f32_16x16x32_bf16 v[70:73], v[200:203], v[240:243], v[70:73]
	v_mfma_f32_16x16x32_bf16 v[66:69], v[208:211], v[240:243], v[66:69]
	s_barrier
	s_add_i32 s72, s73, s5
	v_lshl_add_u64 v[160:161], s[92:93], 0, v[132:133]
	s_mov_b32 m0, s72
	ds_read_b128 v[212:215], v143 offset:16384
	ds_read_b128 v[216:219], v143 offset:17408
	ds_read_b128 v[220:223], v143 offset:18432
	ds_read_b128 v[224:227], v143 offset:19456
	ds_read_b128 v[228:231], v143 offset:20480
	ds_read_b128 v[232:235], v143 offset:21504
	ds_read_b128 v[236:239], v143 offset:22528
	ds_read_b128 v[240:243], v143 offset:23552
	global_load_lds_dwordx4 v[160:161], off
	s_add_i32 m0, s72, 0x2000
	s_add_u32 s76, s92, 0x40000
	v_lshl_add_u64 v[244:245], s[92:93], 0, v[136:137]
	s_addc_u32 s77, s93, 0
	s_add_i32 s61, s61, s5
	global_load_lds_dwordx4 v[244:245], off
	v_lshl_add_u64 v[246:247], s[76:77], 0, v[132:133]
	s_mov_b32 m0, s61
	v_lshl_add_u64 v[248:249], s[94:95], 0, v[134:135]
	global_load_lds_dwordx4 v[246:247], off
	v_lshl_add_u64 v[246:247], s[76:77], 0, v[136:137]
	s_add_i32 m0, s61, 0x2000
	s_nop 0
	global_load_lds_dwordx4 v[246:247], off
	v_lshl_add_u64 v[246:247], s[94:95], 0, v[130:131]
	s_mov_b32 m0, s8
	s_nop 0
	global_load_lds_dwordx4 v[246:247], off
	s_mov_b32 m0, s9
	s_nop 0
	global_load_lds_dwordx4 v[248:249], off
	s_waitcnt vmcnt(8)
	s_waitcnt lgkmcnt(0)
	s_barrier
; #define PG8_STAGE(bufoff, gbase, voff) do { _Pragma("unroll") for (int _i = 0; _i < 2; ++_i) \
;         __builtin_amdgcn_global_load_lds((const unsigned*)((const char*)(gbase) + (voff)[_i]), (PG8_LAS unsigned*)(lds + (bufoff) + ldsw + _i * 8192), 16, 0, 0); } while (0)
; #define PG8_LDA(dst, b, h) do { _Pragma("unroll") for (int m = 0; m < 4; ++m) _Pragma("unroll") for (int k = 0; k < 2; ++k) dst[m][k] = *(const PG8_LAS bf16x8*)(lds + PG8_SA(b, h) + aoff + m * 2048 + k * 1024); } while (0)
; #define PG8_LDB(dst, b, h) do { _Pragma("unroll") for (int n = 0; n < 2; ++n) _Pragma("unroll") for (int k = 0; k < 2; ++k) dst[n][k] = *(const PG8_LAS bf16x8*)(lds + PG8_SB(b, h) + boff + n * 2048 + k * 1024); } while (0)
; #define PG8_MMA(ai, bj, At, Bt) do { __builtin_amdgcn_s_setprio(1); _Pragma("unroll") for (int m = 0; m < 4; ++m) _Pragma("unroll") for (int n = 0; n < 2; ++n) _Pragma("unroll") for (int k = 0; k < 2; ++k) \
;         acc[ai][bj][m][n] = __builtin_amdgcn_mfma_f32_16x16x32_bf16(Bt[n][k], At[m][k], acc[ai][bj][m][n], 0, 0, 0); __builtin_amdgcn_s_setprio(0); } while (0)
; #define PG8_WAIT_V(n) asm volatile("s_waitcnt vmcnt(" #n ")" ::: "memory")
; #define PG8_WAIT_L(n) asm volatile("s_waitcnt lgkmcnt(" #n ")" ::: "memory")
; #define PG8_BAR __builtin_amdgcn_s_barrier()
; #define PG8_SCHED __builtin_amdgcn_sched_barrier(0)
; template <class Epi, class Sched, bool ALIGN_EPI = false, bool SP2 = false>
; __device__ __forceinline__ void gemm_phase(PG8_LAS unsigned char* lds, const Gemm g, const Sched& S, const Epi& E) {
;     ...
;             PG8_WAIT_V(8); PG8_WAIT_L(0); PG8_BAR; PG8_MMA(1, 0, At, B0); PG8_MMA(1, 1, At, B1); PG8_BAR; PG8_SCHED;
;             PG8_LDB(B0, 1, 0); PG8_LDB(B1, 1, 1); PG8_SCHED; PG8_LDA(At, 1, 0); PG8_STAGE(PG8_SA(0, 1), a2 + hstep, voffA);
;             PG8_WAIT_V(8); PG8_WAIT_L(0); PG8_BAR; PG8_MMA(0, 0, At, B0); PG8_MMA(0, 1, At, B1); PG8_BAR; PG8_SCHED;
	v_mfma_f32_16x16x32_bf16 v[62:65], v[170:173], v[212:215], v[62:65]
	v_mfma_f32_16x16x32_bf16 v[58:61], v[178:181], v[212:215], v[58:61]
	v_mfma_f32_16x16x32_bf16 v[50:53], v[170:173], v[220:223], v[50:53]
	v_mfma_f32_16x16x32_bf16 v[42:45], v[178:181], v[220:223], v[42:45]
	v_mfma_f32_16x16x32_bf16 v[34:37], v[170:173], v[228:231], v[34:37]
	v_mfma_f32_16x16x32_bf16 v[24:27], v[178:181], v[228:231], v[24:27]
	v_mfma_f32_16x16x32_bf16 v[16:19], v[170:173], v[236:239], v[16:19]
	v_mfma_f32_16x16x32_bf16 v[8:11], v[178:181], v[236:239], v[8:11]
	v_mfma_f32_16x16x32_bf16 v[62:65], v[174:177], v[216:219], v[62:65]
	v_mfma_f32_16x16x32_bf16 v[58:61], v[182:185], v[216:219], v[58:61]
	v_mfma_f32_16x16x32_bf16 v[50:53], v[174:177], v[224:227], v[50:53]
	v_mfma_f32_16x16x32_bf16 v[42:45], v[182:185], v[224:227], v[42:45]
	v_mfma_f32_16x16x32_bf16 v[34:37], v[174:177], v[232:235], v[34:37]
	v_mfma_f32_16x16x32_bf16 v[24:27], v[182:185], v[232:235], v[24:27]
	v_mfma_f32_16x16x32_bf16 v[16:19], v[174:177], v[240:243], v[16:19]
	v_mfma_f32_16x16x32_bf16 v[8:11], v[182:185], v[240:243], v[8:11]
	v_mfma_f32_16x16x32_bf16 v[54:57], v[196:199], v[212:215], v[54:57]
	v_mfma_f32_16x16x32_bf16 v[46:49], v[204:207], v[212:215], v[46:49]
	v_mfma_f32_16x16x32_bf16 v[38:41], v[196:199], v[220:223], v[38:41]
	v_mfma_f32_16x16x32_bf16 v[28:31], v[204:207], v[220:223], v[28:31]
	v_mfma_f32_16x16x32_bf16 v[20:23], v[196:199], v[228:231], v[20:23]
	v_mfma_f32_16x16x32_bf16 v[12:15], v[204:207], v[228:231], v[12:15]
	v_mfma_f32_16x16x32_bf16 v[4:7], v[196:199], v[236:239], v[4:7]
	v_mfma_f32_16x16x32_bf16 v[0:3], v[204:207], v[236:239], v[0:3]
	v_mfma_f32_16x16x32_bf16 v[54:57], v[200:203], v[216:219], v[54:57]
	v_mfma_f32_16x16x32_bf16 v[46:49], v[208:211], v[216:219], v[46:49]
	v_mfma_f32_16x16x32_bf16 v[38:41], v[200:203], v[224:227], v[38:41]
	v_mfma_f32_16x16x32_bf16 v[28:31], v[208:211], v[224:227], v[28:31]
	v_mfma_f32_16x16x32_bf16 v[20:23], v[200:203], v[232:235], v[20:23]
	v_mfma_f32_16x16x32_bf16 v[12:15], v[208:211], v[232:235], v[12:15]
	v_mfma_f32_16x16x32_bf16 v[4:7], v[200:203], v[240:243], v[4:7]
	v_mfma_f32_16x16x32_bf16 v[0:3], v[208:211], v[240:243], v[0:3]
	s_barrier
	s_add_i32 s61, 0, 0x18000
	v_add_u32_e32 v147, s61, v139
	s_add_i32 s72, 0, 0x1c000
	ds_read_b128 v[170:173], v147
	ds_read_b128 v[174:177], v147 offset:1024
	ds_read_b128 v[178:181], v147 offset:2048
	ds_read_b128 v[182:185], v147 offset:3072
	v_add_u32_e32 v147, s72, v139
	ds_read_b128 v[196:199], v147
	ds_read_b128 v[200:203], v147 offset:1024
	ds_read_b128 v[204:207], v147 offset:2048
	ds_read_b128 v[208:211], v147 offset:3072
	s_add_u32 s76, s94, 0x40000
	s_addc_u32 s77, s95, 0
	s_mov_b32 m0, s89
	v_lshl_add_u64 v[250:251], s[76:77], 0, v[130:131]
	ds_read_b128 v[212:215], v143 offset:32768
	ds_read_b128 v[216:219], v143 offset:33792
	ds_read_b128 v[220:223], v143 offset:34816
	ds_read_b128 v[224:227], v143 offset:35840
	ds_read_b128 v[228:231], v143 offset:36864
	ds_read_b128 v[232:235], v143 offset:37888
	ds_read_b128 v[236:239], v143 offset:38912
	ds_read_b128 v[240:243], v143 offset:39936
	global_load_lds_dwordx4 v[250:251], off
	v_lshl_add_u64 v[250:251], s[76:77], 0, v[134:135]
	s_mov_b32 m0, s96
	s_nop 0
	global_load_lds_dwordx4 v[250:251], off
	s_waitcnt vmcnt(8)
	s_waitcnt lgkmcnt(0)
	s_barrier
	v_mfma_f32_16x16x32_bf16 v[126:129], v[170:173], v[212:215], v[126:129]
	v_mfma_f32_16x16x32_bf16 v[122:125], v[178:181], v[212:215], v[122:125]
	v_mfma_f32_16x16x32_bf16 v[110:113], v[170:173], v[220:223], v[110:113]
	v_mfma_f32_16x16x32_bf16 v[106:109], v[178:181], v[220:223], v[106:109]
	v_mfma_f32_16x16x32_bf16 v[94:97], v[170:173], v[228:231], v[94:97]
	v_mfma_f32_16x16x32_bf16 v[90:93], v[178:181], v[228:231], v[90:93]
	v_mfma_f32_16x16x32_bf16 v[78:81], v[170:173], v[236:239], v[78:81]
	v_mfma_f32_16x16x32_bf16 v[74:77], v[178:181], v[236:239], v[74:77]
	v_mfma_f32_16x16x32_bf16 v[126:129], v[174:177], v[216:219], v[126:129]
	v_mfma_f32_16x16x32_bf16 v[122:125], v[182:185], v[216:219], v[122:125]
	v_mfma_f32_16x16x32_bf16 v[110:113], v[174:177], v[224:227], v[110:113]
	v_mfma_f32_16x16x32_bf16 v[106:109], v[182:185], v[224:227], v[106:109]
	v_mfma_f32_16x16x32_bf16 v[94:97], v[174:177], v[232:235], v[94:97]
	v_mfma_f32_16x16x32_bf16 v[90:93], v[182:185], v[232:235], v[90:93]
	v_mfma_f32_16x16x32_bf16 v[78:81], v[174:177], v[240:243], v[78:81]
	v_mfma_f32_16x16x32_bf16 v[74:77], v[182:185], v[240:243], v[74:77]
	v_mfma_f32_16x16x32_bf16 v[118:121], v[196:199], v[212:215], v[118:121]
	v_mfma_f32_16x16x32_bf16 v[114:117], v[204:207], v[212:215], v[114:117]
	v_mfma_f32_16x16x32_bf16 v[102:105], v[196:199], v[220:223], v[102:105]
	v_mfma_f32_16x16x32_bf16 v[98:101], v[204:207], v[220:223], v[98:101]
	v_mfma_f32_16x16x32_bf16 v[86:89], v[196:199], v[228:231], v[86:89]
	v_mfma_f32_16x16x32_bf16 v[82:85], v[204:207], v[228:231], v[82:85]
	v_mfma_f32_16x16x32_bf16 v[70:73], v[196:199], v[236:239], v[70:73]
	v_mfma_f32_16x16x32_bf16 v[66:69], v[204:207], v[236:239], v[66:69]
	v_mfma_f32_16x16x32_bf16 v[118:121], v[200:203], v[216:219], v[118:121]
	v_mfma_f32_16x16x32_bf16 v[114:117], v[208:211], v[216:219], v[114:117]
	v_mfma_f32_16x16x32_bf16 v[102:105], v[200:203], v[224:227], v[102:105]
	v_mfma_f32_16x16x32_bf16 v[98:101], v[208:211], v[224:227], v[98:101]
	v_mfma_f32_16x16x32_bf16 v[86:89], v[200:203], v[232:235], v[86:89]
	v_mfma_f32_16x16x32_bf16 v[82:85], v[208:211], v[232:235], v[82:85]
	v_mfma_f32_16x16x32_bf16 v[70:73], v[200:203], v[240:243], v[70:73]
	v_mfma_f32_16x16x32_bf16 v[66:69], v[208:211], v[240:243], v[66:69]
	s_barrier
; #define PG8_STAGE(bufoff, gbase, voff) do { _Pragma("unroll") for (int _i = 0; _i < 2; ++_i) \
;         __builtin_amdgcn_global_load_lds((const unsigned*)((const char*)(gbase) + (voff)[_i]), (PG8_LAS unsigned*)(lds + (bufoff) + ldsw + _i * 8192), 16, 0, 0); } while (0)
; #define PG8_LDA(dst, b, h) do { _Pragma("unroll") for (int m = 0; m < 4; ++m) _Pragma("unroll") for (int k = 0; k < 2; ++k) dst[m][k] = *(const PG8_LAS bf16x8*)(lds + PG8_SA(b, h) + aoff + m * 2048 + k * 1024); } while (0)
; #define PG8_MMA(ai, bj, At, Bt) do { __builtin_amdgcn_s_setprio(1); _Pragma("unroll") for (int m = 0; m < 4; ++m) _Pragma("unroll") for (int n = 0; n < 2; ++n) _Pragma("unroll") for (int k = 0; k < 2; ++k) \
;         acc[ai][bj][m][n] = __builtin_amdgcn_mfma_f32_16x16x32_bf16(Bt[n][k], At[m][k], acc[ai][bj][m][n], 0, 0, 0); __builtin_amdgcn_s_setprio(0); } while (0)
; #define PG8_WAIT_V(n) asm volatile("s_waitcnt vmcnt(" #n ")" ::: "memory")
; #define PG8_WAIT_L(n) asm volatile("s_waitcnt lgkmcnt(" #n ")" ::: "memory")
; #define PG8_BAR __builtin_amdgcn_s_barrier()
; #define PG8_SCHED __builtin_amdgcn_sched_barrier(0)
; template <class Epi, class Sched, bool ALIGN_EPI = false, bool SP2 = false>
; __device__ __forceinline__ void gemm_phase(PG8_LAS unsigned char* lds, const Gemm g, const Sched& S, const Epi& E) {
;     ...
;             PG8_LDA(At, 1, 1); PG8_STAGE(PG8_SB(1, 0), b3, voffB); PG8_STAGE(PG8_SB(1, 1), b3 + hstep, voffB); PG8_STAGE(PG8_SA(1, 0), a3, voffA);
;             PG8_WAIT_V(8); PG8_WAIT_L(0); PG8_BAR; PG8_MMA(1, 0, At, B0); PG8_MMA(1, 1, At, B1); PG8_BAR; PG8_SCHED;
;     ...
;         if constexpr (ALIGN_EPI) { if (wr == 0) PG8_BAR; }
	s_add_i32 s61, s61, s5
	v_lshl_add_u64 v[160:161], v[160:161], 0, s[34:35]
	s_mov_b32 m0, s61
	ds_read_b128 v[212:215], v143 offset:49152
	ds_read_b128 v[216:219], v143 offset:50176
	ds_read_b128 v[220:223], v143 offset:51200
	ds_read_b128 v[224:227], v143 offset:52224
	ds_read_b128 v[228:231], v143 offset:53248
	ds_read_b128 v[232:235], v143 offset:54272
	ds_read_b128 v[236:239], v143 offset:55296
	ds_read_b128 v[240:243], v143 offset:56320
	global_load_lds_dwordx4 v[160:161], off
	s_add_i32 m0, s61, 0x2000
	s_add_u32 s76, s92, 0x40080
	v_lshl_add_u64 v[160:161], v[244:245], 0, s[34:35]
	s_addc_u32 s77, s93, 0
	s_add_i32 s61, s72, s5
	global_load_lds_dwordx4 v[160:161], off
	v_lshl_add_u64 v[160:161], s[76:77], 0, v[132:133]
	s_mov_b32 m0, s61
	s_nop 0
	global_load_lds_dwordx4 v[160:161], off
	v_lshl_add_u64 v[160:161], s[76:77], 0, v[136:137]
	s_add_i32 m0, s61, 0x2000
	s_nop 0
	global_load_lds_dwordx4 v[160:161], off
	v_lshl_add_u64 v[160:161], v[246:247], 0, s[34:35]
	s_mov_b32 m0, s0
	s_nop 0
	global_load_lds_dwordx4 v[160:161], off
	v_lshl_add_u64 v[160:161], v[248:249], 0, s[34:35]
	s_mov_b32 m0, s97
	s_nop 0
	global_load_lds_dwordx4 v[160:161], off
	s_waitcnt vmcnt(8)
	s_waitcnt lgkmcnt(0)
	s_barrier
	v_mfma_f32_16x16x32_bf16 v[62:65], v[170:173], v[212:215], v[62:65]
	v_mfma_f32_16x16x32_bf16 v[58:61], v[178:181], v[212:215], v[58:61]
	v_mfma_f32_16x16x32_bf16 v[50:53], v[170:173], v[220:223], v[50:53]
	v_mfma_f32_16x16x32_bf16 v[42:45], v[178:181], v[220:223], v[42:45]
	v_mfma_f32_16x16x32_bf16 v[34:37], v[170:173], v[228:231], v[34:37]
	v_mfma_f32_16x16x32_bf16 v[24:27], v[178:181], v[228:231], v[24:27]
	v_mfma_f32_16x16x32_bf16 v[16:19], v[170:173], v[236:239], v[16:19]
	v_mfma_f32_16x16x32_bf16 v[8:11], v[178:181], v[236:239], v[8:11]
	v_mfma_f32_16x16x32_bf16 v[62:65], v[174:177], v[216:219], v[62:65]
	v_mfma_f32_16x16x32_bf16 v[58:61], v[182:185], v[216:219], v[58:61]
	v_mfma_f32_16x16x32_bf16 v[50:53], v[174:177], v[224:227], v[50:53]
	v_mfma_f32_16x16x32_bf16 v[42:45], v[182:185], v[224:227], v[42:45]
	v_mfma_f32_16x16x32_bf16 v[34:37], v[174:177], v[232:235], v[34:37]
	v_mfma_f32_16x16x32_bf16 v[24:27], v[182:185], v[232:235], v[24:27]
	v_mfma_f32_16x16x32_bf16 v[16:19], v[174:177], v[240:243], v[16:19]
	v_mfma_f32_16x16x32_bf16 v[8:11], v[182:185], v[240:243], v[8:11]
	v_mfma_f32_16x16x32_bf16 v[54:57], v[196:199], v[212:215], v[54:57]
	v_mfma_f32_16x16x32_bf16 v[46:49], v[204:207], v[212:215], v[46:49]
	v_mfma_f32_16x16x32_bf16 v[38:41], v[196:199], v[220:223], v[38:41]
	v_mfma_f32_16x16x32_bf16 v[28:31], v[204:207], v[220:223], v[28:31]
	v_mfma_f32_16x16x32_bf16 v[20:23], v[196:199], v[228:231], v[20:23]
	v_mfma_f32_16x16x32_bf16 v[12:15], v[204:207], v[228:231], v[12:15]
	v_mfma_f32_16x16x32_bf16 v[4:7], v[196:199], v[236:239], v[4:7]
	v_mfma_f32_16x16x32_bf16 v[0:3], v[204:207], v[236:239], v[0:3]
	v_mfma_f32_16x16x32_bf16 v[54:57], v[200:203], v[216:219], v[54:57]
	v_mfma_f32_16x16x32_bf16 v[46:49], v[208:211], v[216:219], v[46:49]
	v_mfma_f32_16x16x32_bf16 v[38:41], v[200:203], v[224:227], v[38:41]
	v_mfma_f32_16x16x32_bf16 v[28:31], v[208:211], v[224:227], v[28:31]
	v_mfma_f32_16x16x32_bf16 v[20:23], v[200:203], v[232:235], v[20:23]
	v_mfma_f32_16x16x32_bf16 v[12:15], v[208:211], v[232:235], v[12:15]
	v_mfma_f32_16x16x32_bf16 v[4:7], v[200:203], v[240:243], v[4:7]
	v_mfma_f32_16x16x32_bf16 v[0:3], v[208:211], v[240:243], v[0:3]
	s_barrier
	s_add_i32 s80, s80, 2
	s_add_u32 s4, s4, 0x100
	s_addc_u32 s7, s7, 0
	s_add_u32 s90, s90, 0x100
	s_addc_u32 s91, s91, 0
	s_cmp_gt_u32 s80, 13
	s_cbranch_scc0 .LBB0_66
	s_and_b64 vcc, exec, s[38:39]
	s_cbranch_vccz .LBB0_69
	s_barrier

; #define PG8_STAGE(bufoff, gbase, voff) do { _Pragma("unroll") for (int _i = 0; _i < 2; ++_i) \
;         __builtin_amdgcn_global_load_lds((const unsigned*)((const char*)(gbase) + (voff)[_i]), (PG8_LAS unsigned*)(lds + (bufoff) + ldsw + _i * 8192), 16, 0, 0); } while (0)
; #define PG8_LDA(dst, b, h) do { _Pragma("unroll") for (int m = 0; m < 4; ++m) _Pragma("unroll") for (int k = 0; k < 2; ++k) dst[m][k] = *(const PG8_LAS bf16x8*)(lds + PG8_SA(b, h) + aoff + m * 2048 + k * 1024); } while (0)
; #define PG8_LDB(dst, b, h) do { _Pragma("unroll") for (int n = 0; n < 2; ++n) _Pragma("unroll") for (int k = 0; k < 2; ++k) dst[n][k] = *(const PG8_LAS bf16x8*)(lds + PG8_SB(b, h) + boff + n * 2048 + k * 1024); } while (0)
; #define PG8_MMA(ai, bj, At, Bt) do { __builtin_amdgcn_s_setprio(1); _Pragma("unroll") for (int m = 0; m < 4; ++m) _Pragma("unroll") for (int n = 0; n < 2; ++n) _Pragma("unroll") for (int k = 0; k < 2; ++k) \
;         acc[ai][bj][m][n] = __builtin_amdgcn_mfma_f32_16x16x32_bf16(Bt[n][k], At[m][k], acc[ai][bj][m][n], 0, 0, 0); __builtin_amdgcn_s_setprio(0); } while (0)
; #define PG8_WAIT_V(n) asm volatile("s_waitcnt vmcnt(" #n ")" ::: "memory")
; #define PG8_WAIT_L(n) asm volatile("s_waitcnt lgkmcnt(" #n ")" ::: "memory")
; template <class Epi, class Sched, bool ALIGN_EPI = false, bool SP2 = false>
; __device__ __forceinline__ void gemm_phase(PG8_LAS unsigned char* lds, const Gemm g, const Sched& S, const Epi& E) {
;     ...
;             const bool last = (t == nt - 2);
;             const char* a1 = cA + (size_t)(t + 1) * kstep;
;             const char* a2 = last ? nA : cA + (size_t)(t + 2) * kstep; const char* b2 = last ? nB : cB + (size_t)(t + 2) * kstep;
;             const char* a3 = a2 + kstep; const char* b3 = b2 + kstep;
;             if (last && has_next) S.a_ready(nxt);
;             if constexpr (SP2) {
;             PG8_LDB(B0, 0, 0); PG8_LDB(B1, 0, 1); PG8_SCHED; PG8_LDA(At, 0, 0); PG8_STAGE(PG8_SA(1, 1), a1 + hstep, voffA);
;             PG8_WAIT_V(8); PG8_WAIT_L(0); PG8_BAR; PG8_MMA(0, 0, At, B0); PG8_MMA(0, 1, At, B1); PG8_BAR; PG8_SCHED;
;             PG8_LDA(At, 0, 1); PG8_STAGE(PG8_SB(0, 0), b2, voffB); PG8_STAGE(PG8_SB(0, 1), b2 + hstep, voffB); PG8_STAGE(PG8_SA(0, 0), a2, voffA);
;             PG8_WAIT_V(8); PG8_WAIT_L(0); PG8_BAR; PG8_MMA(1, 0, At, B0); PG8_MMA(1, 1, At, B1); PG8_BAR; PG8_SCHED;
.LBB0_91:
	s_add_u32 s48, s46, 0xfffc0080
	s_addc_u32 s49, s47, -1
	s_add_i32 s61, 0, 0x10000
	s_cmp_eq_u32 s80, 12
	s_cselect_b32 s51, s89, s49
	s_cselect_b32 s50, vcc_lo, s48
	s_cselect_b32 s49, s87, s7
	s_cselect_b32 s48, vcc_hi, s5
	s_add_i32 s72, 0, 0x14000
	v_add_u32_e32 v110, s61, v170
	v_add_u32_e32 v173, s72, v170
	ds_read_b128 v[98:101], v110
	ds_read_b128 v[102:105], v110 offset:1024
	ds_read_b128 v[106:109], v110 offset:2048
	ds_read_b128 v[110:113], v110 offset:3072
	ds_read_b128 v[158:161], v173
	ds_read_b128 v[174:177], v173 offset:1024
	ds_read_b128 v[178:181], v173 offset:2048
	ds_read_b128 v[182:185], v173 offset:3072
	v_lshl_add_u64 v[228:229], s[46:47], 0, v[156:157]
	s_add_i32 m0, s9, 0xc000
	ds_read_b128 v[196:199], v172
	ds_read_b128 v[200:203], v172 offset:1024
	ds_read_b128 v[204:207], v172 offset:2048
	ds_read_b128 v[208:211], v172 offset:3072
	ds_read_b128 v[212:215], v172 offset:4096
	ds_read_b128 v[216:219], v172 offset:5120
	ds_read_b128 v[220:223], v172 offset:6144
	ds_read_b128 v[224:227], v172 offset:7168
	global_load_lds_dwordx4 v[228:229], off
	v_lshl_add_u64 v[228:229], s[46:47], 0, v[154:155]
	s_add_i32 m0, s9, 0xe000
	s_nop 0
	global_load_lds_dwordx4 v[228:229], off
	s_waitcnt vmcnt(8)
	s_waitcnt lgkmcnt(0)
	s_barrier
	v_mfma_f32_16x16x32_bf16 v[142:145], v[98:101], v[196:199], v[142:145]
	v_mfma_f32_16x16x32_bf16 v[138:141], v[106:109], v[196:199], v[138:141]
	v_mfma_f32_16x16x32_bf16 v[126:129], v[98:101], v[204:207], v[126:129]
	v_mfma_f32_16x16x32_bf16 v[122:125], v[106:109], v[204:207], v[122:125]
	v_mfma_f32_16x16x32_bf16 v[94:97], v[98:101], v[212:215], v[94:97]
	v_mfma_f32_16x16x32_bf16 v[90:93], v[106:109], v[212:215], v[90:93]
	v_mfma_f32_16x16x32_bf16 v[78:81], v[98:101], v[220:223], v[78:81]
	v_mfma_f32_16x16x32_bf16 v[74:77], v[106:109], v[220:223], v[74:77]
	v_mfma_f32_16x16x32_bf16 v[142:145], v[102:105], v[200:203], v[142:145]
	v_mfma_f32_16x16x32_bf16 v[138:141], v[110:113], v[200:203], v[138:141]
	v_mfma_f32_16x16x32_bf16 v[126:129], v[102:105], v[208:211], v[126:129]
	v_mfma_f32_16x16x32_bf16 v[122:125], v[110:113], v[208:211], v[122:125]
	v_mfma_f32_16x16x32_bf16 v[94:97], v[102:105], v[216:219], v[94:97]
	v_mfma_f32_16x16x32_bf16 v[90:93], v[110:113], v[216:219], v[90:93]
	v_mfma_f32_16x16x32_bf16 v[78:81], v[102:105], v[224:227], v[78:81]
	v_mfma_f32_16x16x32_bf16 v[74:77], v[110:113], v[224:227], v[74:77]
	v_mfma_f32_16x16x32_bf16 v[134:137], v[158:161], v[196:199], v[134:137]
	v_mfma_f32_16x16x32_bf16 v[130:133], v[178:181], v[196:199], v[130:133]
	v_mfma_f32_16x16x32_bf16 v[118:121], v[158:161], v[204:207], v[118:121]
	v_mfma_f32_16x16x32_bf16 v[114:117], v[178:181], v[204:207], v[114:117]
	v_mfma_f32_16x16x32_bf16 v[86:89], v[158:161], v[212:215], v[86:89]
	v_mfma_f32_16x16x32_bf16 v[82:85], v[178:181], v[212:215], v[82:85]
	v_mfma_f32_16x16x32_bf16 v[70:73], v[158:161], v[220:223], v[70:73]
	v_mfma_f32_16x16x32_bf16 v[66:69], v[178:181], v[220:223], v[66:69]
	v_mfma_f32_16x16x32_bf16 v[134:137], v[174:177], v[200:203], v[134:137]
	v_mfma_f32_16x16x32_bf16 v[130:133], v[182:185], v[200:203], v[130:133]
	v_mfma_f32_16x16x32_bf16 v[118:121], v[174:177], v[208:211], v[118:121]
	v_mfma_f32_16x16x32_bf16 v[114:117], v[182:185], v[208:211], v[114:117]
	v_mfma_f32_16x16x32_bf16 v[86:89], v[174:177], v[216:219], v[86:89]
	v_mfma_f32_16x16x32_bf16 v[82:85], v[182:185], v[216:219], v[82:85]
	v_mfma_f32_16x16x32_bf16 v[70:73], v[174:177], v[224:227], v[70:73]
	v_mfma_f32_16x16x32_bf16 v[66:69], v[182:185], v[224:227], v[66:69]
	s_barrier
	s_add_i32 s61, s61, s8
	v_lshl_add_u64 v[228:229], s[48:49], 0, v[148:149]
	s_mov_b32 m0, s61
	ds_read_b128 v[196:199], v172 offset:16384
	ds_read_b128 v[200:203], v172 offset:17408
	ds_read_b128 v[204:207], v172 offset:18432
	ds_read_b128 v[208:211], v172 offset:19456
	ds_read_b128 v[212:215], v172 offset:20480
	ds_read_b128 v[216:219], v172 offset:21504
	ds_read_b128 v[220:223], v172 offset:22528
	ds_read_b128 v[224:227], v172 offset:23552
	global_load_lds_dwordx4 v[228:229], off
	s_add_i32 m0, s61, 0x2000
	s_add_u32 s76, s48, 0x40000
	v_lshl_add_u64 v[230:231], s[48:49], 0, v[152:153]
	s_addc_u32 s77, s49, 0
	s_add_i32 s61, s72, s8
	global_load_lds_dwordx4 v[230:231], off
	v_lshl_add_u64 v[232:233], s[76:77], 0, v[148:149]
	s_mov_b32 m0, s61
	v_lshl_add_u64 v[234:235], s[50:51], 0, v[150:151]
	global_load_lds_dwordx4 v[232:233], off
	v_lshl_add_u64 v[232:233], s[76:77], 0, v[152:153]
	s_add_i32 m0, s61, 0x2000
	s_nop 0
	global_load_lds_dwordx4 v[232:233], off
	v_lshl_add_u64 v[232:233], s[50:51], 0, v[146:147]
	s_mov_b32 m0, s9
	s_nop 0
	global_load_lds_dwordx4 v[232:233], off
	s_mov_b32 m0, s96
	s_nop 0
	global_load_lds_dwordx4 v[234:235], off
	s_waitcnt vmcnt(8)
	s_waitcnt lgkmcnt(0)
	s_barrier
; #define PG8_STAGE(bufoff, gbase, voff) do { _Pragma("unroll") for (int _i = 0; _i < 2; ++_i) \
;         __builtin_amdgcn_global_load_lds((const unsigned*)((const char*)(gbase) + (voff)[_i]), (PG8_LAS unsigned*)(lds + (bufoff) + ldsw + _i * 8192), 16, 0, 0); } while (0)
; #define PG8_LDA(dst, b, h) do { _Pragma("unroll") for (int m = 0; m < 4; ++m) _Pragma("unroll") for (int k = 0; k < 2; ++k) dst[m][k] = *(const PG8_LAS bf16x8*)(lds + PG8_SA(b, h) + aoff + m * 2048 + k * 1024); } while (0)
; #define PG8_LDB(dst, b, h) do { _Pragma("unroll") for (int n = 0; n < 2; ++n) _Pragma("unroll") for (int k = 0; k < 2; ++k) dst[n][k] = *(const PG8_LAS bf16x8*)(lds + PG8_SB(b, h) + boff + n * 2048 + k * 1024); } while (0)
; #define PG8_MMA(ai, bj, At, Bt) do { __builtin_amdgcn_s_setprio(1); _Pragma("unroll") for (int m = 0; m < 4; ++m) _Pragma("unroll") for (int n = 0; n < 2; ++n) _Pragma("unroll") for (int k = 0; k < 2; ++k) \
;         acc[ai][bj][m][n] = __builtin_amdgcn_mfma_f32_16x16x32_bf16(Bt[n][k], At[m][k], acc[ai][bj][m][n], 0, 0, 0); __builtin_amdgcn_s_setprio(0); } while (0)
; #define PG8_WAIT_V(n) asm volatile("s_waitcnt vmcnt(" #n ")" ::: "memory")
; #define PG8_WAIT_L(n) asm volatile("s_waitcnt lgkmcnt(" #n ")" ::: "memory")
; #define PG8_BAR __builtin_amdgcn_s_barrier()
; #define PG8_SCHED __builtin_amdgcn_sched_barrier(0)
; template <class Epi, class Sched, bool ALIGN_EPI = false, bool SP2 = false>
; __device__ __forceinline__ void gemm_phase(PG8_LAS unsigned char* lds, const Gemm g, const Sched& S, const Epi& E) {
;     ...
;             PG8_WAIT_V(8); PG8_WAIT_L(0); PG8_BAR; PG8_MMA(1, 0, At, B0); PG8_MMA(1, 1, At, B1); PG8_BAR; PG8_SCHED;
;             PG8_LDB(B0, 1, 0); PG8_LDB(B1, 1, 1); PG8_SCHED; PG8_LDA(At, 1, 0); PG8_STAGE(PG8_SA(0, 1), a2 + hstep, voffA);
;             PG8_WAIT_V(8); PG8_WAIT_L(0); PG8_BAR; PG8_MMA(0, 0, At, B0); PG8_MMA(0, 1, At, B1); PG8_BAR; PG8_SCHED;
	v_mfma_f32_16x16x32_bf16 v[62:65], v[98:101], v[196:199], v[62:65]
	v_mfma_f32_16x16x32_bf16 v[58:61], v[106:109], v[196:199], v[58:61]
	v_mfma_f32_16x16x32_bf16 v[50:53], v[98:101], v[204:207], v[50:53]
	v_mfma_f32_16x16x32_bf16 v[42:45], v[106:109], v[204:207], v[42:45]
	v_mfma_f32_16x16x32_bf16 v[34:37], v[98:101], v[212:215], v[34:37]
	v_mfma_f32_16x16x32_bf16 v[24:27], v[106:109], v[212:215], v[24:27]
	v_mfma_f32_16x16x32_bf16 v[12:15], v[98:101], v[220:223], v[12:15]
	v_mfma_f32_16x16x32_bf16 v[8:11], v[106:109], v[220:223], v[8:11]
	v_mfma_f32_16x16x32_bf16 v[62:65], v[102:105], v[200:203], v[62:65]
	v_mfma_f32_16x16x32_bf16 v[58:61], v[110:113], v[200:203], v[58:61]
	v_mfma_f32_16x16x32_bf16 v[50:53], v[102:105], v[208:211], v[50:53]
	v_mfma_f32_16x16x32_bf16 v[42:45], v[110:113], v[208:211], v[42:45]
	v_mfma_f32_16x16x32_bf16 v[34:37], v[102:105], v[216:219], v[34:37]
	v_mfma_f32_16x16x32_bf16 v[24:27], v[110:113], v[216:219], v[24:27]
	v_mfma_f32_16x16x32_bf16 v[12:15], v[102:105], v[224:227], v[12:15]
	v_mfma_f32_16x16x32_bf16 v[8:11], v[110:113], v[224:227], v[8:11]
	v_mfma_f32_16x16x32_bf16 v[54:57], v[158:161], v[196:199], v[54:57]
	v_mfma_f32_16x16x32_bf16 v[46:49], v[178:181], v[196:199], v[46:49]
	v_mfma_f32_16x16x32_bf16 v[38:41], v[158:161], v[204:207], v[38:41]
	v_mfma_f32_16x16x32_bf16 v[28:31], v[178:181], v[204:207], v[28:31]
	v_mfma_f32_16x16x32_bf16 v[20:23], v[158:161], v[212:215], v[20:23]
	v_mfma_f32_16x16x32_bf16 v[16:19], v[178:181], v[212:215], v[16:19]
	v_mfma_f32_16x16x32_bf16 v[4:7], v[158:161], v[220:223], v[4:7]
	v_mfma_f32_16x16x32_bf16 v[0:3], v[178:181], v[220:223], v[0:3]
	v_mfma_f32_16x16x32_bf16 v[54:57], v[174:177], v[200:203], v[54:57]
	v_mfma_f32_16x16x32_bf16 v[46:49], v[182:185], v[200:203], v[46:49]
	v_mfma_f32_16x16x32_bf16 v[38:41], v[174:177], v[208:211], v[38:41]
	v_mfma_f32_16x16x32_bf16 v[28:31], v[182:185], v[208:211], v[28:31]
	v_mfma_f32_16x16x32_bf16 v[20:23], v[174:177], v[216:219], v[20:23]
	v_mfma_f32_16x16x32_bf16 v[16:19], v[182:185], v[216:219], v[16:19]
	v_mfma_f32_16x16x32_bf16 v[4:7], v[174:177], v[224:227], v[4:7]
	v_mfma_f32_16x16x32_bf16 v[0:3], v[182:185], v[224:227], v[0:3]
	s_barrier
	s_add_i32 s61, 0, 0x18000
	s_add_i32 s72, 0, 0x1c000
	v_add_u32_e32 v110, s61, v170
	v_add_u32_e32 v173, s72, v170
	ds_read_b128 v[98:101], v110
	ds_read_b128 v[102:105], v110 offset:1024
	ds_read_b128 v[106:109], v110 offset:2048
	ds_read_b128 v[110:113], v110 offset:3072
	ds_read_b128 v[158:161], v173
	ds_read_b128 v[174:177], v173 offset:1024
	ds_read_b128 v[178:181], v173 offset:2048
	ds_read_b128 v[182:185], v173 offset:3072
	s_add_u32 s50, s50, 0x40000
	s_addc_u32 s51, s51, 0
	s_mov_b32 m0, s97
	v_lshl_add_u64 v[236:237], s[50:51], 0, v[146:147]
	ds_read_b128 v[196:199], v172 offset:32768
	ds_read_b128 v[200:203], v172 offset:33792
	ds_read_b128 v[204:207], v172 offset:34816
	ds_read_b128 v[208:211], v172 offset:35840
	ds_read_b128 v[212:215], v172 offset:36864
	ds_read_b128 v[216:219], v172 offset:37888
	ds_read_b128 v[220:223], v172 offset:38912
	ds_read_b128 v[224:227], v172 offset:39936
	global_load_lds_dwordx4 v[236:237], off
	v_lshl_add_u64 v[236:237], s[50:51], 0, v[150:151]
	s_mov_b32 m0, s2
	s_nop 0
	global_load_lds_dwordx4 v[236:237], off
	s_waitcnt vmcnt(8)
	s_waitcnt lgkmcnt(0)
	s_barrier
	v_mfma_f32_16x16x32_bf16 v[142:145], v[98:101], v[196:199], v[142:145]
	v_mfma_f32_16x16x32_bf16 v[138:141], v[106:109], v[196:199], v[138:141]
	v_mfma_f32_16x16x32_bf16 v[126:129], v[98:101], v[204:207], v[126:129]
	v_mfma_f32_16x16x32_bf16 v[122:125], v[106:109], v[204:207], v[122:125]
	v_mfma_f32_16x16x32_bf16 v[94:97], v[98:101], v[212:215], v[94:97]
	v_mfma_f32_16x16x32_bf16 v[90:93], v[106:109], v[212:215], v[90:93]
	v_mfma_f32_16x16x32_bf16 v[78:81], v[98:101], v[220:223], v[78:81]
	v_mfma_f32_16x16x32_bf16 v[74:77], v[106:109], v[220:223], v[74:77]
	v_mfma_f32_16x16x32_bf16 v[142:145], v[102:105], v[200:203], v[142:145]
	v_mfma_f32_16x16x32_bf16 v[138:141], v[110:113], v[200:203], v[138:141]
	v_mfma_f32_16x16x32_bf16 v[126:129], v[102:105], v[208:211], v[126:129]
	v_mfma_f32_16x16x32_bf16 v[122:125], v[110:113], v[208:211], v[122:125]
	v_mfma_f32_16x16x32_bf16 v[94:97], v[102:105], v[216:219], v[94:97]
	v_mfma_f32_16x16x32_bf16 v[90:93], v[110:113], v[216:219], v[90:93]
	v_mfma_f32_16x16x32_bf16 v[78:81], v[102:105], v[224:227], v[78:81]
	v_mfma_f32_16x16x32_bf16 v[74:77], v[110:113], v[224:227], v[74:77]
	v_mfma_f32_16x16x32_bf16 v[134:137], v[158:161], v[196:199], v[134:137]
	v_mfma_f32_16x16x32_bf16 v[130:133], v[178:181], v[196:199], v[130:133]
	v_mfma_f32_16x16x32_bf16 v[118:121], v[158:161], v[204:207], v[118:121]
	v_mfma_f32_16x16x32_bf16 v[114:117], v[178:181], v[204:207], v[114:117]
	v_mfma_f32_16x16x32_bf16 v[86:89], v[158:161], v[212:215], v[86:89]
	v_mfma_f32_16x16x32_bf16 v[82:85], v[178:181], v[212:215], v[82:85]
	v_mfma_f32_16x16x32_bf16 v[70:73], v[158:161], v[220:223], v[70:73]
	v_mfma_f32_16x16x32_bf16 v[66:69], v[178:181], v[220:223], v[66:69]
	v_mfma_f32_16x16x32_bf16 v[134:137], v[174:177], v[200:203], v[134:137]
	v_mfma_f32_16x16x32_bf16 v[130:133], v[182:185], v[200:203], v[130:133]
	v_mfma_f32_16x16x32_bf16 v[118:121], v[174:177], v[208:211], v[118:121]
	v_mfma_f32_16x16x32_bf16 v[114:117], v[182:185], v[208:211], v[114:117]
	v_mfma_f32_16x16x32_bf16 v[86:89], v[174:177], v[216:219], v[86:89]
	v_mfma_f32_16x16x32_bf16 v[82:85], v[182:185], v[216:219], v[82:85]
	v_mfma_f32_16x16x32_bf16 v[70:73], v[174:177], v[224:227], v[70:73]
	v_mfma_f32_16x16x32_bf16 v[66:69], v[182:185], v[224:227], v[66:69]
	s_barrier
; #define PG8_STAGE(bufoff, gbase, voff) do { _Pragma("unroll") for (int _i = 0; _i < 2; ++_i) \
;         __builtin_amdgcn_global_load_lds((const unsigned*)((const char*)(gbase) + (voff)[_i]), (PG8_LAS unsigned*)(lds + (bufoff) + ldsw + _i * 8192), 16, 0, 0); } while (0)
; #define PG8_LDA(dst, b, h) do { _Pragma("unroll") for (int m = 0; m < 4; ++m) _Pragma("unroll") for (int k = 0; k < 2; ++k) dst[m][k] = *(const PG8_LAS bf16x8*)(lds + PG8_SA(b, h) + aoff + m * 2048 + k * 1024); } while (0)
; #define PG8_MMA(ai, bj, At, Bt) do { __builtin_amdgcn_s_setprio(1); _Pragma("unroll") for (int m = 0; m < 4; ++m) _Pragma("unroll") for (int n = 0; n < 2; ++n) _Pragma("unroll") for (int k = 0; k < 2; ++k) \
;         acc[ai][bj][m][n] = __builtin_amdgcn_mfma_f32_16x16x32_bf16(Bt[n][k], At[m][k], acc[ai][bj][m][n], 0, 0, 0); __builtin_amdgcn_s_setprio(0); } while (0)
; #define PG8_WAIT_V(n) asm volatile("s_waitcnt vmcnt(" #n ")" ::: "memory")
; #define PG8_WAIT_L(n) asm volatile("s_waitcnt lgkmcnt(" #n ")" ::: "memory")
; #define PG8_BAR __builtin_amdgcn_s_barrier()
; #define PG8_SCHED __builtin_amdgcn_sched_barrier(0)
; template <class Epi, class Sched, bool ALIGN_EPI = false, bool SP2 = false>
; __device__ __forceinline__ void gemm_phase(PG8_LAS unsigned char* lds, const Gemm g, const Sched& S, const Epi& E) {
;     ...
;             PG8_LDA(At, 1, 1); PG8_STAGE(PG8_SB(1, 0), b3, voffB); PG8_STAGE(PG8_SB(1, 1), b3 + hstep, voffB); PG8_STAGE(PG8_SA(1, 0), a3, voffA);
;             PG8_WAIT_V(8); PG8_WAIT_L(0); PG8_BAR; PG8_MMA(1, 0, At, B0); PG8_MMA(1, 1, At, B1); PG8_BAR; PG8_SCHED;
;     ...
;         if constexpr (ALIGN_EPI) { if (wr == 0) PG8_BAR; }
	s_add_i32 s50, s61, s8
	v_lshl_add_u64 v[228:229], v[228:229], 0, s[34:35]
	s_mov_b32 m0, s50
	ds_read_b128 v[196:199], v172 offset:49152
	ds_read_b128 v[200:203], v172 offset:50176
	ds_read_b128 v[204:207], v172 offset:51200
	ds_read_b128 v[208:211], v172 offset:52224
	ds_read_b128 v[212:215], v172 offset:53248
	ds_read_b128 v[216:219], v172 offset:54272
	ds_read_b128 v[220:223], v172 offset:55296
	ds_read_b128 v[224:227], v172 offset:56320
	global_load_lds_dwordx4 v[228:229], off
	s_add_i32 m0, s50, 0x2000
	s_add_u32 s48, s48, 0x40080
	v_lshl_add_u64 v[228:229], v[230:231], 0, s[34:35]
	s_addc_u32 s49, s49, 0
	s_add_i32 s50, s72, s8
	global_load_lds_dwordx4 v[228:229], off
	v_lshl_add_u64 v[228:229], s[48:49], 0, v[148:149]
	s_mov_b32 m0, s50
	s_nop 0
	global_load_lds_dwordx4 v[228:229], off
	v_lshl_add_u64 v[228:229], s[48:49], 0, v[152:153]
	s_add_i32 m0, s50, 0x2000
	s_nop 0
	global_load_lds_dwordx4 v[228:229], off
	v_lshl_add_u64 v[228:229], v[232:233], 0, s[34:35]
	s_mov_b32 m0, s0
	s_nop 0
	global_load_lds_dwordx4 v[228:229], off
	v_lshl_add_u64 v[228:229], v[234:235], 0, s[34:35]
	s_mov_b32 m0, s3
	s_nop 0
	global_load_lds_dwordx4 v[228:229], off
	s_waitcnt vmcnt(8)
	s_waitcnt lgkmcnt(0)
	s_barrier
	v_mfma_f32_16x16x32_bf16 v[62:65], v[98:101], v[196:199], v[62:65]
	v_mfma_f32_16x16x32_bf16 v[58:61], v[106:109], v[196:199], v[58:61]
	v_mfma_f32_16x16x32_bf16 v[50:53], v[98:101], v[204:207], v[50:53]
	v_mfma_f32_16x16x32_bf16 v[42:45], v[106:109], v[204:207], v[42:45]
	v_mfma_f32_16x16x32_bf16 v[34:37], v[98:101], v[212:215], v[34:37]
	v_mfma_f32_16x16x32_bf16 v[24:27], v[106:109], v[212:215], v[24:27]
	v_mfma_f32_16x16x32_bf16 v[12:15], v[98:101], v[220:223], v[12:15]
	v_mfma_f32_16x16x32_bf16 v[8:11], v[106:109], v[220:223], v[8:11]
	v_mfma_f32_16x16x32_bf16 v[62:65], v[102:105], v[200:203], v[62:65]
	v_mfma_f32_16x16x32_bf16 v[58:61], v[110:113], v[200:203], v[58:61]
	v_mfma_f32_16x16x32_bf16 v[50:53], v[102:105], v[208:211], v[50:53]
	v_mfma_f32_16x16x32_bf16 v[42:45], v[110:113], v[208:211], v[42:45]
	v_mfma_f32_16x16x32_bf16 v[34:37], v[102:105], v[216:219], v[34:37]
	v_mfma_f32_16x16x32_bf16 v[24:27], v[110:113], v[216:219], v[24:27]
	v_mfma_f32_16x16x32_bf16 v[12:15], v[102:105], v[224:227], v[12:15]
	v_mfma_f32_16x16x32_bf16 v[8:11], v[110:113], v[224:227], v[8:11]
	v_mfma_f32_16x16x32_bf16 v[54:57], v[158:161], v[196:199], v[54:57]
	v_mfma_f32_16x16x32_bf16 v[46:49], v[178:181], v[196:199], v[46:49]
	v_mfma_f32_16x16x32_bf16 v[38:41], v[158:161], v[204:207], v[38:41]
	v_mfma_f32_16x16x32_bf16 v[28:31], v[178:181], v[204:207], v[28:31]
	v_mfma_f32_16x16x32_bf16 v[20:23], v[158:161], v[212:215], v[20:23]
	v_mfma_f32_16x16x32_bf16 v[16:19], v[178:181], v[212:215], v[16:19]
	v_mfma_f32_16x16x32_bf16 v[4:7], v[158:161], v[220:223], v[4:7]
	v_mfma_f32_16x16x32_bf16 v[0:3], v[178:181], v[220:223], v[0:3]
	v_mfma_f32_16x16x32_bf16 v[54:57], v[174:177], v[200:203], v[54:57]
	v_mfma_f32_16x16x32_bf16 v[46:49], v[182:185], v[200:203], v[46:49]
	v_mfma_f32_16x16x32_bf16 v[38:41], v[174:177], v[208:211], v[38:41]
	v_mfma_f32_16x16x32_bf16 v[28:31], v[182:185], v[208:211], v[28:31]
	v_mfma_f32_16x16x32_bf16 v[20:23], v[174:177], v[216:219], v[20:23]
	v_mfma_f32_16x16x32_bf16 v[16:19], v[182:185], v[216:219], v[16:19]
	v_mfma_f32_16x16x32_bf16 v[4:7], v[174:177], v[224:227], v[4:7]
	v_mfma_f32_16x16x32_bf16 v[0:3], v[182:185], v[224:227], v[0:3]
	s_barrier
	s_add_i32 s80, s80, 2
	s_add_u32 s5, s5, 0x100
	s_addc_u32 s7, s7, 0
	s_add_u32 s46, s46, 0x100
	s_addc_u32 s47, s47, 0
	s_cmp_gt_u32 s80, 13
	s_cbranch_scc0 .LBB0_91
	s_and_b64 vcc, exec, s[38:39]
	s_cbranch_vccz .LBB0_94
	s_barrier

; #define PG8_STAGE(bufoff, gbase, voff) do { _Pragma("unroll") for (int _i = 0; _i < 2; ++_i) \
;         __builtin_amdgcn_global_load_lds((const unsigned*)((const char*)(gbase) + (voff)[_i]), (PG8_LAS unsigned*)(lds + (bufoff) + ldsw + _i * 8192), 16, 0, 0); } while (0)
; #define PG8_LDA(dst, b, h) do { _Pragma("unroll") for (int m = 0; m < 4; ++m) _Pragma("unroll") for (int k = 0; k < 2; ++k) dst[m][k] = *(const PG8_LAS bf16x8*)(lds + PG8_SA(b, h) + aoff + m * 2048 + k * 1024); } while (0)
; #define PG8_LDB(dst, b, h) do { _Pragma("unroll") for (int n = 0; n < 2; ++n) _Pragma("unroll") for (int k = 0; k < 2; ++k) dst[n][k] = *(const PG8_LAS bf16x8*)(lds + PG8_SB(b, h) + boff + n * 2048 + k * 1024); } while (0)
; #define PG8_MMA(ai, bj, At, Bt) do { __builtin_amdgcn_s_setprio(1); _Pragma("unroll") for (int m = 0; m < 4; ++m) _Pragma("unroll") for (int n = 0; n < 2; ++n) _Pragma("unroll") for (int k = 0; k < 2; ++k) \
;         acc[ai][bj][m][n] = __builtin_amdgcn_mfma_f32_16x16x32_bf16(Bt[n][k], At[m][k], acc[ai][bj][m][n], 0, 0, 0); __builtin_amdgcn_s_setprio(0); } while (0)
; #define PG8_WAIT_V(n) asm volatile("s_waitcnt vmcnt(" #n ")" ::: "memory")
; #define PG8_WAIT_L(n) asm volatile("s_waitcnt lgkmcnt(" #n ")" ::: "memory")
; template <class Epi, class Sched, bool ALIGN_EPI = false, bool SP2 = false>
; __device__ __forceinline__ void gemm_phase(PG8_LAS unsigned char* lds, const Gemm g, const Sched& S, const Epi& E) {
;     ...
;             const bool last = (t == nt - 2);
;             const char* a1 = cA + (size_t)(t + 1) * kstep;
;             const char* a2 = last ? nA : cA + (size_t)(t + 2) * kstep; const char* b2 = last ? nB : cB + (size_t)(t + 2) * kstep;
;             const char* a3 = a2 + kstep; const char* b3 = b2 + kstep;
;             if (last && has_next) S.a_ready(nxt);
;             if constexpr (SP2) {
;             PG8_LDB(B0, 0, 0); PG8_LDB(B1, 0, 1); PG8_SCHED; PG8_LDA(At, 0, 0); PG8_STAGE(PG8_SA(1, 1), a1 + hstep, voffA);
;             PG8_WAIT_V(8); PG8_WAIT_L(0); PG8_BAR; PG8_MMA(0, 0, At, B0); PG8_MMA(0, 1, At, B1); PG8_BAR; PG8_SCHED;
;             PG8_LDA(At, 0, 1); PG8_STAGE(PG8_SB(0, 0), b2, voffB); PG8_STAGE(PG8_SB(0, 1), b2 + hstep, voffB); PG8_STAGE(PG8_SA(0, 0), a2, voffA);
;             PG8_WAIT_V(8); PG8_WAIT_L(0); PG8_BAR; PG8_MMA(1, 0, At, B0); PG8_MMA(1, 1, At, B1); PG8_BAR; PG8_SCHED;
.LBB0_118:
	s_add_u32 s48, s46, 0xfffc0080
	s_addc_u32 s49, s47, -1
	s_add_i32 s61, 0, 0x10000
	s_cmp_eq_u32 vcc_lo, 12
	s_cselect_b32 s51, s5, s49
	s_cselect_b32 s50, s7, s48
	v_add_u32_e32 v150, s61, v145
	s_cselect_b32 s49, s8, s91
	s_cselect_b32 s48, s45, s89
	s_add_i32 s72, 0, 0x14000
	ds_read_b128 v[174:177], v150
	ds_read_b128 v[178:181], v150 offset:1024
	ds_read_b128 v[182:185], v150 offset:2048
	ds_read_b128 v[196:199], v150 offset:3072
	v_add_u32_e32 v150, s72, v145
	ds_read_b128 v[200:203], v150
	ds_read_b128 v[204:207], v150 offset:1024
	ds_read_b128 v[208:211], v150 offset:2048
	ds_read_b128 v[212:215], v150 offset:3072
	v_lshl_add_u64 v[150:151], s[46:47], 0, v[142:143]
	s_add_i32 m0, s39, 0xc000
	ds_read_b128 v[216:219], v149
	ds_read_b128 v[220:223], v149 offset:1024
	ds_read_b128 v[224:227], v149 offset:2048
	ds_read_b128 v[228:231], v149 offset:3072
	ds_read_b128 v[232:235], v149 offset:4096
	ds_read_b128 v[236:239], v149 offset:5120
	ds_read_b128 v[240:243], v149 offset:6144
	ds_read_b128 v[244:247], v149 offset:7168
	global_load_lds_dwordx4 v[150:151], off
	v_lshl_add_u64 v[150:151], s[46:47], 0, v[140:141]
	s_add_i32 m0, s39, 0xe000
	s_nop 0
	global_load_lds_dwordx4 v[150:151], off
	s_waitcnt vmcnt(8)
	s_waitcnt lgkmcnt(0)
	s_barrier
	v_mfma_f32_16x16x32_bf16 v[126:129], v[174:177], v[216:219], v[126:129]
	v_mfma_f32_16x16x32_bf16 v[122:125], v[182:185], v[216:219], v[122:125]
	v_mfma_f32_16x16x32_bf16 v[110:113], v[174:177], v[224:227], v[110:113]
	v_mfma_f32_16x16x32_bf16 v[106:109], v[182:185], v[224:227], v[106:109]
	v_mfma_f32_16x16x32_bf16 v[94:97], v[174:177], v[232:235], v[94:97]
	v_mfma_f32_16x16x32_bf16 v[90:93], v[182:185], v[232:235], v[90:93]
	v_mfma_f32_16x16x32_bf16 v[78:81], v[174:177], v[240:243], v[78:81]
	v_mfma_f32_16x16x32_bf16 v[74:77], v[182:185], v[240:243], v[74:77]
	v_mfma_f32_16x16x32_bf16 v[126:129], v[178:181], v[220:223], v[126:129]
	v_mfma_f32_16x16x32_bf16 v[122:125], v[196:199], v[220:223], v[122:125]
	v_mfma_f32_16x16x32_bf16 v[110:113], v[178:181], v[228:231], v[110:113]
	v_mfma_f32_16x16x32_bf16 v[106:109], v[196:199], v[228:231], v[106:109]
	v_mfma_f32_16x16x32_bf16 v[94:97], v[178:181], v[236:239], v[94:97]
	v_mfma_f32_16x16x32_bf16 v[90:93], v[196:199], v[236:239], v[90:93]
	v_mfma_f32_16x16x32_bf16 v[78:81], v[178:181], v[244:247], v[78:81]
	v_mfma_f32_16x16x32_bf16 v[74:77], v[196:199], v[244:247], v[74:77]
	v_mfma_f32_16x16x32_bf16 v[118:121], v[200:203], v[216:219], v[118:121]
	v_mfma_f32_16x16x32_bf16 v[114:117], v[208:211], v[216:219], v[114:117]
	v_mfma_f32_16x16x32_bf16 v[102:105], v[200:203], v[224:227], v[102:105]
	v_mfma_f32_16x16x32_bf16 v[98:101], v[208:211], v[224:227], v[98:101]
	v_mfma_f32_16x16x32_bf16 v[86:89], v[200:203], v[232:235], v[86:89]
	v_mfma_f32_16x16x32_bf16 v[82:85], v[208:211], v[232:235], v[82:85]
	v_mfma_f32_16x16x32_bf16 v[70:73], v[200:203], v[240:243], v[70:73]
	v_mfma_f32_16x16x32_bf16 v[66:69], v[208:211], v[240:243], v[66:69]
	v_mfma_f32_16x16x32_bf16 v[118:121], v[204:207], v[220:223], v[118:121]
	v_mfma_f32_16x16x32_bf16 v[114:117], v[212:215], v[220:223], v[114:117]
	v_mfma_f32_16x16x32_bf16 v[102:105], v[204:207], v[228:231], v[102:105]
	v_mfma_f32_16x16x32_bf16 v[98:101], v[212:215], v[228:231], v[98:101]
	v_mfma_f32_16x16x32_bf16 v[86:89], v[204:207], v[236:239], v[86:89]
	v_mfma_f32_16x16x32_bf16 v[82:85], v[212:215], v[236:239], v[82:85]
	v_mfma_f32_16x16x32_bf16 v[70:73], v[204:207], v[244:247], v[70:73]
	v_mfma_f32_16x16x32_bf16 v[66:69], v[212:215], v[244:247], v[66:69]
	s_barrier
	s_add_i32 s61, s61, s38
	v_lshl_add_u64 v[150:151], s[48:49], 0, v[132:133]
	s_mov_b32 m0, s61
	ds_read_b128 v[216:219], v149 offset:16384
	ds_read_b128 v[220:223], v149 offset:17408
	ds_read_b128 v[224:227], v149 offset:18432
	ds_read_b128 v[228:231], v149 offset:19456
	ds_read_b128 v[232:235], v149 offset:20480
	ds_read_b128 v[236:239], v149 offset:21504
	ds_read_b128 v[240:243], v149 offset:22528
	ds_read_b128 v[244:247], v149 offset:23552
	global_load_lds_dwordx4 v[150:151], off
	s_add_i32 m0, s61, 0x2000
	s_add_u32 s80, s48, 0x40000
	v_lshl_add_u64 v[160:161], s[48:49], 0, v[136:137]
	s_addc_u32 s81, s49, 0
	s_add_i32 s61, s72, s38
	global_load_lds_dwordx4 v[160:161], off
	v_lshl_add_u64 v[170:171], s[80:81], 0, v[132:133]
	s_mov_b32 m0, s61
	v_lshl_add_u64 v[248:249], s[50:51], 0, v[134:135]
	global_load_lds_dwordx4 v[170:171], off
	v_lshl_add_u64 v[170:171], s[80:81], 0, v[136:137]
	s_add_i32 m0, s61, 0x2000
	s_nop 0
	global_load_lds_dwordx4 v[170:171], off
	v_lshl_add_u64 v[170:171], s[50:51], 0, v[130:131]
	s_mov_b32 m0, s39
	s_nop 0
	global_load_lds_dwordx4 v[170:171], off
	s_mov_b32 m0, s2
	s_nop 0
	global_load_lds_dwordx4 v[248:249], off
	s_waitcnt vmcnt(8)
	s_waitcnt lgkmcnt(0)
	s_barrier
; #define PG8_STAGE(bufoff, gbase, voff) do { _Pragma("unroll") for (int _i = 0; _i < 2; ++_i) \
;         __builtin_amdgcn_global_load_lds((const unsigned*)((const char*)(gbase) + (voff)[_i]), (PG8_LAS unsigned*)(lds + (bufoff) + ldsw + _i * 8192), 16, 0, 0); } while (0)
; #define PG8_LDA(dst, b, h) do { _Pragma("unroll") for (int m = 0; m < 4; ++m) _Pragma("unroll") for (int k = 0; k < 2; ++k) dst[m][k] = *(const PG8_LAS bf16x8*)(lds + PG8_SA(b, h) + aoff + m * 2048 + k * 1024); } while (0)
; #define PG8_LDB(dst, b, h) do { _Pragma("unroll") for (int n = 0; n < 2; ++n) _Pragma("unroll") for (int k = 0; k < 2; ++k) dst[n][k] = *(const PG8_LAS bf16x8*)(lds + PG8_SB(b, h) + boff + n * 2048 + k * 1024); } while (0)
; #define PG8_MMA(ai, bj, At, Bt) do { __builtin_amdgcn_s_setprio(1); _Pragma("unroll") for (int m = 0; m < 4; ++m) _Pragma("unroll") for (int n = 0; n < 2; ++n) _Pragma("unroll") for (int k = 0; k < 2; ++k) \
;         acc[ai][bj][m][n] = __builtin_amdgcn_mfma_f32_16x16x32_bf16(Bt[n][k], At[m][k], acc[ai][bj][m][n], 0, 0, 0); __builtin_amdgcn_s_setprio(0); } while (0)
; #define PG8_WAIT_V(n) asm volatile("s_waitcnt vmcnt(" #n ")" ::: "memory")
; #define PG8_WAIT_L(n) asm volatile("s_waitcnt lgkmcnt(" #n ")" ::: "memory")
; #define PG8_BAR __builtin_amdgcn_s_barrier()
; #define PG8_SCHED __builtin_amdgcn_sched_barrier(0)
; template <class Epi, class Sched, bool ALIGN_EPI = false, bool SP2 = false>
; __device__ __forceinline__ void gemm_phase(PG8_LAS unsigned char* lds, const Gemm g, const Sched& S, const Epi& E) {
;     ...
;             PG8_WAIT_V(8); PG8_WAIT_L(0); PG8_BAR; PG8_MMA(1, 0, At, B0); PG8_MMA(1, 1, At, B1); PG8_BAR; PG8_SCHED;
;             PG8_LDB(B0, 1, 0); PG8_LDB(B1, 1, 1); PG8_SCHED; PG8_LDA(At, 1, 0); PG8_STAGE(PG8_SA(0, 1), a2 + hstep, voffA);
;             PG8_WAIT_V(8); PG8_WAIT_L(0); PG8_BAR; PG8_MMA(0, 0, At, B0); PG8_MMA(0, 1, At, B1); PG8_BAR; PG8_SCHED;
	v_mfma_f32_16x16x32_bf16 v[62:65], v[174:177], v[216:219], v[62:65]
	v_mfma_f32_16x16x32_bf16 v[58:61], v[182:185], v[216:219], v[58:61]
	v_mfma_f32_16x16x32_bf16 v[46:49], v[174:177], v[224:227], v[46:49]
	v_mfma_f32_16x16x32_bf16 v[42:45], v[182:185], v[224:227], v[42:45]
	v_mfma_f32_16x16x32_bf16 v[28:31], v[174:177], v[232:235], v[28:31]
	v_mfma_f32_16x16x32_bf16 v[24:27], v[182:185], v[232:235], v[24:27]
	v_mfma_f32_16x16x32_bf16 v[12:15], v[174:177], v[240:243], v[12:15]
	v_mfma_f32_16x16x32_bf16 v[8:11], v[182:185], v[240:243], v[8:11]
	v_mfma_f32_16x16x32_bf16 v[62:65], v[178:181], v[220:223], v[62:65]
	v_mfma_f32_16x16x32_bf16 v[58:61], v[196:199], v[220:223], v[58:61]
	v_mfma_f32_16x16x32_bf16 v[46:49], v[178:181], v[228:231], v[46:49]
	v_mfma_f32_16x16x32_bf16 v[42:45], v[196:199], v[228:231], v[42:45]
	v_mfma_f32_16x16x32_bf16 v[28:31], v[178:181], v[236:239], v[28:31]
	v_mfma_f32_16x16x32_bf16 v[24:27], v[196:199], v[236:239], v[24:27]
	v_mfma_f32_16x16x32_bf16 v[12:15], v[178:181], v[244:247], v[12:15]
	v_mfma_f32_16x16x32_bf16 v[8:11], v[196:199], v[244:247], v[8:11]
	v_mfma_f32_16x16x32_bf16 v[54:57], v[200:203], v[216:219], v[54:57]
	v_mfma_f32_16x16x32_bf16 v[50:53], v[208:211], v[216:219], v[50:53]
	v_mfma_f32_16x16x32_bf16 v[38:41], v[200:203], v[224:227], v[38:41]
	v_mfma_f32_16x16x32_bf16 v[34:37], v[208:211], v[224:227], v[34:37]
	v_mfma_f32_16x16x32_bf16 v[20:23], v[200:203], v[232:235], v[20:23]
	v_mfma_f32_16x16x32_bf16 v[16:19], v[208:211], v[232:235], v[16:19]
	v_mfma_f32_16x16x32_bf16 v[4:7], v[200:203], v[240:243], v[4:7]
	v_mfma_f32_16x16x32_bf16 v[0:3], v[208:211], v[240:243], v[0:3]
	v_mfma_f32_16x16x32_bf16 v[54:57], v[204:207], v[220:223], v[54:57]
	v_mfma_f32_16x16x32_bf16 v[50:53], v[212:215], v[220:223], v[50:53]
	v_mfma_f32_16x16x32_bf16 v[38:41], v[204:207], v[228:231], v[38:41]
	v_mfma_f32_16x16x32_bf16 v[34:37], v[212:215], v[228:231], v[34:37]
	v_mfma_f32_16x16x32_bf16 v[20:23], v[204:207], v[236:239], v[20:23]
	v_mfma_f32_16x16x32_bf16 v[16:19], v[212:215], v[236:239], v[16:19]
	v_mfma_f32_16x16x32_bf16 v[4:7], v[204:207], v[244:247], v[4:7]
	v_mfma_f32_16x16x32_bf16 v[0:3], v[212:215], v[244:247], v[0:3]
	s_barrier
	s_add_i32 s61, 0, 0x18000
	v_add_u32_e32 v153, s61, v145
	s_add_i32 s72, 0, 0x1c000
	ds_read_b128 v[174:177], v153
	ds_read_b128 v[178:181], v153 offset:1024
	ds_read_b128 v[182:185], v153 offset:2048
	ds_read_b128 v[196:199], v153 offset:3072
	v_add_u32_e32 v153, s72, v145
	ds_read_b128 v[200:203], v153
	ds_read_b128 v[204:207], v153 offset:1024
	ds_read_b128 v[208:211], v153 offset:2048
	ds_read_b128 v[212:215], v153 offset:3072
	s_add_u32 s50, s50, 0x40000
	s_addc_u32 s51, s51, 0
	s_mov_b32 m0, s3
	v_lshl_add_u64 v[250:251], s[50:51], 0, v[130:131]
	ds_read_b128 v[216:219], v149 offset:32768
	ds_read_b128 v[220:223], v149 offset:33792
	ds_read_b128 v[224:227], v149 offset:34816
	ds_read_b128 v[228:231], v149 offset:35840
	ds_read_b128 v[232:235], v149 offset:36864
	ds_read_b128 v[236:239], v149 offset:37888
	ds_read_b128 v[240:243], v149 offset:38912
	ds_read_b128 v[244:247], v149 offset:39936
	global_load_lds_dwordx4 v[250:251], off
	v_lshl_add_u64 v[250:251], s[50:51], 0, v[134:135]
	s_mov_b32 m0, s87
	s_nop 0
	global_load_lds_dwordx4 v[250:251], off
	s_waitcnt vmcnt(8)
	s_waitcnt lgkmcnt(0)
	s_barrier
	v_mfma_f32_16x16x32_bf16 v[126:129], v[174:177], v[216:219], v[126:129]
	v_mfma_f32_16x16x32_bf16 v[122:125], v[182:185], v[216:219], v[122:125]
	v_mfma_f32_16x16x32_bf16 v[110:113], v[174:177], v[224:227], v[110:113]
	v_mfma_f32_16x16x32_bf16 v[106:109], v[182:185], v[224:227], v[106:109]
	v_mfma_f32_16x16x32_bf16 v[94:97], v[174:177], v[232:235], v[94:97]
	v_mfma_f32_16x16x32_bf16 v[90:93], v[182:185], v[232:235], v[90:93]
	v_mfma_f32_16x16x32_bf16 v[78:81], v[174:177], v[240:243], v[78:81]
	v_mfma_f32_16x16x32_bf16 v[74:77], v[182:185], v[240:243], v[74:77]
	v_mfma_f32_16x16x32_bf16 v[126:129], v[178:181], v[220:223], v[126:129]
	v_mfma_f32_16x16x32_bf16 v[122:125], v[196:199], v[220:223], v[122:125]
	v_mfma_f32_16x16x32_bf16 v[110:113], v[178:181], v[228:231], v[110:113]
	v_mfma_f32_16x16x32_bf16 v[106:109], v[196:199], v[228:231], v[106:109]
	v_mfma_f32_16x16x32_bf16 v[94:97], v[178:181], v[236:239], v[94:97]
	v_mfma_f32_16x16x32_bf16 v[90:93], v[196:199], v[236:239], v[90:93]
	v_mfma_f32_16x16x32_bf16 v[78:81], v[178:181], v[244:247], v[78:81]
	v_mfma_f32_16x16x32_bf16 v[74:77], v[196:199], v[244:247], v[74:77]
	v_mfma_f32_16x16x32_bf16 v[118:121], v[200:203], v[216:219], v[118:121]
	v_mfma_f32_16x16x32_bf16 v[114:117], v[208:211], v[216:219], v[114:117]
	v_mfma_f32_16x16x32_bf16 v[102:105], v[200:203], v[224:227], v[102:105]
	v_mfma_f32_16x16x32_bf16 v[98:101], v[208:211], v[224:227], v[98:101]
	v_mfma_f32_16x16x32_bf16 v[86:89], v[200:203], v[232:235], v[86:89]
	v_mfma_f32_16x16x32_bf16 v[82:85], v[208:211], v[232:235], v[82:85]
	v_mfma_f32_16x16x32_bf16 v[70:73], v[200:203], v[240:243], v[70:73]
	v_mfma_f32_16x16x32_bf16 v[66:69], v[208:211], v[240:243], v[66:69]
	v_mfma_f32_16x16x32_bf16 v[118:121], v[204:207], v[220:223], v[118:121]
	v_mfma_f32_16x16x32_bf16 v[114:117], v[212:215], v[220:223], v[114:117]
	v_mfma_f32_16x16x32_bf16 v[102:105], v[204:207], v[228:231], v[102:105]
	v_mfma_f32_16x16x32_bf16 v[98:101], v[212:215], v[228:231], v[98:101]
	v_mfma_f32_16x16x32_bf16 v[86:89], v[204:207], v[236:239], v[86:89]
	v_mfma_f32_16x16x32_bf16 v[82:85], v[212:215], v[236:239], v[82:85]
	v_mfma_f32_16x16x32_bf16 v[70:73], v[204:207], v[244:247], v[70:73]
	v_mfma_f32_16x16x32_bf16 v[66:69], v[212:215], v[244:247], v[66:69]
	s_barrier
; #define PG8_STAGE(bufoff, gbase, voff) do { _Pragma("unroll") for (int _i = 0; _i < 2; ++_i) \
;         __builtin_amdgcn_global_load_lds((const unsigned*)((const char*)(gbase) + (voff)[_i]), (PG8_LAS unsigned*)(lds + (bufoff) + ldsw + _i * 8192), 16, 0, 0); } while (0)
; #define PG8_LDA(dst, b, h) do { _Pragma("unroll") for (int m = 0; m < 4; ++m) _Pragma("unroll") for (int k = 0; k < 2; ++k) dst[m][k] = *(const PG8_LAS bf16x8*)(lds + PG8_SA(b, h) + aoff + m * 2048 + k * 1024); } while (0)
; #define PG8_MMA(ai, bj, At, Bt) do { __builtin_amdgcn_s_setprio(1); _Pragma("unroll") for (int m = 0; m < 4; ++m) _Pragma("unroll") for (int n = 0; n < 2; ++n) _Pragma("unroll") for (int k = 0; k < 2; ++k) \
;         acc[ai][bj][m][n] = __builtin_amdgcn_mfma_f32_16x16x32_bf16(Bt[n][k], At[m][k], acc[ai][bj][m][n], 0, 0, 0); __builtin_amdgcn_s_setprio(0); } while (0)
; #define PG8_WAIT_V(n) asm volatile("s_waitcnt vmcnt(" #n ")" ::: "memory")
; #define PG8_WAIT_L(n) asm volatile("s_waitcnt lgkmcnt(" #n ")" ::: "memory")
; #define PG8_BAR __builtin_amdgcn_s_barrier()
; #define PG8_SCHED __builtin_amdgcn_sched_barrier(0)
; template <class Epi, class Sched, bool ALIGN_EPI = false, bool SP2 = false>
; __device__ __forceinline__ void gemm_phase(PG8_LAS unsigned char* lds, const Gemm g, const Sched& S, const Epi& E) {
;     ...
;             PG8_LDA(At, 1, 1); PG8_STAGE(PG8_SB(1, 0), b3, voffB); PG8_STAGE(PG8_SB(1, 1), b3 + hstep, voffB); PG8_STAGE(PG8_SA(1, 0), a3, voffA);
;             PG8_WAIT_V(8); PG8_WAIT_L(0); PG8_BAR; PG8_MMA(1, 0, At, B0); PG8_MMA(1, 1, At, B1); PG8_BAR; PG8_SCHED;
;     ...
;         if constexpr (ALIGN_EPI) { if (wr == 0) PG8_BAR; }
	s_add_i32 s50, s61, s38
	v_lshl_add_u64 v[150:151], v[150:151], 0, s[34:35]
	s_mov_b32 m0, s50
	ds_read_b128 v[216:219], v149 offset:49152
	ds_read_b128 v[220:223], v149 offset:50176
	ds_read_b128 v[224:227], v149 offset:51200
	ds_read_b128 v[228:231], v149 offset:52224
	ds_read_b128 v[232:235], v149 offset:53248
	ds_read_b128 v[236:239], v149 offset:54272
	ds_read_b128 v[240:243], v149 offset:55296
	ds_read_b128 v[244:247], v149 offset:56320
	global_load_lds_dwordx4 v[150:151], off
	s_add_i32 m0, s50, 0x2000
	s_add_u32 s48, s48, 0x40080
	v_lshl_add_u64 v[150:151], v[160:161], 0, s[34:35]
	s_addc_u32 s49, s49, 0
	s_add_i32 s50, s72, s38
	global_load_lds_dwordx4 v[150:151], off
	v_lshl_add_u64 v[150:151], s[48:49], 0, v[132:133]
	s_mov_b32 m0, s50
	s_nop 0
	global_load_lds_dwordx4 v[150:151], off
	v_lshl_add_u64 v[150:151], s[48:49], 0, v[136:137]
	s_add_i32 m0, s50, 0x2000
	s_nop 0
	global_load_lds_dwordx4 v[150:151], off
	v_lshl_add_u64 v[150:151], v[170:171], 0, s[34:35]
	s_mov_b32 m0, s0
	s_nop 0
	global_load_lds_dwordx4 v[150:151], off
	v_lshl_add_u64 v[150:151], v[248:249], 0, s[34:35]
	s_mov_b32 m0, s86
	s_nop 0
	global_load_lds_dwordx4 v[150:151], off
	s_waitcnt vmcnt(8)
	s_waitcnt lgkmcnt(0)
	s_barrier
	v_mfma_f32_16x16x32_bf16 v[62:65], v[174:177], v[216:219], v[62:65]
	v_mfma_f32_16x16x32_bf16 v[58:61], v[182:185], v[216:219], v[58:61]
	v_mfma_f32_16x16x32_bf16 v[46:49], v[174:177], v[224:227], v[46:49]
	v_mfma_f32_16x16x32_bf16 v[42:45], v[182:185], v[224:227], v[42:45]
	v_mfma_f32_16x16x32_bf16 v[28:31], v[174:177], v[232:235], v[28:31]
	v_mfma_f32_16x16x32_bf16 v[24:27], v[182:185], v[232:235], v[24:27]
	v_mfma_f32_16x16x32_bf16 v[12:15], v[174:177], v[240:243], v[12:15]
	v_mfma_f32_16x16x32_bf16 v[8:11], v[182:185], v[240:243], v[8:11]
	v_mfma_f32_16x16x32_bf16 v[62:65], v[178:181], v[220:223], v[62:65]
	v_mfma_f32_16x16x32_bf16 v[58:61], v[196:199], v[220:223], v[58:61]
	v_mfma_f32_16x16x32_bf16 v[46:49], v[178:181], v[228:231], v[46:49]
	v_mfma_f32_16x16x32_bf16 v[42:45], v[196:199], v[228:231], v[42:45]
	v_mfma_f32_16x16x32_bf16 v[28:31], v[178:181], v[236:239], v[28:31]
	v_mfma_f32_16x16x32_bf16 v[24:27], v[196:199], v[236:239], v[24:27]
	v_mfma_f32_16x16x32_bf16 v[12:15], v[178:181], v[244:247], v[12:15]
	v_mfma_f32_16x16x32_bf16 v[8:11], v[196:199], v[244:247], v[8:11]
	v_mfma_f32_16x16x32_bf16 v[54:57], v[200:203], v[216:219], v[54:57]
	v_mfma_f32_16x16x32_bf16 v[50:53], v[208:211], v[216:219], v[50:53]
	v_mfma_f32_16x16x32_bf16 v[38:41], v[200:203], v[224:227], v[38:41]
	v_mfma_f32_16x16x32_bf16 v[34:37], v[208:211], v[224:227], v[34:37]
	v_mfma_f32_16x16x32_bf16 v[20:23], v[200:203], v[232:235], v[20:23]
	v_mfma_f32_16x16x32_bf16 v[16:19], v[208:211], v[232:235], v[16:19]
	v_mfma_f32_16x16x32_bf16 v[4:7], v[200:203], v[240:243], v[4:7]
	v_mfma_f32_16x16x32_bf16 v[0:3], v[208:211], v[240:243], v[0:3]
	v_mfma_f32_16x16x32_bf16 v[54:57], v[204:207], v[220:223], v[54:57]
	v_mfma_f32_16x16x32_bf16 v[50:53], v[212:215], v[220:223], v[50:53]
	v_mfma_f32_16x16x32_bf16 v[38:41], v[204:207], v[228:231], v[38:41]
	v_mfma_f32_16x16x32_bf16 v[34:37], v[212:215], v[228:231], v[34:37]
	v_mfma_f32_16x16x32_bf16 v[20:23], v[204:207], v[236:239], v[20:23]
	v_mfma_f32_16x16x32_bf16 v[16:19], v[212:215], v[236:239], v[16:19]
	v_mfma_f32_16x16x32_bf16 v[4:7], v[204:207], v[244:247], v[4:7]
	v_mfma_f32_16x16x32_bf16 v[0:3], v[212:215], v[244:247], v[0:3]
	s_barrier
	s_add_i32 vcc_lo, vcc_lo, 2
	s_add_u32 s89, s89, 0x100
	s_addc_u32 s91, s91, 0
	s_add_u32 s46, s46, 0x100
	s_addc_u32 s47, s47, 0
	s_cmp_gt_u32 vcc_lo, 13
	s_cbranch_scc0 .LBB0_118
	v_readlane_b32 s46, v254, 51
	v_readlane_b32 s47, v254, 52
	s_and_b64 vcc, exec, s[46:47]
	s_cbranch_vccz .LBB0_121
	s_barrier

; #define PG8_STAGE(bufoff, gbase, voff) do { _Pragma("unroll") for (int _i = 0; _i < 2; ++_i) \
;         __builtin_amdgcn_global_load_lds((const unsigned*)((const char*)(gbase) + (voff)[_i]), (PG8_LAS unsigned*)(lds + (bufoff) + ldsw + _i * 8192), 16, 0, 0); } while (0)
; #define PG8_LDA(dst, b, h) do { _Pragma("unroll") for (int m = 0; m < 4; ++m) _Pragma("unroll") for (int k = 0; k < 2; ++k) dst[m][k] = *(const PG8_LAS bf16x8*)(lds + PG8_SA(b, h) + aoff + m * 2048 + k * 1024); } while (0)
; #define PG8_LDB(dst, b, h) do { _Pragma("unroll") for (int n = 0; n < 2; ++n) _Pragma("unroll") for (int k = 0; k < 2; ++k) dst[n][k] = *(const PG8_LAS bf16x8*)(lds + PG8_SB(b, h) + boff + n * 2048 + k * 1024); } while (0)
; #define PG8_MMA(ai, bj, At, Bt) do { __builtin_amdgcn_s_setprio(1); _Pragma("unroll") for (int m = 0; m < 4; ++m) _Pragma("unroll") for (int n = 0; n < 2; ++n) _Pragma("unroll") for (int k = 0; k < 2; ++k) \
;         acc[ai][bj][m][n] = __builtin_amdgcn_mfma_f32_16x16x32_bf16(Bt[n][k], At[m][k], acc[ai][bj][m][n], 0, 0, 0); __builtin_amdgcn_s_setprio(0); } while (0)
; #define PG8_WAIT_V(n) asm volatile("s_waitcnt vmcnt(" #n ")" ::: "memory")
; #define PG8_WAIT_L(n) asm volatile("s_waitcnt lgkmcnt(" #n ")" ::: "memory")
; template <class Epi, class Sched, bool ALIGN_EPI = false, bool SP2 = false>
; __device__ __forceinline__ void gemm_phase(PG8_LAS unsigned char* lds, const Gemm g, const Sched& S, const Epi& E) {
;     ...
;             const bool last = (t == nt - 2);
;             const char* a1 = cA + (size_t)(t + 1) * kstep;
;             const char* a2 = last ? nA : cA + (size_t)(t + 2) * kstep; const char* b2 = last ? nB : cB + (size_t)(t + 2) * kstep;
;             const char* a3 = a2 + kstep; const char* b3 = b2 + kstep;
;             if (last && has_next) S.a_ready(nxt);
;             if constexpr (SP2) {
;             PG8_LDB(B0, 0, 0); PG8_LDB(B1, 0, 1); PG8_SCHED; PG8_LDA(At, 0, 0); PG8_STAGE(PG8_SA(1, 1), a1 + hstep, voffA);
;             PG8_WAIT_V(8); PG8_WAIT_L(0); PG8_BAR; PG8_MMA(0, 0, At, B0); PG8_MMA(0, 1, At, B1); PG8_BAR; PG8_SCHED;
;             PG8_LDA(At, 0, 1); PG8_STAGE(PG8_SB(0, 0), b2, voffB); PG8_STAGE(PG8_SB(0, 1), b2 + hstep, voffB); PG8_STAGE(PG8_SA(0, 0), a2, voffA);
;             PG8_WAIT_V(8); PG8_WAIT_L(0); PG8_BAR; PG8_MMA(1, 0, At, B0); PG8_MMA(1, 1, At, B1); PG8_BAR; PG8_SCHED;
.LBB0_145:
	s_add_u32 s48, s46, 0xfffc0080
	s_addc_u32 s49, s47, -1
	s_add_i32 s61, 0, 0x10000
	s_cmp_eq_u32 s80, 12
	s_cselect_b32 s51, s3, s49
	s_cselect_b32 s50, s45, s48
	s_cselect_b32 s49, s89, s7
	s_cselect_b32 s48, vcc_lo, vcc_hi
	s_add_i32 s72, 0, 0x14000
	v_add_u32_e32 v70, s61, v176
	v_add_u32_e32 v174, s72, v176
	ds_read_b128 v[50:53], v70
	ds_read_b128 v[54:57], v70 offset:1024
	ds_read_b128 v[66:69], v70 offset:2048
	ds_read_b128 v[70:73], v70 offset:3072
	ds_read_b128 v[158:161], v174
	ds_read_b128 v[170:173], v174 offset:1024
	ds_read_b128 v[180:183], v174 offset:2048
	ds_read_b128 v[196:199], v174 offset:3072
	v_lshl_add_u64 v[174:175], s[46:47], 0, v[156:157]
	s_add_i32 m0, s5, 0xc000
	ds_read_b128 v[200:203], v178
	ds_read_b128 v[204:207], v178 offset:1024
	ds_read_b128 v[208:211], v178 offset:2048
	ds_read_b128 v[212:215], v178 offset:3072
	ds_read_b128 v[216:219], v178 offset:4096
	ds_read_b128 v[220:223], v178 offset:5120
	ds_read_b128 v[224:227], v178 offset:6144
	ds_read_b128 v[228:231], v178 offset:7168
	global_load_lds_dwordx4 v[174:175], off
	v_lshl_add_u64 v[174:175], s[46:47], 0, v[154:155]
	s_add_i32 m0, s5, 0xe000
	s_nop 0
	global_load_lds_dwordx4 v[174:175], off
	s_waitcnt vmcnt(8)
	s_waitcnt lgkmcnt(0)
	s_barrier
	v_mfma_f32_16x16x32_bf16 v[142:145], v[50:53], v[200:203], v[142:145]
	v_mfma_f32_16x16x32_bf16 v[138:141], v[66:69], v[200:203], v[138:141]
	v_mfma_f32_16x16x32_bf16 v[126:129], v[50:53], v[208:211], v[126:129]
	v_mfma_f32_16x16x32_bf16 v[122:125], v[66:69], v[208:211], v[122:125]
	v_mfma_f32_16x16x32_bf16 v[110:113], v[50:53], v[216:219], v[110:113]
	v_mfma_f32_16x16x32_bf16 v[106:109], v[66:69], v[216:219], v[106:109]
	v_mfma_f32_16x16x32_bf16 v[94:97], v[50:53], v[224:227], v[94:97]
	v_mfma_f32_16x16x32_bf16 v[90:93], v[66:69], v[224:227], v[90:93]
	v_mfma_f32_16x16x32_bf16 v[142:145], v[54:57], v[204:207], v[142:145]
	v_mfma_f32_16x16x32_bf16 v[138:141], v[70:73], v[204:207], v[138:141]
	v_mfma_f32_16x16x32_bf16 v[126:129], v[54:57], v[212:215], v[126:129]
	v_mfma_f32_16x16x32_bf16 v[122:125], v[70:73], v[212:215], v[122:125]
	v_mfma_f32_16x16x32_bf16 v[110:113], v[54:57], v[220:223], v[110:113]
	v_mfma_f32_16x16x32_bf16 v[106:109], v[70:73], v[220:223], v[106:109]
	v_mfma_f32_16x16x32_bf16 v[94:97], v[54:57], v[228:231], v[94:97]
	v_mfma_f32_16x16x32_bf16 v[90:93], v[70:73], v[228:231], v[90:93]
	v_mfma_f32_16x16x32_bf16 v[134:137], v[158:161], v[200:203], v[134:137]
	v_mfma_f32_16x16x32_bf16 v[130:133], v[180:183], v[200:203], v[130:133]
	v_mfma_f32_16x16x32_bf16 v[118:121], v[158:161], v[208:211], v[118:121]
	v_mfma_f32_16x16x32_bf16 v[114:117], v[180:183], v[208:211], v[114:117]
	v_mfma_f32_16x16x32_bf16 v[102:105], v[158:161], v[216:219], v[102:105]
	v_mfma_f32_16x16x32_bf16 v[98:101], v[180:183], v[216:219], v[98:101]
	v_mfma_f32_16x16x32_bf16 v[86:89], v[158:161], v[224:227], v[86:89]
	v_mfma_f32_16x16x32_bf16 v[82:85], v[180:183], v[224:227], v[82:85]
	v_mfma_f32_16x16x32_bf16 v[134:137], v[170:173], v[204:207], v[134:137]
	v_mfma_f32_16x16x32_bf16 v[130:133], v[196:199], v[204:207], v[130:133]
	v_mfma_f32_16x16x32_bf16 v[118:121], v[170:173], v[212:215], v[118:121]
	v_mfma_f32_16x16x32_bf16 v[114:117], v[196:199], v[212:215], v[114:117]
	v_mfma_f32_16x16x32_bf16 v[102:105], v[170:173], v[220:223], v[102:105]
	v_mfma_f32_16x16x32_bf16 v[98:101], v[196:199], v[220:223], v[98:101]
	v_mfma_f32_16x16x32_bf16 v[86:89], v[170:173], v[228:231], v[86:89]
	v_mfma_f32_16x16x32_bf16 v[82:85], v[196:199], v[228:231], v[82:85]
	s_barrier
	s_add_i32 s61, s61, s4
	v_lshl_add_u64 v[174:175], s[48:49], 0, v[148:149]
	s_mov_b32 m0, s61
	ds_read_b128 v[200:203], v178 offset:16384
	ds_read_b128 v[204:207], v178 offset:17408
	ds_read_b128 v[208:211], v178 offset:18432
	ds_read_b128 v[212:215], v178 offset:19456
	ds_read_b128 v[216:219], v178 offset:20480
	ds_read_b128 v[220:223], v178 offset:21504
	ds_read_b128 v[224:227], v178 offset:22528
	ds_read_b128 v[228:231], v178 offset:23552
	global_load_lds_dwordx4 v[174:175], off
	s_add_i32 m0, s61, 0x2000
	s_add_u32 s76, s48, 0x40000
	v_lshl_add_u64 v[184:185], s[48:49], 0, v[152:153]
	s_addc_u32 s77, s49, 0
	s_add_i32 s61, s72, s4
	global_load_lds_dwordx4 v[184:185], off
	v_lshl_add_u64 v[232:233], s[76:77], 0, v[148:149]
	s_mov_b32 m0, s61
	v_lshl_add_u64 v[234:235], s[50:51], 0, v[150:151]
	global_load_lds_dwordx4 v[232:233], off
	v_lshl_add_u64 v[232:233], s[76:77], 0, v[152:153]
	s_add_i32 m0, s61, 0x2000
	s_nop 0
	global_load_lds_dwordx4 v[232:233], off
	v_lshl_add_u64 v[232:233], s[50:51], 0, v[146:147]
	s_mov_b32 m0, s5
	s_nop 0
	global_load_lds_dwordx4 v[232:233], off
	s_mov_b32 m0, s91
	s_nop 0
	global_load_lds_dwordx4 v[234:235], off
	s_waitcnt vmcnt(8)
	s_waitcnt lgkmcnt(0)
	s_barrier
; #define PG8_STAGE(bufoff, gbase, voff) do { _Pragma("unroll") for (int _i = 0; _i < 2; ++_i) \
;         __builtin_amdgcn_global_load_lds((const unsigned*)((const char*)(gbase) + (voff)[_i]), (PG8_LAS unsigned*)(lds + (bufoff) + ldsw + _i * 8192), 16, 0, 0); } while (0)
; #define PG8_LDA(dst, b, h) do { _Pragma("unroll") for (int m = 0; m < 4; ++m) _Pragma("unroll") for (int k = 0; k < 2; ++k) dst[m][k] = *(const PG8_LAS bf16x8*)(lds + PG8_SA(b, h) + aoff + m * 2048 + k * 1024); } while (0)
; #define PG8_LDB(dst, b, h) do { _Pragma("unroll") for (int n = 0; n < 2; ++n) _Pragma("unroll") for (int k = 0; k < 2; ++k) dst[n][k] = *(const PG8_LAS bf16x8*)(lds + PG8_SB(b, h) + boff + n * 2048 + k * 1024); } while (0)
; #define PG8_MMA(ai, bj, At, Bt) do { __builtin_amdgcn_s_setprio(1); _Pragma("unroll") for (int m = 0; m < 4; ++m) _Pragma("unroll") for (int n = 0; n < 2; ++n) _Pragma("unroll") for (int k = 0; k < 2; ++k) \
;         acc[ai][bj][m][n] = __builtin_amdgcn_mfma_f32_16x16x32_bf16(Bt[n][k], At[m][k], acc[ai][bj][m][n], 0, 0, 0); __builtin_amdgcn_s_setprio(0); } while (0)
; #define PG8_WAIT_V(n) asm volatile("s_waitcnt vmcnt(" #n ")" ::: "memory")
; #define PG8_WAIT_L(n) asm volatile("s_waitcnt lgkmcnt(" #n ")" ::: "memory")
; #define PG8_BAR __builtin_amdgcn_s_barrier()
; #define PG8_SCHED __builtin_amdgcn_sched_barrier(0)
; template <class Epi, class Sched, bool ALIGN_EPI = false, bool SP2 = false>
; __device__ __forceinline__ void gemm_phase(PG8_LAS unsigned char* lds, const Gemm g, const Sched& S, const Epi& E) {
;     ...
;             PG8_WAIT_V(8); PG8_WAIT_L(0); PG8_BAR; PG8_MMA(1, 0, At, B0); PG8_MMA(1, 1, At, B1); PG8_BAR; PG8_SCHED;
;             PG8_LDB(B0, 1, 0); PG8_LDB(B1, 1, 1); PG8_SCHED; PG8_LDA(At, 1, 0); PG8_STAGE(PG8_SA(0, 1), a2 + hstep, voffA);
;             PG8_WAIT_V(8); PG8_WAIT_L(0); PG8_BAR; PG8_MMA(0, 0, At, B0); PG8_MMA(0, 1, At, B1); PG8_BAR; PG8_SCHED;
	v_mfma_f32_16x16x32_bf16 v[78:81], v[50:53], v[200:203], v[78:81]
	v_mfma_f32_16x16x32_bf16 v[74:77], v[66:69], v[200:203], v[74:77]
	v_mfma_f32_16x16x32_bf16 v[46:49], v[50:53], v[208:211], v[46:49]
	v_mfma_f32_16x16x32_bf16 v[42:45], v[66:69], v[208:211], v[42:45]
	v_mfma_f32_16x16x32_bf16 v[28:31], v[50:53], v[216:219], v[28:31]
	v_mfma_f32_16x16x32_bf16 v[24:27], v[66:69], v[216:219], v[24:27]
	v_mfma_f32_16x16x32_bf16 v[12:15], v[50:53], v[224:227], v[12:15]
	v_mfma_f32_16x16x32_bf16 v[8:11], v[66:69], v[224:227], v[8:11]
	v_mfma_f32_16x16x32_bf16 v[78:81], v[54:57], v[204:207], v[78:81]
	v_mfma_f32_16x16x32_bf16 v[74:77], v[70:73], v[204:207], v[74:77]
	v_mfma_f32_16x16x32_bf16 v[46:49], v[54:57], v[212:215], v[46:49]
	v_mfma_f32_16x16x32_bf16 v[42:45], v[70:73], v[212:215], v[42:45]
	v_mfma_f32_16x16x32_bf16 v[28:31], v[54:57], v[220:223], v[28:31]
	v_mfma_f32_16x16x32_bf16 v[24:27], v[70:73], v[220:223], v[24:27]
	v_mfma_f32_16x16x32_bf16 v[12:15], v[54:57], v[228:231], v[12:15]
	v_mfma_f32_16x16x32_bf16 v[8:11], v[70:73], v[228:231], v[8:11]
	v_mfma_f32_16x16x32_bf16 v[38:41], v[158:161], v[208:211], v[38:41]
	v_mfma_f32_16x16x32_bf16 v[34:37], v[180:183], v[208:211], v[34:37]
	v_mfma_f32_16x16x32_bf16 v[20:23], v[158:161], v[216:219], v[20:23]
	v_mfma_f32_16x16x32_bf16 v[16:19], v[180:183], v[216:219], v[16:19]
	v_mfma_f32_16x16x32_bf16 v[4:7], v[158:161], v[224:227], v[4:7]
	v_mfma_f32_16x16x32_bf16 v[0:3], v[180:183], v[224:227], v[0:3]
	v_mfma_f32_16x16x32_bf16 v[50:53], v[158:161], v[200:203], v[62:65]
	v_mfma_f32_16x16x32_bf16 v[54:57], v[180:183], v[200:203], v[58:61]
	v_mfma_f32_16x16x32_bf16 v[38:41], v[170:173], v[212:215], v[38:41]
	v_mfma_f32_16x16x32_bf16 v[34:37], v[196:199], v[212:215], v[34:37]
	v_mfma_f32_16x16x32_bf16 v[20:23], v[170:173], v[220:223], v[20:23]
	v_mfma_f32_16x16x32_bf16 v[16:19], v[196:199], v[220:223], v[16:19]
	v_mfma_f32_16x16x32_bf16 v[4:7], v[170:173], v[228:231], v[4:7]
	v_mfma_f32_16x16x32_bf16 v[0:3], v[196:199], v[228:231], v[0:3]
	v_mfma_f32_16x16x32_bf16 v[50:53], v[170:173], v[204:207], v[50:53]
	v_mfma_f32_16x16x32_bf16 v[54:57], v[196:199], v[204:207], v[54:57]
	s_barrier
	s_add_i32 s61, 0, 0x18000
	s_add_i32 s72, 0, 0x1c000
	v_add_u32_e32 v70, s61, v176
	v_add_u32_e32 v179, s72, v176
	ds_read_b128 v[58:61], v70
	ds_read_b128 v[62:65], v70 offset:1024
	ds_read_b128 v[66:69], v70 offset:2048
	ds_read_b128 v[70:73], v70 offset:3072
	ds_read_b128 v[158:161], v179
	ds_read_b128 v[170:173], v179 offset:1024
	ds_read_b128 v[180:183], v179 offset:2048
	ds_read_b128 v[196:199], v179 offset:3072
	s_add_u32 s50, s50, 0x40000
	s_addc_u32 s51, s51, 0
	s_mov_b32 m0, s8
	v_lshl_add_u64 v[236:237], s[50:51], 0, v[146:147]
	ds_read_b128 v[200:203], v178 offset:32768
	ds_read_b128 v[204:207], v178 offset:33792
	ds_read_b128 v[208:211], v178 offset:34816
	ds_read_b128 v[212:215], v178 offset:35840
	ds_read_b128 v[216:219], v178 offset:36864
	ds_read_b128 v[220:223], v178 offset:37888
	ds_read_b128 v[224:227], v178 offset:38912
	ds_read_b128 v[228:231], v178 offset:39936
	global_load_lds_dwordx4 v[236:237], off
	v_lshl_add_u64 v[236:237], s[50:51], 0, v[150:151]
	s_mov_b32 m0, s0
	s_nop 0
	global_load_lds_dwordx4 v[236:237], off
	s_waitcnt vmcnt(8)
	s_waitcnt lgkmcnt(0)
	s_barrier
	v_mfma_f32_16x16x32_bf16 v[142:145], v[58:61], v[200:203], v[142:145]
	v_mfma_f32_16x16x32_bf16 v[138:141], v[66:69], v[200:203], v[138:141]
	v_mfma_f32_16x16x32_bf16 v[126:129], v[58:61], v[208:211], v[126:129]
	v_mfma_f32_16x16x32_bf16 v[122:125], v[66:69], v[208:211], v[122:125]
	v_mfma_f32_16x16x32_bf16 v[110:113], v[58:61], v[216:219], v[110:113]
	v_mfma_f32_16x16x32_bf16 v[106:109], v[66:69], v[216:219], v[106:109]
	v_mfma_f32_16x16x32_bf16 v[94:97], v[58:61], v[224:227], v[94:97]
	v_mfma_f32_16x16x32_bf16 v[90:93], v[66:69], v[224:227], v[90:93]
	v_mfma_f32_16x16x32_bf16 v[142:145], v[62:65], v[204:207], v[142:145]
	v_mfma_f32_16x16x32_bf16 v[138:141], v[70:73], v[204:207], v[138:141]
	v_mfma_f32_16x16x32_bf16 v[126:129], v[62:65], v[212:215], v[126:129]
	v_mfma_f32_16x16x32_bf16 v[122:125], v[70:73], v[212:215], v[122:125]
	v_mfma_f32_16x16x32_bf16 v[110:113], v[62:65], v[220:223], v[110:113]
	v_mfma_f32_16x16x32_bf16 v[106:109], v[70:73], v[220:223], v[106:109]
	v_mfma_f32_16x16x32_bf16 v[94:97], v[62:65], v[228:231], v[94:97]
	v_mfma_f32_16x16x32_bf16 v[90:93], v[70:73], v[228:231], v[90:93]
	v_mfma_f32_16x16x32_bf16 v[134:137], v[158:161], v[200:203], v[134:137]
	v_mfma_f32_16x16x32_bf16 v[130:133], v[180:183], v[200:203], v[130:133]
	v_mfma_f32_16x16x32_bf16 v[118:121], v[158:161], v[208:211], v[118:121]
	v_mfma_f32_16x16x32_bf16 v[114:117], v[180:183], v[208:211], v[114:117]
	v_mfma_f32_16x16x32_bf16 v[102:105], v[158:161], v[216:219], v[102:105]
	v_mfma_f32_16x16x32_bf16 v[98:101], v[180:183], v[216:219], v[98:101]
	v_mfma_f32_16x16x32_bf16 v[86:89], v[158:161], v[224:227], v[86:89]
	v_mfma_f32_16x16x32_bf16 v[82:85], v[180:183], v[224:227], v[82:85]
	v_mfma_f32_16x16x32_bf16 v[134:137], v[170:173], v[204:207], v[134:137]
	v_mfma_f32_16x16x32_bf16 v[130:133], v[196:199], v[204:207], v[130:133]
	v_mfma_f32_16x16x32_bf16 v[118:121], v[170:173], v[212:215], v[118:121]
	v_mfma_f32_16x16x32_bf16 v[114:117], v[196:199], v[212:215], v[114:117]
	v_mfma_f32_16x16x32_bf16 v[102:105], v[170:173], v[220:223], v[102:105]
	v_mfma_f32_16x16x32_bf16 v[98:101], v[196:199], v[220:223], v[98:101]
	v_mfma_f32_16x16x32_bf16 v[86:89], v[170:173], v[228:231], v[86:89]
	v_mfma_f32_16x16x32_bf16 v[82:85], v[196:199], v[228:231], v[82:85]
	s_barrier
; #define PG8_STAGE(bufoff, gbase, voff) do { _Pragma("unroll") for (int _i = 0; _i < 2; ++_i) \
;         __builtin_amdgcn_global_load_lds((const unsigned*)((const char*)(gbase) + (voff)[_i]), (PG8_LAS unsigned*)(lds + (bufoff) + ldsw + _i * 8192), 16, 0, 0); } while (0)
; #define PG8_LDA(dst, b, h) do { _Pragma("unroll") for (int m = 0; m < 4; ++m) _Pragma("unroll") for (int k = 0; k < 2; ++k) dst[m][k] = *(const PG8_LAS bf16x8*)(lds + PG8_SA(b, h) + aoff + m * 2048 + k * 1024); } while (0)
; #define PG8_MMA(ai, bj, At, Bt) do { __builtin_amdgcn_s_setprio(1); _Pragma("unroll") for (int m = 0; m < 4; ++m) _Pragma("unroll") for (int n = 0; n < 2; ++n) _Pragma("unroll") for (int k = 0; k < 2; ++k) \
;         acc[ai][bj][m][n] = __builtin_amdgcn_mfma_f32_16x16x32_bf16(Bt[n][k], At[m][k], acc[ai][bj][m][n], 0, 0, 0); __builtin_amdgcn_s_setprio(0); } while (0)
; #define PG8_WAIT_V(n) asm volatile("s_waitcnt vmcnt(" #n ")" ::: "memory")
; #define PG8_WAIT_L(n) asm volatile("s_waitcnt lgkmcnt(" #n ")" ::: "memory")
; #define PG8_BAR __builtin_amdgcn_s_barrier()
; #define PG8_SCHED __builtin_amdgcn_sched_barrier(0)
; template <class Epi, class Sched, bool ALIGN_EPI = false, bool SP2 = false>
; __device__ __forceinline__ void gemm_phase(PG8_LAS unsigned char* lds, const Gemm g, const Sched& S, const Epi& E) {
;     ...
;             PG8_LDA(At, 1, 1); PG8_STAGE(PG8_SB(1, 0), b3, voffB); PG8_STAGE(PG8_SB(1, 1), b3 + hstep, voffB); PG8_STAGE(PG8_SA(1, 0), a3, voffA);
;             PG8_WAIT_V(8); PG8_WAIT_L(0); PG8_BAR; PG8_MMA(1, 0, At, B0); PG8_MMA(1, 1, At, B1); PG8_BAR; PG8_SCHED;
;     ...
;         if constexpr (ALIGN_EPI) { if (wr == 0) PG8_BAR; }
	s_add_i32 s50, s61, s4
	v_lshl_add_u64 v[174:175], v[174:175], 0, s[34:35]
	s_mov_b32 m0, s50
	ds_read_b128 v[200:203], v178 offset:49152
	ds_read_b128 v[204:207], v178 offset:50176
	ds_read_b128 v[208:211], v178 offset:51200
	ds_read_b128 v[212:215], v178 offset:52224
	ds_read_b128 v[216:219], v178 offset:53248
	ds_read_b128 v[220:223], v178 offset:54272
	ds_read_b128 v[224:227], v178 offset:55296
	ds_read_b128 v[228:231], v178 offset:56320
	global_load_lds_dwordx4 v[174:175], off
	s_add_i32 m0, s50, 0x2000
	s_add_u32 s48, s48, 0x40080
	v_lshl_add_u64 v[174:175], v[184:185], 0, s[34:35]
	s_addc_u32 s49, s49, 0
	s_add_i32 s50, s72, s4
	global_load_lds_dwordx4 v[174:175], off
	v_lshl_add_u64 v[174:175], s[48:49], 0, v[148:149]
	s_mov_b32 m0, s50
	s_nop 0
	global_load_lds_dwordx4 v[174:175], off
	v_lshl_add_u64 v[174:175], s[48:49], 0, v[152:153]
	s_add_i32 m0, s50, 0x2000
	s_nop 0
	global_load_lds_dwordx4 v[174:175], off
	v_lshl_add_u64 v[174:175], v[232:233], 0, s[34:35]
	s_mov_b32 m0, s9
	s_nop 0
	global_load_lds_dwordx4 v[174:175], off
	v_lshl_add_u64 v[174:175], v[234:235], 0, s[34:35]
	s_mov_b32 m0, s86
	s_nop 0
	global_load_lds_dwordx4 v[174:175], off
	s_waitcnt vmcnt(8)
	s_waitcnt lgkmcnt(0)
	s_barrier
	v_mfma_f32_16x16x32_bf16 v[78:81], v[58:61], v[200:203], v[78:81]
	v_mfma_f32_16x16x32_bf16 v[74:77], v[66:69], v[200:203], v[74:77]
	v_mfma_f32_16x16x32_bf16 v[46:49], v[58:61], v[208:211], v[46:49]
	v_mfma_f32_16x16x32_bf16 v[42:45], v[66:69], v[208:211], v[42:45]
	v_mfma_f32_16x16x32_bf16 v[28:31], v[58:61], v[216:219], v[28:31]
	v_mfma_f32_16x16x32_bf16 v[24:27], v[66:69], v[216:219], v[24:27]
	v_mfma_f32_16x16x32_bf16 v[12:15], v[58:61], v[224:227], v[12:15]
	v_mfma_f32_16x16x32_bf16 v[8:11], v[66:69], v[224:227], v[8:11]
	v_mfma_f32_16x16x32_bf16 v[78:81], v[62:65], v[204:207], v[78:81]
	v_mfma_f32_16x16x32_bf16 v[74:77], v[70:73], v[204:207], v[74:77]
	v_mfma_f32_16x16x32_bf16 v[46:49], v[62:65], v[212:215], v[46:49]
	v_mfma_f32_16x16x32_bf16 v[42:45], v[70:73], v[212:215], v[42:45]
	v_mfma_f32_16x16x32_bf16 v[28:31], v[62:65], v[220:223], v[28:31]
	v_mfma_f32_16x16x32_bf16 v[24:27], v[70:73], v[220:223], v[24:27]
	v_mfma_f32_16x16x32_bf16 v[12:15], v[62:65], v[228:231], v[12:15]
	v_mfma_f32_16x16x32_bf16 v[8:11], v[70:73], v[228:231], v[8:11]
	v_mfma_f32_16x16x32_bf16 v[50:53], v[158:161], v[200:203], v[50:53]
	v_mfma_f32_16x16x32_bf16 v[62:65], v[170:173], v[204:207], v[50:53]
	v_mfma_f32_16x16x32_bf16 v[50:53], v[180:183], v[200:203], v[54:57]
	v_mfma_f32_16x16x32_bf16 v[38:41], v[158:161], v[208:211], v[38:41]
	v_mfma_f32_16x16x32_bf16 v[34:37], v[180:183], v[208:211], v[34:37]
	v_mfma_f32_16x16x32_bf16 v[20:23], v[158:161], v[216:219], v[20:23]
	v_mfma_f32_16x16x32_bf16 v[16:19], v[180:183], v[216:219], v[16:19]
	v_mfma_f32_16x16x32_bf16 v[4:7], v[158:161], v[224:227], v[4:7]
	v_mfma_f32_16x16x32_bf16 v[0:3], v[180:183], v[224:227], v[0:3]
	v_mfma_f32_16x16x32_bf16 v[58:61], v[196:199], v[204:207], v[50:53]
	v_mfma_f32_16x16x32_bf16 v[38:41], v[170:173], v[212:215], v[38:41]
	v_mfma_f32_16x16x32_bf16 v[34:37], v[196:199], v[212:215], v[34:37]
	v_mfma_f32_16x16x32_bf16 v[20:23], v[170:173], v[220:223], v[20:23]
	v_mfma_f32_16x16x32_bf16 v[16:19], v[196:199], v[220:223], v[16:19]
	v_mfma_f32_16x16x32_bf16 v[4:7], v[170:173], v[228:231], v[4:7]
	v_mfma_f32_16x16x32_bf16 v[0:3], v[196:199], v[228:231], v[0:3]
	s_barrier
	s_add_i32 s80, s80, 2
	s_add_u32 vcc_hi, vcc_hi, 0x100
	s_addc_u32 s7, s7, 0
	s_add_u32 s46, s46, 0x100
	s_addc_u32 s47, s47, 0
	s_cmp_gt_u32 s80, 13
	s_cbranch_scc0 .LBB0_145
	v_readlane_b32 s46, v254, 51
	v_readlane_b32 s47, v254, 52
	s_and_b64 vcc, exec, s[46:47]
	s_cbranch_vccz .LBB0_148
	s_barrier

; #define PG8_STAGE(bufoff, gbase, voff) do { _Pragma("unroll") for (int _i = 0; _i < 2; ++_i) \
;         __builtin_amdgcn_global_load_lds((const unsigned*)((const char*)(gbase) + (voff)[_i]), (PG8_LAS unsigned*)(lds + (bufoff) + ldsw + _i * 8192), 16, 0, 0); } while (0)
; #define PG8_LDA(dst, b, h) do { _Pragma("unroll") for (int m = 0; m < 4; ++m) _Pragma("unroll") for (int k = 0; k < 2; ++k) dst[m][k] = *(const PG8_LAS bf16x8*)(lds + PG8_SA(b, h) + aoff + m * 2048 + k * 1024); } while (0)
; #define PG8_LDB(dst, b, h) do { _Pragma("unroll") for (int n = 0; n < 2; ++n) _Pragma("unroll") for (int k = 0; k < 2; ++k) dst[n][k] = *(const PG8_LAS bf16x8*)(lds + PG8_SB(b, h) + boff + n * 2048 + k * 1024); } while (0)
; #define PG8_MMA(ai, bj, At, Bt) do { __builtin_amdgcn_s_setprio(1); _Pragma("unroll") for (int m = 0; m < 4; ++m) _Pragma("unroll") for (int n = 0; n < 2; ++n) _Pragma("unroll") for (int k = 0; k < 2; ++k) \
;         acc[ai][bj][m][n] = __builtin_amdgcn_mfma_f32_16x16x32_bf16(Bt[n][k], At[m][k], acc[ai][bj][m][n], 0, 0, 0); __builtin_amdgcn_s_setprio(0); } while (0)
; #define PG8_WAIT_V(n) asm volatile("s_waitcnt vmcnt(" #n ")" ::: "memory")
; #define PG8_WAIT_L(n) asm volatile("s_waitcnt lgkmcnt(" #n ")" ::: "memory")
; template <class Epi, class Sched, bool ALIGN_EPI = false, bool SP2 = false>
; __device__ __forceinline__ void gemm_phase(PG8_LAS unsigned char* lds, const Gemm g, const Sched& S, const Epi& E) {
;     ...
;             const bool last = (t == nt - 2);
;             const char* a1 = cA + (size_t)(t + 1) * kstep;
;             const char* a2 = last ? nA : cA + (size_t)(t + 2) * kstep; const char* b2 = last ? nB : cB + (size_t)(t + 2) * kstep;
;             const char* a3 = a2 + kstep; const char* b3 = b2 + kstep;
;             if (last && has_next) S.a_ready(nxt);
;             if constexpr (SP2) {
;             PG8_LDB(B0, 0, 0); PG8_LDB(B1, 0, 1); PG8_SCHED; PG8_LDA(At, 0, 0); PG8_STAGE(PG8_SA(1, 1), a1 + hstep, voffA);
;             PG8_WAIT_V(8); PG8_WAIT_L(0); PG8_BAR; PG8_MMA(0, 0, At, B0); PG8_MMA(0, 1, At, B1); PG8_BAR; PG8_SCHED;
;             PG8_LDA(At, 0, 1); PG8_STAGE(PG8_SB(0, 0), b2, voffB); PG8_STAGE(PG8_SB(0, 1), b2 + hstep, voffB); PG8_STAGE(PG8_SA(0, 0), a2, voffA);
;             PG8_WAIT_V(8); PG8_WAIT_L(0); PG8_BAR; PG8_MMA(1, 0, At, B0); PG8_MMA(1, 1, At, B1); PG8_BAR; PG8_SCHED;
.LBB0_369:
	s_add_i32 s92, s46, 2
	s_add_u32 s61, s44, 0x80
	s_addc_u32 s47, s45, 0
	s_add_i32 s72, 0, 0x10000
	s_cmp_eq_u32 s87, s46
	s_cselect_b32 s47, s43, s47
	s_cselect_b32 s46, s42, s61
	v_add_u32_e32 v149, s72, v146
	s_cselect_b32 s95, s77, s91
	s_cselect_b32 s94, s76, s90
	s_add_i32 s61, 0, 0x14000
	ds_read_b128 v[142:145], v149
	ds_read_b128 v[150:153], v149 offset:1024
	ds_read_b128 v[154:157], v149 offset:2048
	ds_read_b128 v[158:161], v149 offset:3072
	v_add_u32_e32 v149, s61, v146
	ds_read_b128 v[170:173], v149
	ds_read_b128 v[174:177], v149 offset:1024
	ds_read_b128 v[178:181], v149 offset:2048
	ds_read_b128 v[182:185], v149 offset:3072
	v_lshl_add_u64 v[228:229], s[44:45], 0, v[140:141]
	s_add_i32 m0, s51, 0xc000
	ds_read_b128 v[196:199], v148
	ds_read_b128 v[200:203], v148 offset:1024
	ds_read_b128 v[204:207], v148 offset:2048
	ds_read_b128 v[208:211], v148 offset:3072
	ds_read_b128 v[212:215], v148 offset:4096
	ds_read_b128 v[216:219], v148 offset:5120
	ds_read_b128 v[220:223], v148 offset:6144
	ds_read_b128 v[224:227], v148 offset:7168
	global_load_lds_dwordx4 v[228:229], off
	v_lshl_add_u64 v[228:229], s[44:45], 0, v[138:139]
	s_add_i32 m0, s51, 0xe000
	s_nop 0
	global_load_lds_dwordx4 v[228:229], off
	s_waitcnt vmcnt(8)
	s_waitcnt lgkmcnt(0)
	s_barrier
	v_mfma_f32_16x16x32_bf16 v[126:129], v[142:145], v[196:199], v[126:129]
	v_mfma_f32_16x16x32_bf16 v[122:125], v[154:157], v[196:199], v[122:125]
	v_mfma_f32_16x16x32_bf16 v[110:113], v[142:145], v[204:207], v[110:113]
	v_mfma_f32_16x16x32_bf16 v[106:109], v[154:157], v[204:207], v[106:109]
	v_mfma_f32_16x16x32_bf16 v[94:97], v[142:145], v[212:215], v[94:97]
	v_mfma_f32_16x16x32_bf16 v[90:93], v[154:157], v[212:215], v[90:93]
	v_mfma_f32_16x16x32_bf16 v[78:81], v[142:145], v[220:223], v[78:81]
	v_mfma_f32_16x16x32_bf16 v[74:77], v[154:157], v[220:223], v[74:77]
	v_mfma_f32_16x16x32_bf16 v[126:129], v[150:153], v[200:203], v[126:129]
	v_mfma_f32_16x16x32_bf16 v[122:125], v[158:161], v[200:203], v[122:125]
	v_mfma_f32_16x16x32_bf16 v[110:113], v[150:153], v[208:211], v[110:113]
	v_mfma_f32_16x16x32_bf16 v[106:109], v[158:161], v[208:211], v[106:109]
	v_mfma_f32_16x16x32_bf16 v[94:97], v[150:153], v[216:219], v[94:97]
	v_mfma_f32_16x16x32_bf16 v[90:93], v[158:161], v[216:219], v[90:93]
	v_mfma_f32_16x16x32_bf16 v[78:81], v[150:153], v[224:227], v[78:81]
	v_mfma_f32_16x16x32_bf16 v[74:77], v[158:161], v[224:227], v[74:77]
	v_mfma_f32_16x16x32_bf16 v[118:121], v[170:173], v[196:199], v[118:121]
	v_mfma_f32_16x16x32_bf16 v[114:117], v[178:181], v[196:199], v[114:117]
	v_mfma_f32_16x16x32_bf16 v[102:105], v[170:173], v[204:207], v[102:105]
	v_mfma_f32_16x16x32_bf16 v[98:101], v[178:181], v[204:207], v[98:101]
	v_mfma_f32_16x16x32_bf16 v[86:89], v[170:173], v[212:215], v[86:89]
	v_mfma_f32_16x16x32_bf16 v[82:85], v[178:181], v[212:215], v[82:85]
	v_mfma_f32_16x16x32_bf16 v[70:73], v[170:173], v[220:223], v[70:73]
	v_mfma_f32_16x16x32_bf16 v[66:69], v[178:181], v[220:223], v[66:69]
	v_mfma_f32_16x16x32_bf16 v[118:121], v[174:177], v[200:203], v[118:121]
	v_mfma_f32_16x16x32_bf16 v[114:117], v[182:185], v[200:203], v[114:117]
	v_mfma_f32_16x16x32_bf16 v[102:105], v[174:177], v[208:211], v[102:105]
	v_mfma_f32_16x16x32_bf16 v[98:101], v[182:185], v[208:211], v[98:101]
	v_mfma_f32_16x16x32_bf16 v[86:89], v[174:177], v[216:219], v[86:89]
	v_mfma_f32_16x16x32_bf16 v[82:85], v[182:185], v[216:219], v[82:85]
	v_mfma_f32_16x16x32_bf16 v[70:73], v[174:177], v[224:227], v[70:73]
	v_mfma_f32_16x16x32_bf16 v[66:69], v[182:185], v[224:227], v[66:69]
	s_barrier
	s_add_i32 s72, s72, s50
	v_lshl_add_u64 v[228:229], s[94:95], 0, v[132:133]
	s_mov_b32 m0, s72
	ds_read_b128 v[196:199], v148 offset:16384
	ds_read_b128 v[200:203], v148 offset:17408
	ds_read_b128 v[204:207], v148 offset:18432
	ds_read_b128 v[208:211], v148 offset:19456
	ds_read_b128 v[212:215], v148 offset:20480
	ds_read_b128 v[216:219], v148 offset:21504
	ds_read_b128 v[220:223], v148 offset:22528
	ds_read_b128 v[224:227], v148 offset:23552
	global_load_lds_dwordx4 v[228:229], off
	s_add_i32 m0, s72, 0x2000
	v_lshl_add_u64 v[230:231], s[94:95], 0, v[136:137]
	s_add_u32 s94, s94, s8
	s_addc_u32 s95, s95, 0
	s_add_i32 s61, s61, s50
	global_load_lds_dwordx4 v[230:231], off
	v_lshl_add_u64 v[232:233], s[94:95], 0, v[132:133]
	s_mov_b32 m0, s61
	v_lshl_add_u64 v[234:235], s[94:95], 0, v[136:137]
	global_load_lds_dwordx4 v[232:233], off
	s_add_i32 m0, s61, 0x2000
	v_lshl_add_u64 v[236:237], s[46:47], 0, v[130:131]
	global_load_lds_dwordx4 v[234:235], off
	s_mov_b32 m0, s51
	v_lshl_add_u64 v[238:239], s[46:47], 0, v[134:135]
	global_load_lds_dwordx4 v[236:237], off
	s_mov_b32 m0, s78
	s_nop 0
	global_load_lds_dwordx4 v[238:239], off
	s_waitcnt vmcnt(8)
	s_waitcnt lgkmcnt(0)
	s_barrier
; #define PG8_STAGE(bufoff, gbase, voff) do { _Pragma("unroll") for (int _i = 0; _i < 2; ++_i) \
;         __builtin_amdgcn_global_load_lds((const unsigned*)((const char*)(gbase) + (voff)[_i]), (PG8_LAS unsigned*)(lds + (bufoff) + ldsw + _i * 8192), 16, 0, 0); } while (0)
; #define PG8_LDA(dst, b, h) do { _Pragma("unroll") for (int m = 0; m < 4; ++m) _Pragma("unroll") for (int k = 0; k < 2; ++k) dst[m][k] = *(const PG8_LAS bf16x8*)(lds + PG8_SA(b, h) + aoff + m * 2048 + k * 1024); } while (0)
; #define PG8_LDB(dst, b, h) do { _Pragma("unroll") for (int n = 0; n < 2; ++n) _Pragma("unroll") for (int k = 0; k < 2; ++k) dst[n][k] = *(const PG8_LAS bf16x8*)(lds + PG8_SB(b, h) + boff + n * 2048 + k * 1024); } while (0)
; #define PG8_MMA(ai, bj, At, Bt) do { __builtin_amdgcn_s_setprio(1); _Pragma("unroll") for (int m = 0; m < 4; ++m) _Pragma("unroll") for (int n = 0; n < 2; ++n) _Pragma("unroll") for (int k = 0; k < 2; ++k) \
;         acc[ai][bj][m][n] = __builtin_amdgcn_mfma_f32_16x16x32_bf16(Bt[n][k], At[m][k], acc[ai][bj][m][n], 0, 0, 0); __builtin_amdgcn_s_setprio(0); } while (0)
; #define PG8_WAIT_V(n) asm volatile("s_waitcnt vmcnt(" #n ")" ::: "memory")
; #define PG8_WAIT_L(n) asm volatile("s_waitcnt lgkmcnt(" #n ")" ::: "memory")
; #define PG8_BAR __builtin_amdgcn_s_barrier()
; #define PG8_SCHED __builtin_amdgcn_sched_barrier(0)
; template <class Epi, class Sched, bool ALIGN_EPI = false, bool SP2 = false>
; __device__ __forceinline__ void gemm_phase(PG8_LAS unsigned char* lds, const Gemm g, const Sched& S, const Epi& E) {
;     ...
;             PG8_WAIT_V(8); PG8_WAIT_L(0); PG8_BAR; PG8_MMA(1, 0, At, B0); PG8_MMA(1, 1, At, B1); PG8_BAR; PG8_SCHED;
;             PG8_LDB(B0, 1, 0); PG8_LDB(B1, 1, 1); PG8_SCHED; PG8_LDA(At, 1, 0); PG8_STAGE(PG8_SA(0, 1), a2 + hstep, voffA);
;             PG8_WAIT_V(8); PG8_WAIT_L(0); PG8_BAR; PG8_MMA(0, 0, At, B0); PG8_MMA(0, 1, At, B1); PG8_BAR; PG8_SCHED;
	v_mfma_f32_16x16x32_bf16 v[62:65], v[142:145], v[196:199], v[62:65]
	v_mfma_f32_16x16x32_bf16 v[58:61], v[154:157], v[196:199], v[58:61]
	v_mfma_f32_16x16x32_bf16 v[46:49], v[142:145], v[204:207], v[46:49]
	v_mfma_f32_16x16x32_bf16 v[42:45], v[154:157], v[204:207], v[42:45]
	v_mfma_f32_16x16x32_bf16 v[28:31], v[142:145], v[212:215], v[28:31]
	v_mfma_f32_16x16x32_bf16 v[24:27], v[154:157], v[212:215], v[24:27]
	v_mfma_f32_16x16x32_bf16 v[12:15], v[142:145], v[220:223], v[12:15]
	v_mfma_f32_16x16x32_bf16 v[8:11], v[154:157], v[220:223], v[8:11]
	v_mfma_f32_16x16x32_bf16 v[62:65], v[150:153], v[200:203], v[62:65]
	v_mfma_f32_16x16x32_bf16 v[58:61], v[158:161], v[200:203], v[58:61]
	v_mfma_f32_16x16x32_bf16 v[46:49], v[150:153], v[208:211], v[46:49]
	v_mfma_f32_16x16x32_bf16 v[42:45], v[158:161], v[208:211], v[42:45]
	v_mfma_f32_16x16x32_bf16 v[28:31], v[150:153], v[216:219], v[28:31]
	v_mfma_f32_16x16x32_bf16 v[24:27], v[158:161], v[216:219], v[24:27]
	v_mfma_f32_16x16x32_bf16 v[12:15], v[150:153], v[224:227], v[12:15]
	v_mfma_f32_16x16x32_bf16 v[8:11], v[158:161], v[224:227], v[8:11]
	v_mfma_f32_16x16x32_bf16 v[54:57], v[170:173], v[196:199], v[54:57]
	v_mfma_f32_16x16x32_bf16 v[50:53], v[178:181], v[196:199], v[50:53]
	v_mfma_f32_16x16x32_bf16 v[38:41], v[170:173], v[204:207], v[38:41]
	v_mfma_f32_16x16x32_bf16 v[34:37], v[178:181], v[204:207], v[34:37]
	v_mfma_f32_16x16x32_bf16 v[20:23], v[170:173], v[212:215], v[20:23]
	v_mfma_f32_16x16x32_bf16 v[16:19], v[178:181], v[212:215], v[16:19]
	v_mfma_f32_16x16x32_bf16 v[4:7], v[170:173], v[220:223], v[4:7]
	v_mfma_f32_16x16x32_bf16 v[0:3], v[178:181], v[220:223], v[0:3]
	v_mfma_f32_16x16x32_bf16 v[54:57], v[174:177], v[200:203], v[54:57]
	v_mfma_f32_16x16x32_bf16 v[50:53], v[182:185], v[200:203], v[50:53]
	v_mfma_f32_16x16x32_bf16 v[38:41], v[174:177], v[208:211], v[38:41]
	v_mfma_f32_16x16x32_bf16 v[34:37], v[182:185], v[208:211], v[34:37]
	v_mfma_f32_16x16x32_bf16 v[20:23], v[174:177], v[216:219], v[20:23]
	v_mfma_f32_16x16x32_bf16 v[16:19], v[182:185], v[216:219], v[16:19]
	v_mfma_f32_16x16x32_bf16 v[4:7], v[174:177], v[224:227], v[4:7]
	v_mfma_f32_16x16x32_bf16 v[0:3], v[182:185], v[224:227], v[0:3]
	s_barrier
	s_add_i32 s61, 0, 0x18000
	v_add_u32_e32 v149, s61, v146
	s_add_i32 s72, 0, 0x1c000
	ds_read_b128 v[142:145], v149
	ds_read_b128 v[150:153], v149 offset:1024
	ds_read_b128 v[154:157], v149 offset:2048
	ds_read_b128 v[158:161], v149 offset:3072
	v_add_u32_e32 v149, s72, v146
	ds_read_b128 v[170:173], v149
	ds_read_b128 v[174:177], v149 offset:1024
	ds_read_b128 v[178:181], v149 offset:2048
	ds_read_b128 v[182:185], v149 offset:3072
	s_add_u32 s46, s46, s8
	s_addc_u32 s47, s47, 0
	s_mov_b32 m0, s79
	v_lshl_add_u64 v[240:241], s[46:47], 0, v[130:131]
	ds_read_b128 v[196:199], v148 offset:32768
	ds_read_b128 v[200:203], v148 offset:33792
	ds_read_b128 v[204:207], v148 offset:34816
	ds_read_b128 v[208:211], v148 offset:35840
	ds_read_b128 v[212:215], v148 offset:36864
	ds_read_b128 v[216:219], v148 offset:37888
	ds_read_b128 v[220:223], v148 offset:38912
	ds_read_b128 v[224:227], v148 offset:39936
	global_load_lds_dwordx4 v[240:241], off
	v_lshl_add_u64 v[240:241], s[46:47], 0, v[134:135]
	s_mov_b32 m0, s80
	s_nop 0
	global_load_lds_dwordx4 v[240:241], off
	s_waitcnt vmcnt(8)
	s_waitcnt lgkmcnt(0)
	s_barrier
	v_mfma_f32_16x16x32_bf16 v[126:129], v[142:145], v[196:199], v[126:129]
	v_mfma_f32_16x16x32_bf16 v[122:125], v[154:157], v[196:199], v[122:125]
	v_mfma_f32_16x16x32_bf16 v[110:113], v[142:145], v[204:207], v[110:113]
	v_mfma_f32_16x16x32_bf16 v[106:109], v[154:157], v[204:207], v[106:109]
	v_mfma_f32_16x16x32_bf16 v[94:97], v[142:145], v[212:215], v[94:97]
	v_mfma_f32_16x16x32_bf16 v[90:93], v[154:157], v[212:215], v[90:93]
	v_mfma_f32_16x16x32_bf16 v[78:81], v[142:145], v[220:223], v[78:81]
	v_mfma_f32_16x16x32_bf16 v[74:77], v[154:157], v[220:223], v[74:77]
	v_mfma_f32_16x16x32_bf16 v[126:129], v[150:153], v[200:203], v[126:129]
	v_mfma_f32_16x16x32_bf16 v[122:125], v[158:161], v[200:203], v[122:125]
	v_mfma_f32_16x16x32_bf16 v[110:113], v[150:153], v[208:211], v[110:113]
	v_mfma_f32_16x16x32_bf16 v[106:109], v[158:161], v[208:211], v[106:109]
	v_mfma_f32_16x16x32_bf16 v[94:97], v[150:153], v[216:219], v[94:97]
	v_mfma_f32_16x16x32_bf16 v[90:93], v[158:161], v[216:219], v[90:93]
	v_mfma_f32_16x16x32_bf16 v[78:81], v[150:153], v[224:227], v[78:81]
	v_mfma_f32_16x16x32_bf16 v[74:77], v[158:161], v[224:227], v[74:77]
	v_mfma_f32_16x16x32_bf16 v[118:121], v[170:173], v[196:199], v[118:121]
	v_mfma_f32_16x16x32_bf16 v[114:117], v[178:181], v[196:199], v[114:117]
	v_mfma_f32_16x16x32_bf16 v[102:105], v[170:173], v[204:207], v[102:105]
	v_mfma_f32_16x16x32_bf16 v[98:101], v[178:181], v[204:207], v[98:101]
	v_mfma_f32_16x16x32_bf16 v[86:89], v[170:173], v[212:215], v[86:89]
	v_mfma_f32_16x16x32_bf16 v[82:85], v[178:181], v[212:215], v[82:85]
	v_mfma_f32_16x16x32_bf16 v[70:73], v[170:173], v[220:223], v[70:73]
	v_mfma_f32_16x16x32_bf16 v[66:69], v[178:181], v[220:223], v[66:69]
	v_mfma_f32_16x16x32_bf16 v[118:121], v[174:177], v[200:203], v[118:121]
	v_mfma_f32_16x16x32_bf16 v[114:117], v[182:185], v[200:203], v[114:117]
	v_mfma_f32_16x16x32_bf16 v[102:105], v[174:177], v[208:211], v[102:105]
	v_mfma_f32_16x16x32_bf16 v[98:101], v[182:185], v[208:211], v[98:101]
	v_mfma_f32_16x16x32_bf16 v[86:89], v[174:177], v[216:219], v[86:89]
	v_mfma_f32_16x16x32_bf16 v[82:85], v[182:185], v[216:219], v[82:85]
	v_mfma_f32_16x16x32_bf16 v[70:73], v[174:177], v[224:227], v[70:73]
	v_mfma_f32_16x16x32_bf16 v[66:69], v[182:185], v[224:227], v[66:69]
	s_barrier
; #define PG8_STAGE(bufoff, gbase, voff) do { _Pragma("unroll") for (int _i = 0; _i < 2; ++_i) \
;         __builtin_amdgcn_global_load_lds((const unsigned*)((const char*)(gbase) + (voff)[_i]), (PG8_LAS unsigned*)(lds + (bufoff) + ldsw + _i * 8192), 16, 0, 0); } while (0)
; #define PG8_LDA(dst, b, h) do { _Pragma("unroll") for (int m = 0; m < 4; ++m) _Pragma("unroll") for (int k = 0; k < 2; ++k) dst[m][k] = *(const PG8_LAS bf16x8*)(lds + PG8_SA(b, h) + aoff + m * 2048 + k * 1024); } while (0)
; #define PG8_MMA(ai, bj, At, Bt) do { __builtin_amdgcn_s_setprio(1); _Pragma("unroll") for (int m = 0; m < 4; ++m) _Pragma("unroll") for (int n = 0; n < 2; ++n) _Pragma("unroll") for (int k = 0; k < 2; ++k) \
;         acc[ai][bj][m][n] = __builtin_amdgcn_mfma_f32_16x16x32_bf16(Bt[n][k], At[m][k], acc[ai][bj][m][n], 0, 0, 0); __builtin_amdgcn_s_setprio(0); } while (0)
; #define PG8_WAIT_V(n) asm volatile("s_waitcnt vmcnt(" #n ")" ::: "memory")
; #define PG8_WAIT_L(n) asm volatile("s_waitcnt lgkmcnt(" #n ")" ::: "memory")
; #define PG8_BAR __builtin_amdgcn_s_barrier()
; #define PG8_SCHED __builtin_amdgcn_sched_barrier(0)
; template <class Epi, class Sched, bool ALIGN_EPI = false, bool SP2 = false>
; __device__ __forceinline__ void gemm_phase(PG8_LAS unsigned char* lds, const Gemm g, const Sched& S, const Epi& E) {
;     ...
;             PG8_LDA(At, 1, 1); PG8_STAGE(PG8_SB(1, 0), b3, voffB); PG8_STAGE(PG8_SB(1, 1), b3 + hstep, voffB); PG8_STAGE(PG8_SA(1, 0), a3, voffA);
;             PG8_WAIT_V(8); PG8_WAIT_L(0); PG8_BAR; PG8_MMA(1, 0, At, B0); PG8_MMA(1, 1, At, B1); PG8_BAR; PG8_SCHED;
;     ...
;         if constexpr (ALIGN_EPI) { if (wr == 0) PG8_BAR; }
	s_add_i32 s46, s61, s50
	v_lshl_add_u64 v[228:229], v[228:229], 0, s[34:35]
	s_mov_b32 m0, s46
	ds_read_b128 v[196:199], v148 offset:49152
	ds_read_b128 v[200:203], v148 offset:50176
	ds_read_b128 v[204:207], v148 offset:51200
	ds_read_b128 v[208:211], v148 offset:52224
	ds_read_b128 v[212:215], v148 offset:53248
	ds_read_b128 v[216:219], v148 offset:54272
	ds_read_b128 v[220:223], v148 offset:55296
	ds_read_b128 v[224:227], v148 offset:56320
	global_load_lds_dwordx4 v[228:229], off
	v_lshl_add_u64 v[228:229], v[230:231], 0, s[34:35]
	s_add_i32 m0, s46, 0x2000
	s_add_i32 s46, s72, s50
	global_load_lds_dwordx4 v[228:229], off
	v_lshl_add_u64 v[228:229], v[232:233], 0, s[34:35]
	s_mov_b32 m0, s46
	s_nop 0
	global_load_lds_dwordx4 v[228:229], off
	v_lshl_add_u64 v[228:229], v[234:235], 0, s[34:35]
	s_add_i32 m0, s46, 0x2000
	s_nop 0
	global_load_lds_dwordx4 v[228:229], off
	v_lshl_add_u64 v[228:229], v[236:237], 0, s[34:35]
	s_mov_b32 m0, s85
	s_nop 0
	global_load_lds_dwordx4 v[228:229], off
	v_lshl_add_u64 v[228:229], v[238:239], 0, s[34:35]
	s_mov_b32 m0, s86
	s_nop 0
	global_load_lds_dwordx4 v[228:229], off
	s_waitcnt vmcnt(8)
	s_waitcnt lgkmcnt(0)
	s_barrier
	v_mfma_f32_16x16x32_bf16 v[62:65], v[142:145], v[196:199], v[62:65]
	v_mfma_f32_16x16x32_bf16 v[58:61], v[154:157], v[196:199], v[58:61]
	v_mfma_f32_16x16x32_bf16 v[46:49], v[142:145], v[204:207], v[46:49]
	v_mfma_f32_16x16x32_bf16 v[42:45], v[154:157], v[204:207], v[42:45]
	v_mfma_f32_16x16x32_bf16 v[28:31], v[142:145], v[212:215], v[28:31]
	v_mfma_f32_16x16x32_bf16 v[24:27], v[154:157], v[212:215], v[24:27]
	v_mfma_f32_16x16x32_bf16 v[12:15], v[142:145], v[220:223], v[12:15]
	v_mfma_f32_16x16x32_bf16 v[8:11], v[154:157], v[220:223], v[8:11]
	v_mfma_f32_16x16x32_bf16 v[62:65], v[150:153], v[200:203], v[62:65]
	v_mfma_f32_16x16x32_bf16 v[58:61], v[158:161], v[200:203], v[58:61]
	v_mfma_f32_16x16x32_bf16 v[46:49], v[150:153], v[208:211], v[46:49]
	v_mfma_f32_16x16x32_bf16 v[42:45], v[158:161], v[208:211], v[42:45]
	v_mfma_f32_16x16x32_bf16 v[28:31], v[150:153], v[216:219], v[28:31]
	v_mfma_f32_16x16x32_bf16 v[24:27], v[158:161], v[216:219], v[24:27]
	v_mfma_f32_16x16x32_bf16 v[12:15], v[150:153], v[224:227], v[12:15]
	v_mfma_f32_16x16x32_bf16 v[8:11], v[158:161], v[224:227], v[8:11]
	v_mfma_f32_16x16x32_bf16 v[54:57], v[170:173], v[196:199], v[54:57]
	v_mfma_f32_16x16x32_bf16 v[50:53], v[178:181], v[196:199], v[50:53]
	v_mfma_f32_16x16x32_bf16 v[38:41], v[170:173], v[204:207], v[38:41]
	v_mfma_f32_16x16x32_bf16 v[34:37], v[178:181], v[204:207], v[34:37]
	v_mfma_f32_16x16x32_bf16 v[20:23], v[170:173], v[212:215], v[20:23]
	v_mfma_f32_16x16x32_bf16 v[16:19], v[178:181], v[212:215], v[16:19]
	v_mfma_f32_16x16x32_bf16 v[4:7], v[170:173], v[220:223], v[4:7]
	v_mfma_f32_16x16x32_bf16 v[0:3], v[178:181], v[220:223], v[0:3]
	v_mfma_f32_16x16x32_bf16 v[54:57], v[174:177], v[200:203], v[54:57]
	v_mfma_f32_16x16x32_bf16 v[50:53], v[182:185], v[200:203], v[50:53]
	v_mfma_f32_16x16x32_bf16 v[38:41], v[174:177], v[208:211], v[38:41]
	v_mfma_f32_16x16x32_bf16 v[34:37], v[182:185], v[208:211], v[34:37]
	v_mfma_f32_16x16x32_bf16 v[20:23], v[174:177], v[216:219], v[20:23]
	v_mfma_f32_16x16x32_bf16 v[16:19], v[182:185], v[216:219], v[16:19]
	v_mfma_f32_16x16x32_bf16 v[4:7], v[174:177], v[224:227], v[4:7]
	v_mfma_f32_16x16x32_bf16 v[0:3], v[182:185], v[224:227], v[0:3]
	s_barrier
	s_add_u32 s90, s90, 0x100
	s_addc_u32 s91, s91, 0
	s_add_u32 s44, s44, 0x100
	s_addc_u32 s45, s45, 0
	s_cmp_ge_u32 s92, s82
	s_mov_b32 s46, s92
	s_cbranch_scc0 .LBB0_369
	s_and_b64 vcc, exec, s[40:41]
	s_cbranch_vccz .LBB0_372
	s_barrier

; #define PG8_STAGE(bufoff, gbase, voff) do { _Pragma("unroll") for (int _i = 0; _i < 2; ++_i) \
;         __builtin_amdgcn_global_load_lds((const unsigned*)((const char*)(gbase) + (voff)[_i]), (PG8_LAS unsigned*)(lds + (bufoff) + ldsw + _i * 8192), 16, 0, 0); } while (0)
; #define PG8_LDA(dst, b, h) do { _Pragma("unroll") for (int m = 0; m < 4; ++m) _Pragma("unroll") for (int k = 0; k < 2; ++k) dst[m][k] = *(const PG8_LAS bf16x8*)(lds + PG8_SA(b, h) + aoff + m * 2048 + k * 1024); } while (0)
; #define PG8_LDB(dst, b, h) do { _Pragma("unroll") for (int n = 0; n < 2; ++n) _Pragma("unroll") for (int k = 0; k < 2; ++k) dst[n][k] = *(const PG8_LAS bf16x8*)(lds + PG8_SB(b, h) + boff + n * 2048 + k * 1024); } while (0)
; #define PG8_MMA(ai, bj, At, Bt) do { __builtin_amdgcn_s_setprio(1); _Pragma("unroll") for (int m = 0; m < 4; ++m) _Pragma("unroll") for (int n = 0; n < 2; ++n) _Pragma("unroll") for (int k = 0; k < 2; ++k) \
;         acc[ai][bj][m][n] = __builtin_amdgcn_mfma_f32_16x16x32_bf16(Bt[n][k], At[m][k], acc[ai][bj][m][n], 0, 0, 0); __builtin_amdgcn_s_setprio(0); } while (0)
; #define PG8_WAIT_V(n) asm volatile("s_waitcnt vmcnt(" #n ")" ::: "memory")
; #define PG8_WAIT_L(n) asm volatile("s_waitcnt lgkmcnt(" #n ")" ::: "memory")
; template <class Epi, class Sched, bool ALIGN_EPI = false, bool SP2 = false>
; __device__ __forceinline__ void gemm_phase(PG8_LAS unsigned char* lds, const Gemm g, const Sched& S, const Epi& E) {
;     ...
;             const bool last = (t == nt - 2);
;             const char* a1 = cA + (size_t)(t + 1) * kstep;
;             const char* a2 = last ? nA : cA + (size_t)(t + 2) * kstep; const char* b2 = last ? nB : cB + (size_t)(t + 2) * kstep;
;             const char* a3 = a2 + kstep; const char* b3 = b2 + kstep;
;             if (last && has_next) S.a_ready(nxt);
;             if constexpr (SP2) {
;             PG8_LDB(B0, 0, 0); PG8_LDB(B1, 0, 1); PG8_SCHED; PG8_LDA(At, 0, 0); PG8_STAGE(PG8_SA(1, 1), a1 + hstep, voffA);
;             PG8_WAIT_V(8); PG8_WAIT_L(0); PG8_BAR; PG8_MMA(0, 0, At, B0); PG8_MMA(0, 1, At, B1); PG8_BAR; PG8_SCHED;
;             PG8_LDA(At, 0, 1); PG8_STAGE(PG8_SB(0, 0), b2, voffB); PG8_STAGE(PG8_SB(0, 1), b2 + hstep, voffB); PG8_STAGE(PG8_SA(0, 0), a2, voffA);
;             PG8_WAIT_V(8); PG8_WAIT_L(0); PG8_BAR; PG8_MMA(1, 0, At, B0); PG8_MMA(1, 1, At, B1); PG8_BAR; PG8_SCHED;
.LBB0_411:
	s_add_i32 vcc_lo, s46, 2
	s_add_u32 s38, s44, 0x80
	s_addc_u32 s39, s45, 0
	s_add_i32 vcc_hi, 0, 0x10000
	s_cmp_eq_u32 s92, s46
	s_cselect_b32 s47, s79, s39
	s_cselect_b32 s46, s78, s38
	v_add_u32_e32 v149, vcc_hi, v146
	s_cselect_b32 s39, s81, s49
	s_cselect_b32 s38, s80, s48
	s_add_i32 s61, 0, 0x14000
	ds_read_b128 v[142:145], v149
	ds_read_b128 v[150:153], v149 offset:1024
	ds_read_b128 v[154:157], v149 offset:2048
	ds_read_b128 v[158:161], v149 offset:3072
	v_add_u32_e32 v149, s61, v146
	ds_read_b128 v[170:173], v149
	ds_read_b128 v[174:177], v149 offset:1024
	ds_read_b128 v[178:181], v149 offset:2048
	ds_read_b128 v[182:185], v149 offset:3072
	v_lshl_add_u64 v[228:229], s[44:45], 0, v[140:141]
	s_add_i32 m0, s82, 0xc000
	ds_read_b128 v[196:199], v148
	ds_read_b128 v[200:203], v148 offset:1024
	ds_read_b128 v[204:207], v148 offset:2048
	ds_read_b128 v[208:211], v148 offset:3072
	ds_read_b128 v[212:215], v148 offset:4096
	ds_read_b128 v[216:219], v148 offset:5120
	ds_read_b128 v[220:223], v148 offset:6144
	ds_read_b128 v[224:227], v148 offset:7168
	global_load_lds_dwordx4 v[228:229], off
	v_lshl_add_u64 v[228:229], s[44:45], 0, v[138:139]
	s_add_i32 m0, s82, 0xe000
	s_nop 0
	global_load_lds_dwordx4 v[228:229], off
	s_waitcnt vmcnt(8)
	s_waitcnt lgkmcnt(0)
	s_barrier
	v_mfma_f32_16x16x32_bf16 v[126:129], v[142:145], v[196:199], v[126:129]
	v_mfma_f32_16x16x32_bf16 v[122:125], v[154:157], v[196:199], v[122:125]
	v_mfma_f32_16x16x32_bf16 v[110:113], v[142:145], v[204:207], v[110:113]
	v_mfma_f32_16x16x32_bf16 v[106:109], v[154:157], v[204:207], v[106:109]
	v_mfma_f32_16x16x32_bf16 v[94:97], v[142:145], v[212:215], v[94:97]
	v_mfma_f32_16x16x32_bf16 v[90:93], v[154:157], v[212:215], v[90:93]
	v_mfma_f32_16x16x32_bf16 v[78:81], v[142:145], v[220:223], v[78:81]
	v_mfma_f32_16x16x32_bf16 v[74:77], v[154:157], v[220:223], v[74:77]
	v_mfma_f32_16x16x32_bf16 v[126:129], v[150:153], v[200:203], v[126:129]
	v_mfma_f32_16x16x32_bf16 v[122:125], v[158:161], v[200:203], v[122:125]
	v_mfma_f32_16x16x32_bf16 v[110:113], v[150:153], v[208:211], v[110:113]
	v_mfma_f32_16x16x32_bf16 v[106:109], v[158:161], v[208:211], v[106:109]
	v_mfma_f32_16x16x32_bf16 v[94:97], v[150:153], v[216:219], v[94:97]
	v_mfma_f32_16x16x32_bf16 v[90:93], v[158:161], v[216:219], v[90:93]
	v_mfma_f32_16x16x32_bf16 v[78:81], v[150:153], v[224:227], v[78:81]
	v_mfma_f32_16x16x32_bf16 v[74:77], v[158:161], v[224:227], v[74:77]
	v_mfma_f32_16x16x32_bf16 v[118:121], v[170:173], v[196:199], v[118:121]
	v_mfma_f32_16x16x32_bf16 v[114:117], v[178:181], v[196:199], v[114:117]
	v_mfma_f32_16x16x32_bf16 v[102:105], v[170:173], v[204:207], v[102:105]
	v_mfma_f32_16x16x32_bf16 v[98:101], v[178:181], v[204:207], v[98:101]
	v_mfma_f32_16x16x32_bf16 v[86:89], v[170:173], v[212:215], v[86:89]
	v_mfma_f32_16x16x32_bf16 v[82:85], v[178:181], v[212:215], v[82:85]
	v_mfma_f32_16x16x32_bf16 v[70:73], v[170:173], v[220:223], v[70:73]
	v_mfma_f32_16x16x32_bf16 v[66:69], v[178:181], v[220:223], v[66:69]
	v_mfma_f32_16x16x32_bf16 v[118:121], v[174:177], v[200:203], v[118:121]
	v_mfma_f32_16x16x32_bf16 v[114:117], v[182:185], v[200:203], v[114:117]
	v_mfma_f32_16x16x32_bf16 v[102:105], v[174:177], v[208:211], v[102:105]
	v_mfma_f32_16x16x32_bf16 v[98:101], v[182:185], v[208:211], v[98:101]
	v_mfma_f32_16x16x32_bf16 v[86:89], v[174:177], v[216:219], v[86:89]
	v_mfma_f32_16x16x32_bf16 v[82:85], v[182:185], v[216:219], v[82:85]
	v_mfma_f32_16x16x32_bf16 v[70:73], v[174:177], v[224:227], v[70:73]
	v_mfma_f32_16x16x32_bf16 v[66:69], v[182:185], v[224:227], v[66:69]
	s_barrier
	s_add_i32 vcc_hi, vcc_hi, s51
	v_lshl_add_u64 v[228:229], s[38:39], 0, v[132:133]
	s_mov_b32 m0, vcc_hi
	ds_read_b128 v[196:199], v148 offset:16384
	ds_read_b128 v[200:203], v148 offset:17408
	ds_read_b128 v[204:207], v148 offset:18432
	ds_read_b128 v[208:211], v148 offset:19456
	ds_read_b128 v[212:215], v148 offset:20480
	ds_read_b128 v[216:219], v148 offset:21504
	ds_read_b128 v[220:223], v148 offset:22528
	ds_read_b128 v[224:227], v148 offset:23552
	global_load_lds_dwordx4 v[228:229], off
	s_add_i32 m0, vcc_hi, 0x2000
	v_lshl_add_u64 v[230:231], s[38:39], 0, v[136:137]
	s_add_u32 s38, s38, s8
	s_addc_u32 s39, s39, 0
	s_add_i32 s61, s61, s51
	global_load_lds_dwordx4 v[230:231], off
	v_lshl_add_u64 v[232:233], s[38:39], 0, v[132:133]
	s_mov_b32 m0, s61
	v_lshl_add_u64 v[234:235], s[38:39], 0, v[136:137]
	global_load_lds_dwordx4 v[232:233], off
	s_add_i32 m0, s61, 0x2000
	v_lshl_add_u64 v[236:237], s[46:47], 0, v[130:131]
	global_load_lds_dwordx4 v[234:235], off
	s_mov_b32 m0, s82
	v_lshl_add_u64 v[238:239], s[46:47], 0, v[134:135]
	global_load_lds_dwordx4 v[236:237], off
	s_mov_b32 m0, s83
	s_nop 0
	global_load_lds_dwordx4 v[238:239], off
	s_waitcnt vmcnt(8)
	s_waitcnt lgkmcnt(0)
	s_barrier
; #define PG8_STAGE(bufoff, gbase, voff) do { _Pragma("unroll") for (int _i = 0; _i < 2; ++_i) \
;         __builtin_amdgcn_global_load_lds((const unsigned*)((const char*)(gbase) + (voff)[_i]), (PG8_LAS unsigned*)(lds + (bufoff) + ldsw + _i * 8192), 16, 0, 0); } while (0)
; #define PG8_LDA(dst, b, h) do { _Pragma("unroll") for (int m = 0; m < 4; ++m) _Pragma("unroll") for (int k = 0; k < 2; ++k) dst[m][k] = *(const PG8_LAS bf16x8*)(lds + PG8_SA(b, h) + aoff + m * 2048 + k * 1024); } while (0)
; #define PG8_LDB(dst, b, h) do { _Pragma("unroll") for (int n = 0; n < 2; ++n) _Pragma("unroll") for (int k = 0; k < 2; ++k) dst[n][k] = *(const PG8_LAS bf16x8*)(lds + PG8_SB(b, h) + boff + n * 2048 + k * 1024); } while (0)
; #define PG8_MMA(ai, bj, At, Bt) do { __builtin_amdgcn_s_setprio(1); _Pragma("unroll") for (int m = 0; m < 4; ++m) _Pragma("unroll") for (int n = 0; n < 2; ++n) _Pragma("unroll") for (int k = 0; k < 2; ++k) \
;         acc[ai][bj][m][n] = __builtin_amdgcn_mfma_f32_16x16x32_bf16(Bt[n][k], At[m][k], acc[ai][bj][m][n], 0, 0, 0); __builtin_amdgcn_s_setprio(0); } while (0)
; #define PG8_WAIT_V(n) asm volatile("s_waitcnt vmcnt(" #n ")" ::: "memory")
; #define PG8_WAIT_L(n) asm volatile("s_waitcnt lgkmcnt(" #n ")" ::: "memory")
; #define PG8_BAR __builtin_amdgcn_s_barrier()
; #define PG8_SCHED __builtin_amdgcn_sched_barrier(0)
; template <class Epi, class Sched, bool ALIGN_EPI = false, bool SP2 = false>
; __device__ __forceinline__ void gemm_phase(PG8_LAS unsigned char* lds, const Gemm g, const Sched& S, const Epi& E) {
;     ...
;             PG8_WAIT_V(8); PG8_WAIT_L(0); PG8_BAR; PG8_MMA(1, 0, At, B0); PG8_MMA(1, 1, At, B1); PG8_BAR; PG8_SCHED;
;             PG8_LDB(B0, 1, 0); PG8_LDB(B1, 1, 1); PG8_SCHED; PG8_LDA(At, 1, 0); PG8_STAGE(PG8_SA(0, 1), a2 + hstep, voffA);
;             PG8_WAIT_V(8); PG8_WAIT_L(0); PG8_BAR; PG8_MMA(0, 0, At, B0); PG8_MMA(0, 1, At, B1); PG8_BAR; PG8_SCHED;
	v_mfma_f32_16x16x32_bf16 v[62:65], v[142:145], v[196:199], v[62:65]
	v_mfma_f32_16x16x32_bf16 v[58:61], v[154:157], v[196:199], v[58:61]
	v_mfma_f32_16x16x32_bf16 v[46:49], v[142:145], v[204:207], v[46:49]
	v_mfma_f32_16x16x32_bf16 v[42:45], v[154:157], v[204:207], v[42:45]
	v_mfma_f32_16x16x32_bf16 v[28:31], v[142:145], v[212:215], v[28:31]
	v_mfma_f32_16x16x32_bf16 v[24:27], v[154:157], v[212:215], v[24:27]
	v_mfma_f32_16x16x32_bf16 v[12:15], v[142:145], v[220:223], v[12:15]
	v_mfma_f32_16x16x32_bf16 v[8:11], v[154:157], v[220:223], v[8:11]
	v_mfma_f32_16x16x32_bf16 v[62:65], v[150:153], v[200:203], v[62:65]
	v_mfma_f32_16x16x32_bf16 v[58:61], v[158:161], v[200:203], v[58:61]
	v_mfma_f32_16x16x32_bf16 v[46:49], v[150:153], v[208:211], v[46:49]
	v_mfma_f32_16x16x32_bf16 v[42:45], v[158:161], v[208:211], v[42:45]
	v_mfma_f32_16x16x32_bf16 v[28:31], v[150:153], v[216:219], v[28:31]
	v_mfma_f32_16x16x32_bf16 v[24:27], v[158:161], v[216:219], v[24:27]
	v_mfma_f32_16x16x32_bf16 v[12:15], v[150:153], v[224:227], v[12:15]
	v_mfma_f32_16x16x32_bf16 v[8:11], v[158:161], v[224:227], v[8:11]
	v_mfma_f32_16x16x32_bf16 v[54:57], v[170:173], v[196:199], v[54:57]
	v_mfma_f32_16x16x32_bf16 v[50:53], v[178:181], v[196:199], v[50:53]
	v_mfma_f32_16x16x32_bf16 v[38:41], v[170:173], v[204:207], v[38:41]
	v_mfma_f32_16x16x32_bf16 v[34:37], v[178:181], v[204:207], v[34:37]
	v_mfma_f32_16x16x32_bf16 v[20:23], v[170:173], v[212:215], v[20:23]
	v_mfma_f32_16x16x32_bf16 v[16:19], v[178:181], v[212:215], v[16:19]
	v_mfma_f32_16x16x32_bf16 v[4:7], v[170:173], v[220:223], v[4:7]
	v_mfma_f32_16x16x32_bf16 v[0:3], v[178:181], v[220:223], v[0:3]
	v_mfma_f32_16x16x32_bf16 v[54:57], v[174:177], v[200:203], v[54:57]
	v_mfma_f32_16x16x32_bf16 v[50:53], v[182:185], v[200:203], v[50:53]
	v_mfma_f32_16x16x32_bf16 v[38:41], v[174:177], v[208:211], v[38:41]
	v_mfma_f32_16x16x32_bf16 v[34:37], v[182:185], v[208:211], v[34:37]
	v_mfma_f32_16x16x32_bf16 v[20:23], v[174:177], v[216:219], v[20:23]
	v_mfma_f32_16x16x32_bf16 v[16:19], v[182:185], v[216:219], v[16:19]
	v_mfma_f32_16x16x32_bf16 v[4:7], v[174:177], v[224:227], v[4:7]
	v_mfma_f32_16x16x32_bf16 v[0:3], v[182:185], v[224:227], v[0:3]
	s_barrier
	s_add_i32 s61, 0, 0x18000
	v_add_u32_e32 v149, s61, v146
	s_add_i32 vcc_hi, 0, 0x1c000
	ds_read_b128 v[142:145], v149
	ds_read_b128 v[150:153], v149 offset:1024
	ds_read_b128 v[154:157], v149 offset:2048
	ds_read_b128 v[158:161], v149 offset:3072
	v_add_u32_e32 v149, vcc_hi, v146
	ds_read_b128 v[170:173], v149
	ds_read_b128 v[174:177], v149 offset:1024
	ds_read_b128 v[178:181], v149 offset:2048
	ds_read_b128 v[182:185], v149 offset:3072
	s_add_u32 s38, s46, s8
	s_addc_u32 s39, s47, 0
	s_mov_b32 m0, s87
	v_lshl_add_u64 v[240:241], s[38:39], 0, v[130:131]
	ds_read_b128 v[196:199], v148 offset:32768
	ds_read_b128 v[200:203], v148 offset:33792
	ds_read_b128 v[204:207], v148 offset:34816
	ds_read_b128 v[208:211], v148 offset:35840
	ds_read_b128 v[212:215], v148 offset:36864
	ds_read_b128 v[216:219], v148 offset:37888
	ds_read_b128 v[220:223], v148 offset:38912
	ds_read_b128 v[224:227], v148 offset:39936
	global_load_lds_dwordx4 v[240:241], off
	v_lshl_add_u64 v[240:241], s[38:39], 0, v[134:135]
	s_mov_b32 m0, s88
	s_nop 0
	global_load_lds_dwordx4 v[240:241], off
	s_waitcnt vmcnt(8)
	s_waitcnt lgkmcnt(0)
	s_barrier
	v_mfma_f32_16x16x32_bf16 v[126:129], v[142:145], v[196:199], v[126:129]
	v_mfma_f32_16x16x32_bf16 v[122:125], v[154:157], v[196:199], v[122:125]
	v_mfma_f32_16x16x32_bf16 v[110:113], v[142:145], v[204:207], v[110:113]
	v_mfma_f32_16x16x32_bf16 v[106:109], v[154:157], v[204:207], v[106:109]
	v_mfma_f32_16x16x32_bf16 v[94:97], v[142:145], v[212:215], v[94:97]
	v_mfma_f32_16x16x32_bf16 v[90:93], v[154:157], v[212:215], v[90:93]
	v_mfma_f32_16x16x32_bf16 v[78:81], v[142:145], v[220:223], v[78:81]
	v_mfma_f32_16x16x32_bf16 v[74:77], v[154:157], v[220:223], v[74:77]
	v_mfma_f32_16x16x32_bf16 v[126:129], v[150:153], v[200:203], v[126:129]
	v_mfma_f32_16x16x32_bf16 v[122:125], v[158:161], v[200:203], v[122:125]
	v_mfma_f32_16x16x32_bf16 v[110:113], v[150:153], v[208:211], v[110:113]
	v_mfma_f32_16x16x32_bf16 v[106:109], v[158:161], v[208:211], v[106:109]
	v_mfma_f32_16x16x32_bf16 v[94:97], v[150:153], v[216:219], v[94:97]
	v_mfma_f32_16x16x32_bf16 v[90:93], v[158:161], v[216:219], v[90:93]
	v_mfma_f32_16x16x32_bf16 v[78:81], v[150:153], v[224:227], v[78:81]
	v_mfma_f32_16x16x32_bf16 v[74:77], v[158:161], v[224:227], v[74:77]
	v_mfma_f32_16x16x32_bf16 v[118:121], v[170:173], v[196:199], v[118:121]
	v_mfma_f32_16x16x32_bf16 v[114:117], v[178:181], v[196:199], v[114:117]
	v_mfma_f32_16x16x32_bf16 v[102:105], v[170:173], v[204:207], v[102:105]
	v_mfma_f32_16x16x32_bf16 v[98:101], v[178:181], v[204:207], v[98:101]
	v_mfma_f32_16x16x32_bf16 v[86:89], v[170:173], v[212:215], v[86:89]
	v_mfma_f32_16x16x32_bf16 v[82:85], v[178:181], v[212:215], v[82:85]
	v_mfma_f32_16x16x32_bf16 v[70:73], v[170:173], v[220:223], v[70:73]
	v_mfma_f32_16x16x32_bf16 v[66:69], v[178:181], v[220:223], v[66:69]
	v_mfma_f32_16x16x32_bf16 v[118:121], v[174:177], v[200:203], v[118:121]
	v_mfma_f32_16x16x32_bf16 v[114:117], v[182:185], v[200:203], v[114:117]
	v_mfma_f32_16x16x32_bf16 v[102:105], v[174:177], v[208:211], v[102:105]
	v_mfma_f32_16x16x32_bf16 v[98:101], v[182:185], v[208:211], v[98:101]
	v_mfma_f32_16x16x32_bf16 v[86:89], v[174:177], v[216:219], v[86:89]
	v_mfma_f32_16x16x32_bf16 v[82:85], v[182:185], v[216:219], v[82:85]
	v_mfma_f32_16x16x32_bf16 v[70:73], v[174:177], v[224:227], v[70:73]
	v_mfma_f32_16x16x32_bf16 v[66:69], v[182:185], v[224:227], v[66:69]
	s_barrier
; #define PG8_STAGE(bufoff, gbase, voff) do { _Pragma("unroll") for (int _i = 0; _i < 2; ++_i) \
;         __builtin_amdgcn_global_load_lds((const unsigned*)((const char*)(gbase) + (voff)[_i]), (PG8_LAS unsigned*)(lds + (bufoff) + ldsw + _i * 8192), 16, 0, 0); } while (0)
; #define PG8_LDA(dst, b, h) do { _Pragma("unroll") for (int m = 0; m < 4; ++m) _Pragma("unroll") for (int k = 0; k < 2; ++k) dst[m][k] = *(const PG8_LAS bf16x8*)(lds + PG8_SA(b, h) + aoff + m * 2048 + k * 1024); } while (0)
; #define PG8_MMA(ai, bj, At, Bt) do { __builtin_amdgcn_s_setprio(1); _Pragma("unroll") for (int m = 0; m < 4; ++m) _Pragma("unroll") for (int n = 0; n < 2; ++n) _Pragma("unroll") for (int k = 0; k < 2; ++k) \
;         acc[ai][bj][m][n] = __builtin_amdgcn_mfma_f32_16x16x32_bf16(Bt[n][k], At[m][k], acc[ai][bj][m][n], 0, 0, 0); __builtin_amdgcn_s_setprio(0); } while (0)
; #define PG8_WAIT_V(n) asm volatile("s_waitcnt vmcnt(" #n ")" ::: "memory")
; #define PG8_WAIT_L(n) asm volatile("s_waitcnt lgkmcnt(" #n ")" ::: "memory")
; #define PG8_BAR __builtin_amdgcn_s_barrier()
; #define PG8_SCHED __builtin_amdgcn_sched_barrier(0)
; template <class Epi, class Sched, bool ALIGN_EPI = false, bool SP2 = false>
; __device__ __forceinline__ void gemm_phase(PG8_LAS unsigned char* lds, const Gemm g, const Sched& S, const Epi& E) {
;     ...
;             PG8_LDA(At, 1, 1); PG8_STAGE(PG8_SB(1, 0), b3, voffB); PG8_STAGE(PG8_SB(1, 1), b3 + hstep, voffB); PG8_STAGE(PG8_SA(1, 0), a3, voffA);
;             PG8_WAIT_V(8); PG8_WAIT_L(0); PG8_BAR; PG8_MMA(1, 0, At, B0); PG8_MMA(1, 1, At, B1); PG8_BAR; PG8_SCHED;
;     ...
;         if constexpr (ALIGN_EPI) { if (wr == 0) PG8_BAR; }
	s_add_i32 s38, s61, s51
	v_lshl_add_u64 v[228:229], v[228:229], 0, s[34:35]
	s_mov_b32 m0, s38
	ds_read_b128 v[196:199], v148 offset:49152
	ds_read_b128 v[200:203], v148 offset:50176
	ds_read_b128 v[204:207], v148 offset:51200
	ds_read_b128 v[208:211], v148 offset:52224
	ds_read_b128 v[212:215], v148 offset:53248
	ds_read_b128 v[216:219], v148 offset:54272
	ds_read_b128 v[220:223], v148 offset:55296
	ds_read_b128 v[224:227], v148 offset:56320
	global_load_lds_dwordx4 v[228:229], off
	v_lshl_add_u64 v[228:229], v[230:231], 0, s[34:35]
	s_add_i32 m0, s38, 0x2000
	s_add_i32 s38, vcc_hi, s51
	global_load_lds_dwordx4 v[228:229], off
	v_lshl_add_u64 v[228:229], v[232:233], 0, s[34:35]
	s_mov_b32 m0, s38
	s_nop 0
	global_load_lds_dwordx4 v[228:229], off
	v_lshl_add_u64 v[228:229], v[234:235], 0, s[34:35]
	s_add_i32 m0, s38, 0x2000
	s_nop 0
	global_load_lds_dwordx4 v[228:229], off
	v_lshl_add_u64 v[228:229], v[236:237], 0, s[34:35]
	s_mov_b32 m0, s90
	s_nop 0
	global_load_lds_dwordx4 v[228:229], off
	v_lshl_add_u64 v[228:229], v[238:239], 0, s[34:35]
	s_mov_b32 m0, s91
	s_nop 0
	global_load_lds_dwordx4 v[228:229], off
	s_waitcnt vmcnt(8)
	s_waitcnt lgkmcnt(0)
	s_barrier
	v_mfma_f32_16x16x32_bf16 v[62:65], v[142:145], v[196:199], v[62:65]
	v_mfma_f32_16x16x32_bf16 v[58:61], v[154:157], v[196:199], v[58:61]
	v_mfma_f32_16x16x32_bf16 v[46:49], v[142:145], v[204:207], v[46:49]
	v_mfma_f32_16x16x32_bf16 v[42:45], v[154:157], v[204:207], v[42:45]
	v_mfma_f32_16x16x32_bf16 v[28:31], v[142:145], v[212:215], v[28:31]
	v_mfma_f32_16x16x32_bf16 v[24:27], v[154:157], v[212:215], v[24:27]
	v_mfma_f32_16x16x32_bf16 v[12:15], v[142:145], v[220:223], v[12:15]
	v_mfma_f32_16x16x32_bf16 v[8:11], v[154:157], v[220:223], v[8:11]
	v_mfma_f32_16x16x32_bf16 v[62:65], v[150:153], v[200:203], v[62:65]
	v_mfma_f32_16x16x32_bf16 v[58:61], v[158:161], v[200:203], v[58:61]
	v_mfma_f32_16x16x32_bf16 v[46:49], v[150:153], v[208:211], v[46:49]
	v_mfma_f32_16x16x32_bf16 v[42:45], v[158:161], v[208:211], v[42:45]
	v_mfma_f32_16x16x32_bf16 v[28:31], v[150:153], v[216:219], v[28:31]
	v_mfma_f32_16x16x32_bf16 v[24:27], v[158:161], v[216:219], v[24:27]
	v_mfma_f32_16x16x32_bf16 v[12:15], v[150:153], v[224:227], v[12:15]
	v_mfma_f32_16x16x32_bf16 v[8:11], v[158:161], v[224:227], v[8:11]
	v_mfma_f32_16x16x32_bf16 v[54:57], v[170:173], v[196:199], v[54:57]
	v_mfma_f32_16x16x32_bf16 v[50:53], v[178:181], v[196:199], v[50:53]
	v_mfma_f32_16x16x32_bf16 v[38:41], v[170:173], v[204:207], v[38:41]
	v_mfma_f32_16x16x32_bf16 v[34:37], v[178:181], v[204:207], v[34:37]
	v_mfma_f32_16x16x32_bf16 v[20:23], v[170:173], v[212:215], v[20:23]
	v_mfma_f32_16x16x32_bf16 v[16:19], v[178:181], v[212:215], v[16:19]
	v_mfma_f32_16x16x32_bf16 v[4:7], v[170:173], v[220:223], v[4:7]
	v_mfma_f32_16x16x32_bf16 v[0:3], v[178:181], v[220:223], v[0:3]
	v_mfma_f32_16x16x32_bf16 v[54:57], v[174:177], v[200:203], v[54:57]
	v_mfma_f32_16x16x32_bf16 v[50:53], v[182:185], v[200:203], v[50:53]
	v_mfma_f32_16x16x32_bf16 v[38:41], v[174:177], v[208:211], v[38:41]
	v_mfma_f32_16x16x32_bf16 v[34:37], v[182:185], v[208:211], v[34:37]
	v_mfma_f32_16x16x32_bf16 v[20:23], v[174:177], v[216:219], v[20:23]
	v_mfma_f32_16x16x32_bf16 v[16:19], v[182:185], v[216:219], v[16:19]
	v_mfma_f32_16x16x32_bf16 v[4:7], v[174:177], v[224:227], v[4:7]
	v_mfma_f32_16x16x32_bf16 v[0:3], v[182:185], v[224:227], v[0:3]
	s_barrier
	s_add_u32 s48, s48, 0x100
	s_addc_u32 s49, s49, 0
	s_add_u32 s44, s44, 0x100
	s_addc_u32 s45, s45, 0
	s_cmp_ge_u32 vcc_lo, s85
	s_mov_b32 s46, vcc_lo
	s_cbranch_scc0 .LBB0_411
	s_and_b64 vcc, exec, s[42:43]
	s_cbranch_vccz .LBB0_414
	s_barrier

; #define PG8_STAGE(bufoff, gbase, voff) do { _Pragma("unroll") for (int _i = 0; _i < 2; ++_i) \
;         __builtin_amdgcn_global_load_lds((const unsigned*)((const char*)(gbase) + (voff)[_i]), (PG8_LAS unsigned*)(lds + (bufoff) + ldsw + _i * 8192), 16, 0, 0); } while (0)
; #define PG8_LDA(dst, b, h) do { _Pragma("unroll") for (int m = 0; m < 4; ++m) _Pragma("unroll") for (int k = 0; k < 2; ++k) dst[m][k] = *(const PG8_LAS bf16x8*)(lds + PG8_SA(b, h) + aoff + m * 2048 + k * 1024); } while (0)
; #define PG8_LDB(dst, b, h) do { _Pragma("unroll") for (int n = 0; n < 2; ++n) _Pragma("unroll") for (int k = 0; k < 2; ++k) dst[n][k] = *(const PG8_LAS bf16x8*)(lds + PG8_SB(b, h) + boff + n * 2048 + k * 1024); } while (0)
; #define PG8_MMA(ai, bj, At, Bt) do { __builtin_amdgcn_s_setprio(1); _Pragma("unroll") for (int m = 0; m < 4; ++m) _Pragma("unroll") for (int n = 0; n < 2; ++n) _Pragma("unroll") for (int k = 0; k < 2; ++k) \
;         acc[ai][bj][m][n] = __builtin_amdgcn_mfma_f32_16x16x32_bf16(Bt[n][k], At[m][k], acc[ai][bj][m][n], 0, 0, 0); __builtin_amdgcn_s_setprio(0); } while (0)
; #define PG8_WAIT_V(n) asm volatile("s_waitcnt vmcnt(" #n ")" ::: "memory")
; #define PG8_WAIT_L(n) asm volatile("s_waitcnt lgkmcnt(" #n ")" ::: "memory")
; template <class Epi, class Sched, bool ALIGN_EPI = false, bool SP2 = false>
; __device__ __forceinline__ void gemm_phase(PG8_LAS unsigned char* lds, const Gemm g, const Sched& S, const Epi& E) {
;     ...
;             const bool last = (t == nt - 2);
;             const char* a1 = cA + (size_t)(t + 1) * kstep;
;             const char* a2 = last ? nA : cA + (size_t)(t + 2) * kstep; const char* b2 = last ? nB : cB + (size_t)(t + 2) * kstep;
;             const char* a3 = a2 + kstep; const char* b3 = b2 + kstep;
;             if (last && has_next) S.a_ready(nxt);
;             if constexpr (SP2) {
;             PG8_LDB(B0, 0, 0); PG8_LDB(B1, 0, 1); PG8_SCHED; PG8_LDA(At, 0, 0); PG8_STAGE(PG8_SA(1, 1), a1 + hstep, voffA);
;             PG8_WAIT_V(8); PG8_WAIT_L(0); PG8_BAR; PG8_MMA(0, 0, At, B0); PG8_MMA(0, 1, At, B1); PG8_BAR; PG8_SCHED;
;             PG8_LDA(At, 0, 1); PG8_STAGE(PG8_SB(0, 0), b2, voffB); PG8_STAGE(PG8_SB(0, 1), b2 + hstep, voffB); PG8_STAGE(PG8_SA(0, 0), a2, voffA);
;             PG8_WAIT_V(8); PG8_WAIT_L(0); PG8_BAR; PG8_MMA(1, 0, At, B0); PG8_MMA(1, 1, At, B1); PG8_BAR; PG8_SCHED;
.LBB0_444:
	s_add_u32 s38, s48, 0xfffc0080
	s_addc_u32 s39, s49, -1
	s_add_i32 s61, 0, 0x10000
	s_cmp_eq_u32 vcc_hi, 12
	s_cselect_b32 s83, s43, s39
	s_cselect_b32 s82, s45, s38
	v_add_u32_e32 v151, s61, v145
	s_cselect_b32 s51, s41, vcc_lo
	s_cselect_b32 s50, s96, s97
	s_add_i32 s72, 0, 0x14000
	ds_read_b128 v[170:173], v151
	ds_read_b128 v[174:177], v151 offset:1024
	ds_read_b128 v[178:181], v151 offset:2048
	ds_read_b128 v[182:185], v151 offset:3072
	v_add_u32_e32 v151, s72, v145
	ds_read_b128 v[196:199], v151
	ds_read_b128 v[200:203], v151 offset:1024
	ds_read_b128 v[204:207], v151 offset:2048
	ds_read_b128 v[208:211], v151 offset:3072
	v_lshl_add_u64 v[160:161], s[48:49], 0, v[142:143]
	s_add_i32 m0, s47, 0xc000
	ds_read_b128 v[212:215], v149
	ds_read_b128 v[216:219], v149 offset:1024
	ds_read_b128 v[220:223], v149 offset:2048
	ds_read_b128 v[224:227], v149 offset:3072
	ds_read_b128 v[228:231], v149 offset:4096
	ds_read_b128 v[232:235], v149 offset:5120
	ds_read_b128 v[236:239], v149 offset:6144
	ds_read_b128 v[240:243], v149 offset:7168
	global_load_lds_dwordx4 v[160:161], off
	v_lshl_add_u64 v[160:161], s[48:49], 0, v[140:141]
	s_add_i32 m0, s47, 0xe000
	s_nop 0
	global_load_lds_dwordx4 v[160:161], off
	s_waitcnt vmcnt(8)
	s_waitcnt lgkmcnt(0)
	s_barrier
	v_mfma_f32_16x16x32_bf16 v[126:129], v[170:173], v[212:215], v[126:129]
	v_mfma_f32_16x16x32_bf16 v[122:125], v[178:181], v[212:215], v[122:125]
	v_mfma_f32_16x16x32_bf16 v[110:113], v[170:173], v[220:223], v[110:113]
	v_mfma_f32_16x16x32_bf16 v[106:109], v[178:181], v[220:223], v[106:109]
	v_mfma_f32_16x16x32_bf16 v[94:97], v[170:173], v[228:231], v[94:97]
	v_mfma_f32_16x16x32_bf16 v[90:93], v[178:181], v[228:231], v[90:93]
	v_mfma_f32_16x16x32_bf16 v[78:81], v[170:173], v[236:239], v[78:81]
	v_mfma_f32_16x16x32_bf16 v[74:77], v[178:181], v[236:239], v[74:77]
	v_mfma_f32_16x16x32_bf16 v[126:129], v[174:177], v[216:219], v[126:129]
	v_mfma_f32_16x16x32_bf16 v[122:125], v[182:185], v[216:219], v[122:125]
	v_mfma_f32_16x16x32_bf16 v[110:113], v[174:177], v[224:227], v[110:113]
	v_mfma_f32_16x16x32_bf16 v[106:109], v[182:185], v[224:227], v[106:109]
	v_mfma_f32_16x16x32_bf16 v[94:97], v[174:177], v[232:235], v[94:97]
	v_mfma_f32_16x16x32_bf16 v[90:93], v[182:185], v[232:235], v[90:93]
	v_mfma_f32_16x16x32_bf16 v[78:81], v[174:177], v[240:243], v[78:81]
	v_mfma_f32_16x16x32_bf16 v[74:77], v[182:185], v[240:243], v[74:77]
	v_mfma_f32_16x16x32_bf16 v[118:121], v[196:199], v[212:215], v[118:121]
	v_mfma_f32_16x16x32_bf16 v[114:117], v[204:207], v[212:215], v[114:117]
	v_mfma_f32_16x16x32_bf16 v[102:105], v[196:199], v[220:223], v[102:105]
	v_mfma_f32_16x16x32_bf16 v[98:101], v[204:207], v[220:223], v[98:101]
	v_mfma_f32_16x16x32_bf16 v[86:89], v[196:199], v[228:231], v[86:89]
	v_mfma_f32_16x16x32_bf16 v[82:85], v[204:207], v[228:231], v[82:85]
	v_mfma_f32_16x16x32_bf16 v[70:73], v[196:199], v[236:239], v[70:73]
	v_mfma_f32_16x16x32_bf16 v[66:69], v[204:207], v[236:239], v[66:69]
	v_mfma_f32_16x16x32_bf16 v[118:121], v[200:203], v[216:219], v[118:121]
	v_mfma_f32_16x16x32_bf16 v[114:117], v[208:211], v[216:219], v[114:117]
	v_mfma_f32_16x16x32_bf16 v[102:105], v[200:203], v[224:227], v[102:105]
	v_mfma_f32_16x16x32_bf16 v[98:101], v[208:211], v[224:227], v[98:101]
	v_mfma_f32_16x16x32_bf16 v[86:89], v[200:203], v[232:235], v[86:89]
	v_mfma_f32_16x16x32_bf16 v[82:85], v[208:211], v[232:235], v[82:85]
	v_mfma_f32_16x16x32_bf16 v[70:73], v[200:203], v[240:243], v[70:73]
	v_mfma_f32_16x16x32_bf16 v[66:69], v[208:211], v[240:243], v[66:69]
	s_barrier
	s_add_i32 s38, s61, s89
	v_lshl_add_u64 v[160:161], s[50:51], 0, v[134:135]
	s_mov_b32 m0, s38
	ds_read_b128 v[212:215], v149 offset:16384
	ds_read_b128 v[216:219], v149 offset:17408
	ds_read_b128 v[220:223], v149 offset:18432
	ds_read_b128 v[224:227], v149 offset:19456
	ds_read_b128 v[228:231], v149 offset:20480
	ds_read_b128 v[232:235], v149 offset:21504
	ds_read_b128 v[236:239], v149 offset:22528
	ds_read_b128 v[240:243], v149 offset:23552
	global_load_lds_dwordx4 v[160:161], off
	s_add_i32 m0, s38, 0x2000
	s_add_u32 s38, s50, 0x40000
	v_lshl_add_u64 v[244:245], s[50:51], 0, v[130:131]
	s_addc_u32 s39, s51, 0
	s_add_i32 s61, s72, s89
	global_load_lds_dwordx4 v[244:245], off
	v_lshl_add_u64 v[246:247], s[38:39], 0, v[134:135]
	s_mov_b32 m0, s61
	v_lshl_add_u64 v[248:249], s[82:83], 0, v[132:133]
	global_load_lds_dwordx4 v[246:247], off
	v_lshl_add_u64 v[246:247], s[38:39], 0, v[130:131]
	s_add_i32 m0, s61, 0x2000
	s_nop 0
	global_load_lds_dwordx4 v[246:247], off
	v_lshl_add_u64 v[246:247], s[82:83], 0, v[136:137]
	s_mov_b32 m0, s47
	s_nop 0
	global_load_lds_dwordx4 v[246:247], off
	s_mov_b32 m0, s90
	s_nop 0
	global_load_lds_dwordx4 v[248:249], off
	s_waitcnt vmcnt(8)
	s_waitcnt lgkmcnt(0)
	s_barrier
; #define PG8_STAGE(bufoff, gbase, voff) do { _Pragma("unroll") for (int _i = 0; _i < 2; ++_i) \
;         __builtin_amdgcn_global_load_lds((const unsigned*)((const char*)(gbase) + (voff)[_i]), (PG8_LAS unsigned*)(lds + (bufoff) + ldsw + _i * 8192), 16, 0, 0); } while (0)
; #define PG8_LDA(dst, b, h) do { _Pragma("unroll") for (int m = 0; m < 4; ++m) _Pragma("unroll") for (int k = 0; k < 2; ++k) dst[m][k] = *(const PG8_LAS bf16x8*)(lds + PG8_SA(b, h) + aoff + m * 2048 + k * 1024); } while (0)
; #define PG8_LDB(dst, b, h) do { _Pragma("unroll") for (int n = 0; n < 2; ++n) _Pragma("unroll") for (int k = 0; k < 2; ++k) dst[n][k] = *(const PG8_LAS bf16x8*)(lds + PG8_SB(b, h) + boff + n * 2048 + k * 1024); } while (0)
; #define PG8_MMA(ai, bj, At, Bt) do { __builtin_amdgcn_s_setprio(1); _Pragma("unroll") for (int m = 0; m < 4; ++m) _Pragma("unroll") for (int n = 0; n < 2; ++n) _Pragma("unroll") for (int k = 0; k < 2; ++k) \
;         acc[ai][bj][m][n] = __builtin_amdgcn_mfma_f32_16x16x32_bf16(Bt[n][k], At[m][k], acc[ai][bj][m][n], 0, 0, 0); __builtin_amdgcn_s_setprio(0); } while (0)
; #define PG8_WAIT_V(n) asm volatile("s_waitcnt vmcnt(" #n ")" ::: "memory")
; #define PG8_WAIT_L(n) asm volatile("s_waitcnt lgkmcnt(" #n ")" ::: "memory")
; #define PG8_BAR __builtin_amdgcn_s_barrier()
; #define PG8_SCHED __builtin_amdgcn_sched_barrier(0)
; template <class Epi, class Sched, bool ALIGN_EPI = false, bool SP2 = false>
; __device__ __forceinline__ void gemm_phase(PG8_LAS unsigned char* lds, const Gemm g, const Sched& S, const Epi& E) {
;     ...
;             PG8_WAIT_V(8); PG8_WAIT_L(0); PG8_BAR; PG8_MMA(1, 0, At, B0); PG8_MMA(1, 1, At, B1); PG8_BAR; PG8_SCHED;
;             PG8_LDB(B0, 1, 0); PG8_LDB(B1, 1, 1); PG8_SCHED; PG8_LDA(At, 1, 0); PG8_STAGE(PG8_SA(0, 1), a2 + hstep, voffA);
;             PG8_WAIT_V(8); PG8_WAIT_L(0); PG8_BAR; PG8_MMA(0, 0, At, B0); PG8_MMA(0, 1, At, B1); PG8_BAR; PG8_SCHED;
	v_mfma_f32_16x16x32_bf16 v[62:65], v[170:173], v[212:215], v[62:65]
	v_mfma_f32_16x16x32_bf16 v[58:61], v[178:181], v[212:215], v[58:61]
	v_mfma_f32_16x16x32_bf16 v[46:49], v[170:173], v[220:223], v[46:49]
	v_mfma_f32_16x16x32_bf16 v[42:45], v[178:181], v[220:223], v[42:45]
	v_mfma_f32_16x16x32_bf16 v[28:31], v[170:173], v[228:231], v[28:31]
	v_mfma_f32_16x16x32_bf16 v[24:27], v[178:181], v[228:231], v[24:27]
	v_mfma_f32_16x16x32_bf16 v[12:15], v[170:173], v[236:239], v[12:15]
	v_mfma_f32_16x16x32_bf16 v[8:11], v[178:181], v[236:239], v[8:11]
	v_mfma_f32_16x16x32_bf16 v[62:65], v[174:177], v[216:219], v[62:65]
	v_mfma_f32_16x16x32_bf16 v[58:61], v[182:185], v[216:219], v[58:61]
	v_mfma_f32_16x16x32_bf16 v[46:49], v[174:177], v[224:227], v[46:49]
	v_mfma_f32_16x16x32_bf16 v[42:45], v[182:185], v[224:227], v[42:45]
	v_mfma_f32_16x16x32_bf16 v[28:31], v[174:177], v[232:235], v[28:31]
	v_mfma_f32_16x16x32_bf16 v[24:27], v[182:185], v[232:235], v[24:27]
	v_mfma_f32_16x16x32_bf16 v[12:15], v[174:177], v[240:243], v[12:15]
	v_mfma_f32_16x16x32_bf16 v[8:11], v[182:185], v[240:243], v[8:11]
	v_mfma_f32_16x16x32_bf16 v[54:57], v[196:199], v[212:215], v[54:57]
	v_mfma_f32_16x16x32_bf16 v[50:53], v[204:207], v[212:215], v[50:53]
	v_mfma_f32_16x16x32_bf16 v[38:41], v[196:199], v[220:223], v[38:41]
	v_mfma_f32_16x16x32_bf16 v[34:37], v[204:207], v[220:223], v[34:37]
	v_mfma_f32_16x16x32_bf16 v[20:23], v[196:199], v[228:231], v[20:23]
	v_mfma_f32_16x16x32_bf16 v[16:19], v[204:207], v[228:231], v[16:19]
	v_mfma_f32_16x16x32_bf16 v[4:7], v[196:199], v[236:239], v[4:7]
	v_mfma_f32_16x16x32_bf16 v[0:3], v[204:207], v[236:239], v[0:3]
	v_mfma_f32_16x16x32_bf16 v[54:57], v[200:203], v[216:219], v[54:57]
	v_mfma_f32_16x16x32_bf16 v[50:53], v[208:211], v[216:219], v[50:53]
	v_mfma_f32_16x16x32_bf16 v[38:41], v[200:203], v[224:227], v[38:41]
	v_mfma_f32_16x16x32_bf16 v[34:37], v[208:211], v[224:227], v[34:37]
	v_mfma_f32_16x16x32_bf16 v[20:23], v[200:203], v[232:235], v[20:23]
	v_mfma_f32_16x16x32_bf16 v[16:19], v[208:211], v[232:235], v[16:19]
	v_mfma_f32_16x16x32_bf16 v[4:7], v[200:203], v[240:243], v[4:7]
	v_mfma_f32_16x16x32_bf16 v[0:3], v[208:211], v[240:243], v[0:3]
	s_barrier
	s_add_i32 s61, 0, 0x18000
	v_add_u32_e32 v151, s61, v145
	s_add_i32 s72, 0, 0x1c000
	ds_read_b128 v[170:173], v151
	ds_read_b128 v[174:177], v151 offset:1024
	ds_read_b128 v[178:181], v151 offset:2048
	ds_read_b128 v[182:185], v151 offset:3072
	v_add_u32_e32 v151, s72, v145
	ds_read_b128 v[196:199], v151
	ds_read_b128 v[200:203], v151 offset:1024
	ds_read_b128 v[204:207], v151 offset:2048
	ds_read_b128 v[208:211], v151 offset:3072
	s_add_u32 s38, s82, 0x40000
	s_addc_u32 s39, s83, 0
	s_mov_b32 m0, s91
	v_lshl_add_u64 v[250:251], s[38:39], 0, v[136:137]
	ds_read_b128 v[212:215], v149 offset:32768
	ds_read_b128 v[216:219], v149 offset:33792
	ds_read_b128 v[220:223], v149 offset:34816
	ds_read_b128 v[224:227], v149 offset:35840
	ds_read_b128 v[228:231], v149 offset:36864
	ds_read_b128 v[232:235], v149 offset:37888
	ds_read_b128 v[236:239], v149 offset:38912
	ds_read_b128 v[240:243], v149 offset:39936
	global_load_lds_dwordx4 v[250:251], off
	v_lshl_add_u64 v[250:251], s[38:39], 0, v[132:133]
	s_mov_b32 m0, s92
	s_nop 0
	global_load_lds_dwordx4 v[250:251], off
	s_waitcnt vmcnt(8)
	s_waitcnt lgkmcnt(0)
	s_barrier
	v_mfma_f32_16x16x32_bf16 v[126:129], v[170:173], v[212:215], v[126:129]
	v_mfma_f32_16x16x32_bf16 v[122:125], v[178:181], v[212:215], v[122:125]
	v_mfma_f32_16x16x32_bf16 v[110:113], v[170:173], v[220:223], v[110:113]
	v_mfma_f32_16x16x32_bf16 v[106:109], v[178:181], v[220:223], v[106:109]
	v_mfma_f32_16x16x32_bf16 v[94:97], v[170:173], v[228:231], v[94:97]
	v_mfma_f32_16x16x32_bf16 v[90:93], v[178:181], v[228:231], v[90:93]
	v_mfma_f32_16x16x32_bf16 v[78:81], v[170:173], v[236:239], v[78:81]
	v_mfma_f32_16x16x32_bf16 v[74:77], v[178:181], v[236:239], v[74:77]
	v_mfma_f32_16x16x32_bf16 v[126:129], v[174:177], v[216:219], v[126:129]
	v_mfma_f32_16x16x32_bf16 v[122:125], v[182:185], v[216:219], v[122:125]
	v_mfma_f32_16x16x32_bf16 v[110:113], v[174:177], v[224:227], v[110:113]
	v_mfma_f32_16x16x32_bf16 v[106:109], v[182:185], v[224:227], v[106:109]
	v_mfma_f32_16x16x32_bf16 v[94:97], v[174:177], v[232:235], v[94:97]
	v_mfma_f32_16x16x32_bf16 v[90:93], v[182:185], v[232:235], v[90:93]
	v_mfma_f32_16x16x32_bf16 v[78:81], v[174:177], v[240:243], v[78:81]
	v_mfma_f32_16x16x32_bf16 v[74:77], v[182:185], v[240:243], v[74:77]
	v_mfma_f32_16x16x32_bf16 v[118:121], v[196:199], v[212:215], v[118:121]
	v_mfma_f32_16x16x32_bf16 v[114:117], v[204:207], v[212:215], v[114:117]
	v_mfma_f32_16x16x32_bf16 v[102:105], v[196:199], v[220:223], v[102:105]
	v_mfma_f32_16x16x32_bf16 v[98:101], v[204:207], v[220:223], v[98:101]
	v_mfma_f32_16x16x32_bf16 v[86:89], v[196:199], v[228:231], v[86:89]
	v_mfma_f32_16x16x32_bf16 v[82:85], v[204:207], v[228:231], v[82:85]
	v_mfma_f32_16x16x32_bf16 v[70:73], v[196:199], v[236:239], v[70:73]
	v_mfma_f32_16x16x32_bf16 v[66:69], v[204:207], v[236:239], v[66:69]
	v_mfma_f32_16x16x32_bf16 v[118:121], v[200:203], v[216:219], v[118:121]
	v_mfma_f32_16x16x32_bf16 v[114:117], v[208:211], v[216:219], v[114:117]
	v_mfma_f32_16x16x32_bf16 v[102:105], v[200:203], v[224:227], v[102:105]
	v_mfma_f32_16x16x32_bf16 v[98:101], v[208:211], v[224:227], v[98:101]
	v_mfma_f32_16x16x32_bf16 v[86:89], v[200:203], v[232:235], v[86:89]
	v_mfma_f32_16x16x32_bf16 v[82:85], v[208:211], v[232:235], v[82:85]
	v_mfma_f32_16x16x32_bf16 v[70:73], v[200:203], v[240:243], v[70:73]
	v_mfma_f32_16x16x32_bf16 v[66:69], v[208:211], v[240:243], v[66:69]
	s_barrier
; #define PG8_STAGE(bufoff, gbase, voff) do { _Pragma("unroll") for (int _i = 0; _i < 2; ++_i) \
;         __builtin_amdgcn_global_load_lds((const unsigned*)((const char*)(gbase) + (voff)[_i]), (PG8_LAS unsigned*)(lds + (bufoff) + ldsw + _i * 8192), 16, 0, 0); } while (0)
; #define PG8_LDA(dst, b, h) do { _Pragma("unroll") for (int m = 0; m < 4; ++m) _Pragma("unroll") for (int k = 0; k < 2; ++k) dst[m][k] = *(const PG8_LAS bf16x8*)(lds + PG8_SA(b, h) + aoff + m * 2048 + k * 1024); } while (0)
; #define PG8_MMA(ai, bj, At, Bt) do { __builtin_amdgcn_s_setprio(1); _Pragma("unroll") for (int m = 0; m < 4; ++m) _Pragma("unroll") for (int n = 0; n < 2; ++n) _Pragma("unroll") for (int k = 0; k < 2; ++k) \
;         acc[ai][bj][m][n] = __builtin_amdgcn_mfma_f32_16x16x32_bf16(Bt[n][k], At[m][k], acc[ai][bj][m][n], 0, 0, 0); __builtin_amdgcn_s_setprio(0); } while (0)
; #define PG8_WAIT_V(n) asm volatile("s_waitcnt vmcnt(" #n ")" ::: "memory")
; #define PG8_WAIT_L(n) asm volatile("s_waitcnt lgkmcnt(" #n ")" ::: "memory")
; #define PG8_BAR __builtin_amdgcn_s_barrier()
; #define PG8_SCHED __builtin_amdgcn_sched_barrier(0)
; template <class Epi, class Sched, bool ALIGN_EPI = false, bool SP2 = false>
; __device__ __forceinline__ void gemm_phase(PG8_LAS unsigned char* lds, const Gemm g, const Sched& S, const Epi& E) {
;     ...
;             PG8_LDA(At, 1, 1); PG8_STAGE(PG8_SB(1, 0), b3, voffB); PG8_STAGE(PG8_SB(1, 1), b3 + hstep, voffB); PG8_STAGE(PG8_SA(1, 0), a3, voffA);
;             PG8_WAIT_V(8); PG8_WAIT_L(0); PG8_BAR; PG8_MMA(1, 0, At, B0); PG8_MMA(1, 1, At, B1); PG8_BAR; PG8_SCHED;
;     ...
;         if constexpr (ALIGN_EPI) { if (wr == 0) PG8_BAR; }
	s_add_i32 s38, s61, s89
	v_lshl_add_u64 v[160:161], v[160:161], 0, s[34:35]
	s_mov_b32 m0, s38
	ds_read_b128 v[212:215], v149 offset:49152
	ds_read_b128 v[216:219], v149 offset:50176
	ds_read_b128 v[220:223], v149 offset:51200
	ds_read_b128 v[224:227], v149 offset:52224
	ds_read_b128 v[228:231], v149 offset:53248
	ds_read_b128 v[232:235], v149 offset:54272
	ds_read_b128 v[236:239], v149 offset:55296
	ds_read_b128 v[240:243], v149 offset:56320
	global_load_lds_dwordx4 v[160:161], off
	s_add_i32 m0, s38, 0x2000
	s_add_u32 s38, s50, 0x40080
	v_lshl_add_u64 v[160:161], v[244:245], 0, s[34:35]
	s_addc_u32 s39, s51, 0
	s_add_i32 s50, s72, s89
	global_load_lds_dwordx4 v[160:161], off
	v_lshl_add_u64 v[160:161], s[38:39], 0, v[134:135]
	s_mov_b32 m0, s50
	s_nop 0
	global_load_lds_dwordx4 v[160:161], off
	v_lshl_add_u64 v[160:161], s[38:39], 0, v[130:131]
	s_add_i32 m0, s50, 0x2000
	s_nop 0
	global_load_lds_dwordx4 v[160:161], off
	v_lshl_add_u64 v[160:161], v[246:247], 0, s[34:35]
	s_mov_b32 m0, s93
	s_nop 0
	global_load_lds_dwordx4 v[160:161], off
	v_lshl_add_u64 v[160:161], v[248:249], 0, s[34:35]
	s_mov_b32 m0, s94
	s_nop 0
	global_load_lds_dwordx4 v[160:161], off
	s_waitcnt vmcnt(8)
	s_waitcnt lgkmcnt(0)
	s_barrier
	v_mfma_f32_16x16x32_bf16 v[62:65], v[170:173], v[212:215], v[62:65]
	v_mfma_f32_16x16x32_bf16 v[58:61], v[178:181], v[212:215], v[58:61]
	v_mfma_f32_16x16x32_bf16 v[46:49], v[170:173], v[220:223], v[46:49]
	v_mfma_f32_16x16x32_bf16 v[42:45], v[178:181], v[220:223], v[42:45]
	v_mfma_f32_16x16x32_bf16 v[28:31], v[170:173], v[228:231], v[28:31]
	v_mfma_f32_16x16x32_bf16 v[24:27], v[178:181], v[228:231], v[24:27]
	v_mfma_f32_16x16x32_bf16 v[12:15], v[170:173], v[236:239], v[12:15]
	v_mfma_f32_16x16x32_bf16 v[8:11], v[178:181], v[236:239], v[8:11]
	v_mfma_f32_16x16x32_bf16 v[62:65], v[174:177], v[216:219], v[62:65]
	v_mfma_f32_16x16x32_bf16 v[58:61], v[182:185], v[216:219], v[58:61]
	v_mfma_f32_16x16x32_bf16 v[46:49], v[174:177], v[224:227], v[46:49]
	v_mfma_f32_16x16x32_bf16 v[42:45], v[182:185], v[224:227], v[42:45]
	v_mfma_f32_16x16x32_bf16 v[28:31], v[174:177], v[232:235], v[28:31]
	v_mfma_f32_16x16x32_bf16 v[24:27], v[182:185], v[232:235], v[24:27]
	v_mfma_f32_16x16x32_bf16 v[12:15], v[174:177], v[240:243], v[12:15]
	v_mfma_f32_16x16x32_bf16 v[8:11], v[182:185], v[240:243], v[8:11]
	v_mfma_f32_16x16x32_bf16 v[54:57], v[196:199], v[212:215], v[54:57]
	v_mfma_f32_16x16x32_bf16 v[50:53], v[204:207], v[212:215], v[50:53]
	v_mfma_f32_16x16x32_bf16 v[38:41], v[196:199], v[220:223], v[38:41]
	v_mfma_f32_16x16x32_bf16 v[34:37], v[204:207], v[220:223], v[34:37]
	v_mfma_f32_16x16x32_bf16 v[20:23], v[196:199], v[228:231], v[20:23]
	v_mfma_f32_16x16x32_bf16 v[16:19], v[204:207], v[228:231], v[16:19]
	v_mfma_f32_16x16x32_bf16 v[4:7], v[196:199], v[236:239], v[4:7]
	v_mfma_f32_16x16x32_bf16 v[0:3], v[204:207], v[236:239], v[0:3]
	v_mfma_f32_16x16x32_bf16 v[54:57], v[200:203], v[216:219], v[54:57]
	v_mfma_f32_16x16x32_bf16 v[50:53], v[208:211], v[216:219], v[50:53]
	v_mfma_f32_16x16x32_bf16 v[38:41], v[200:203], v[224:227], v[38:41]
	v_mfma_f32_16x16x32_bf16 v[34:37], v[208:211], v[224:227], v[34:37]
	v_mfma_f32_16x16x32_bf16 v[20:23], v[200:203], v[232:235], v[20:23]
	v_mfma_f32_16x16x32_bf16 v[16:19], v[208:211], v[232:235], v[16:19]
	v_mfma_f32_16x16x32_bf16 v[4:7], v[200:203], v[240:243], v[4:7]
	v_mfma_f32_16x16x32_bf16 v[0:3], v[208:211], v[240:243], v[0:3]
	s_barrier
	s_add_i32 vcc_hi, vcc_hi, 2
	s_add_u32 s97, s97, 0x100
	s_addc_u32 vcc_lo, vcc_lo, 0
	s_add_u32 s48, s48, 0x100
	s_addc_u32 s49, s49, 0
	s_cmp_gt_u32 vcc_hi, 13
	s_cbranch_scc0 .LBB0_444
	s_and_b64 vcc, exec, s[4:5]
	s_cbranch_vccz .LBB0_447
	s_barrier

; #define PG8_STAGE(bufoff, gbase, voff) do { _Pragma("unroll") for (int _i = 0; _i < 2; ++_i) \
;         __builtin_amdgcn_global_load_lds((const unsigned*)((const char*)(gbase) + (voff)[_i]), (PG8_LAS unsigned*)(lds + (bufoff) + ldsw + _i * 8192), 16, 0, 0); } while (0)
; #define PG8_LDA(dst, b, h) do { _Pragma("unroll") for (int m = 0; m < 4; ++m) _Pragma("unroll") for (int k = 0; k < 2; ++k) dst[m][k] = *(const PG8_LAS bf16x8*)(lds + PG8_SA(b, h) + aoff + m * 2048 + k * 1024); } while (0)
; #define PG8_LDB(dst, b, h) do { _Pragma("unroll") for (int n = 0; n < 2; ++n) _Pragma("unroll") for (int k = 0; k < 2; ++k) dst[n][k] = *(const PG8_LAS bf16x8*)(lds + PG8_SB(b, h) + boff + n * 2048 + k * 1024); } while (0)
; #define PG8_MMA(ai, bj, At, Bt) do { __builtin_amdgcn_s_setprio(1); _Pragma("unroll") for (int m = 0; m < 4; ++m) _Pragma("unroll") for (int n = 0; n < 2; ++n) _Pragma("unroll") for (int k = 0; k < 2; ++k) \
;         acc[ai][bj][m][n] = __builtin_amdgcn_mfma_f32_16x16x32_bf16(Bt[n][k], At[m][k], acc[ai][bj][m][n], 0, 0, 0); __builtin_amdgcn_s_setprio(0); } while (0)
; #define PG8_WAIT_V(n) asm volatile("s_waitcnt vmcnt(" #n ")" ::: "memory")
; #define PG8_WAIT_L(n) asm volatile("s_waitcnt lgkmcnt(" #n ")" ::: "memory")
; template <class Epi, class Sched, bool ALIGN_EPI = false, bool SP2 = false>
; __device__ __forceinline__ void gemm_phase(PG8_LAS unsigned char* lds, const Gemm g, const Sched& S, const Epi& E) {
;     ...
;             const bool last = (t == nt - 2);
;             const char* a1 = cA + (size_t)(t + 1) * kstep;
;             const char* a2 = last ? nA : cA + (size_t)(t + 2) * kstep; const char* b2 = last ? nB : cB + (size_t)(t + 2) * kstep;
;             const char* a3 = a2 + kstep; const char* b3 = b2 + kstep;
;             if (last && has_next) S.a_ready(nxt);
;             if constexpr (SP2) {
;             PG8_LDB(B0, 0, 0); PG8_LDB(B1, 0, 1); PG8_SCHED; PG8_LDA(At, 0, 0); PG8_STAGE(PG8_SA(1, 1), a1 + hstep, voffA);
;             PG8_WAIT_V(8); PG8_WAIT_L(0); PG8_BAR; PG8_MMA(0, 0, At, B0); PG8_MMA(0, 1, At, B1); PG8_BAR; PG8_SCHED;
;             PG8_LDA(At, 0, 1); PG8_STAGE(PG8_SB(0, 0), b2, voffB); PG8_STAGE(PG8_SB(0, 1), b2 + hstep, voffB); PG8_STAGE(PG8_SA(0, 0), a2, voffA);
;             PG8_WAIT_V(8); PG8_WAIT_L(0); PG8_BAR; PG8_MMA(1, 0, At, B0); PG8_MMA(1, 1, At, B1); PG8_BAR; PG8_SCHED;
.LBB0_546:
	s_add_i32 s48, s46, 2
	s_add_u32 s49, s44, 0x80
	s_addc_u32 s47, s45, 0
	s_add_i32 s61, 0, 0x10000
	s_cmp_eq_u32 s87, s46
	s_cselect_b32 s47, s43, s47
	s_cselect_b32 s46, s42, s49
	v_add_u32_e32 v149, s61, v146
	s_cselect_b32 s93, s77, s9
	s_cselect_b32 s92, s76, s0
	s_add_i32 s49, 0, 0x14000
	ds_read_b128 v[142:145], v149
	ds_read_b128 v[150:153], v149 offset:1024
	ds_read_b128 v[154:157], v149 offset:2048
	ds_read_b128 v[158:161], v149 offset:3072
	v_add_u32_e32 v149, s49, v146
	ds_read_b128 v[170:173], v149
	ds_read_b128 v[174:177], v149 offset:1024
	ds_read_b128 v[178:181], v149 offset:2048
	ds_read_b128 v[182:185], v149 offset:3072
	v_lshl_add_u64 v[228:229], s[44:45], 0, v[140:141]
	s_add_i32 m0, s78, 0xc000
	ds_read_b128 v[196:199], v148
	ds_read_b128 v[200:203], v148 offset:1024
	ds_read_b128 v[204:207], v148 offset:2048
	ds_read_b128 v[208:211], v148 offset:3072
	ds_read_b128 v[212:215], v148 offset:4096
	ds_read_b128 v[216:219], v148 offset:5120
	ds_read_b128 v[220:223], v148 offset:6144
	ds_read_b128 v[224:227], v148 offset:7168
	global_load_lds_dwordx4 v[228:229], off
	v_lshl_add_u64 v[228:229], s[44:45], 0, v[138:139]
	s_add_i32 m0, s78, 0xe000
	s_nop 0
	global_load_lds_dwordx4 v[228:229], off
	s_waitcnt vmcnt(8)
	s_waitcnt lgkmcnt(0)
	s_barrier
	v_mfma_f32_16x16x32_bf16 v[126:129], v[142:145], v[196:199], v[126:129]
	v_mfma_f32_16x16x32_bf16 v[122:125], v[154:157], v[196:199], v[122:125]
	v_mfma_f32_16x16x32_bf16 v[110:113], v[142:145], v[204:207], v[110:113]
	v_mfma_f32_16x16x32_bf16 v[106:109], v[154:157], v[204:207], v[106:109]
	v_mfma_f32_16x16x32_bf16 v[94:97], v[142:145], v[212:215], v[94:97]
	v_mfma_f32_16x16x32_bf16 v[90:93], v[154:157], v[212:215], v[90:93]
	v_mfma_f32_16x16x32_bf16 v[78:81], v[142:145], v[220:223], v[78:81]
	v_mfma_f32_16x16x32_bf16 v[74:77], v[154:157], v[220:223], v[74:77]
	v_mfma_f32_16x16x32_bf16 v[126:129], v[150:153], v[200:203], v[126:129]
	v_mfma_f32_16x16x32_bf16 v[122:125], v[158:161], v[200:203], v[122:125]
	v_mfma_f32_16x16x32_bf16 v[110:113], v[150:153], v[208:211], v[110:113]
	v_mfma_f32_16x16x32_bf16 v[106:109], v[158:161], v[208:211], v[106:109]
	v_mfma_f32_16x16x32_bf16 v[94:97], v[150:153], v[216:219], v[94:97]
	v_mfma_f32_16x16x32_bf16 v[90:93], v[158:161], v[216:219], v[90:93]
	v_mfma_f32_16x16x32_bf16 v[78:81], v[150:153], v[224:227], v[78:81]
	v_mfma_f32_16x16x32_bf16 v[74:77], v[158:161], v[224:227], v[74:77]
	v_mfma_f32_16x16x32_bf16 v[118:121], v[170:173], v[196:199], v[118:121]
	v_mfma_f32_16x16x32_bf16 v[114:117], v[178:181], v[196:199], v[114:117]
	v_mfma_f32_16x16x32_bf16 v[102:105], v[170:173], v[204:207], v[102:105]
	v_mfma_f32_16x16x32_bf16 v[98:101], v[178:181], v[204:207], v[98:101]
	v_mfma_f32_16x16x32_bf16 v[86:89], v[170:173], v[212:215], v[86:89]
	v_mfma_f32_16x16x32_bf16 v[82:85], v[178:181], v[212:215], v[82:85]
	v_mfma_f32_16x16x32_bf16 v[70:73], v[170:173], v[220:223], v[70:73]
	v_mfma_f32_16x16x32_bf16 v[66:69], v[178:181], v[220:223], v[66:69]
	v_mfma_f32_16x16x32_bf16 v[118:121], v[174:177], v[200:203], v[118:121]
	v_mfma_f32_16x16x32_bf16 v[114:117], v[182:185], v[200:203], v[114:117]
	v_mfma_f32_16x16x32_bf16 v[102:105], v[174:177], v[208:211], v[102:105]
	v_mfma_f32_16x16x32_bf16 v[98:101], v[182:185], v[208:211], v[98:101]
	v_mfma_f32_16x16x32_bf16 v[86:89], v[174:177], v[216:219], v[86:89]
	v_mfma_f32_16x16x32_bf16 v[82:85], v[182:185], v[216:219], v[82:85]
	v_mfma_f32_16x16x32_bf16 v[70:73], v[174:177], v[224:227], v[70:73]
	v_mfma_f32_16x16x32_bf16 v[66:69], v[182:185], v[224:227], v[66:69]
	s_barrier
	s_add_i32 s61, s61, s51
	v_lshl_add_u64 v[228:229], s[92:93], 0, v[132:133]
	s_mov_b32 m0, s61
	ds_read_b128 v[196:199], v148 offset:16384
	ds_read_b128 v[200:203], v148 offset:17408
	ds_read_b128 v[204:207], v148 offset:18432
	ds_read_b128 v[208:211], v148 offset:19456
	ds_read_b128 v[212:215], v148 offset:20480
	ds_read_b128 v[216:219], v148 offset:21504
	ds_read_b128 v[220:223], v148 offset:22528
	ds_read_b128 v[224:227], v148 offset:23552
	global_load_lds_dwordx4 v[228:229], off
	s_add_i32 m0, s61, 0x2000
	v_lshl_add_u64 v[230:231], s[92:93], 0, v[136:137]
	s_add_u32 s92, s92, s8
	s_addc_u32 s93, s93, 0
	s_add_i32 s49, s49, s51
	global_load_lds_dwordx4 v[230:231], off
	v_lshl_add_u64 v[232:233], s[92:93], 0, v[132:133]
	s_mov_b32 m0, s49
	v_lshl_add_u64 v[234:235], s[92:93], 0, v[136:137]
	global_load_lds_dwordx4 v[232:233], off
	s_add_i32 m0, s49, 0x2000
	v_lshl_add_u64 v[236:237], s[46:47], 0, v[130:131]
	global_load_lds_dwordx4 v[234:235], off
	s_mov_b32 m0, s78
	v_lshl_add_u64 v[238:239], s[46:47], 0, v[134:135]
	global_load_lds_dwordx4 v[236:237], off
	s_mov_b32 m0, s79
	s_nop 0
	global_load_lds_dwordx4 v[238:239], off
	s_waitcnt vmcnt(8)
	s_waitcnt lgkmcnt(0)
	s_barrier
; #define PG8_STAGE(bufoff, gbase, voff) do { _Pragma("unroll") for (int _i = 0; _i < 2; ++_i) \
;         __builtin_amdgcn_global_load_lds((const unsigned*)((const char*)(gbase) + (voff)[_i]), (PG8_LAS unsigned*)(lds + (bufoff) + ldsw + _i * 8192), 16, 0, 0); } while (0)
; #define PG8_LDA(dst, b, h) do { _Pragma("unroll") for (int m = 0; m < 4; ++m) _Pragma("unroll") for (int k = 0; k < 2; ++k) dst[m][k] = *(const PG8_LAS bf16x8*)(lds + PG8_SA(b, h) + aoff + m * 2048 + k * 1024); } while (0)
; #define PG8_LDB(dst, b, h) do { _Pragma("unroll") for (int n = 0; n < 2; ++n) _Pragma("unroll") for (int k = 0; k < 2; ++k) dst[n][k] = *(const PG8_LAS bf16x8*)(lds + PG8_SB(b, h) + boff + n * 2048 + k * 1024); } while (0)
; #define PG8_MMA(ai, bj, At, Bt) do { __builtin_amdgcn_s_setprio(1); _Pragma("unroll") for (int m = 0; m < 4; ++m) _Pragma("unroll") for (int n = 0; n < 2; ++n) _Pragma("unroll") for (int k = 0; k < 2; ++k) \
;         acc[ai][bj][m][n] = __builtin_amdgcn_mfma_f32_16x16x32_bf16(Bt[n][k], At[m][k], acc[ai][bj][m][n], 0, 0, 0); __builtin_amdgcn_s_setprio(0); } while (0)
; #define PG8_WAIT_V(n) asm volatile("s_waitcnt vmcnt(" #n ")" ::: "memory")
; #define PG8_WAIT_L(n) asm volatile("s_waitcnt lgkmcnt(" #n ")" ::: "memory")
; #define PG8_BAR __builtin_amdgcn_s_barrier()
; #define PG8_SCHED __builtin_amdgcn_sched_barrier(0)
; template <class Epi, class Sched, bool ALIGN_EPI = false, bool SP2 = false>
; __device__ __forceinline__ void gemm_phase(PG8_LAS unsigned char* lds, const Gemm g, const Sched& S, const Epi& E) {
;     ...
;             PG8_WAIT_V(8); PG8_WAIT_L(0); PG8_BAR; PG8_MMA(1, 0, At, B0); PG8_MMA(1, 1, At, B1); PG8_BAR; PG8_SCHED;
;             PG8_LDB(B0, 1, 0); PG8_LDB(B1, 1, 1); PG8_SCHED; PG8_LDA(At, 1, 0); PG8_STAGE(PG8_SA(0, 1), a2 + hstep, voffA);
;             PG8_WAIT_V(8); PG8_WAIT_L(0); PG8_BAR; PG8_MMA(0, 0, At, B0); PG8_MMA(0, 1, At, B1); PG8_BAR; PG8_SCHED;
	v_mfma_f32_16x16x32_bf16 v[62:65], v[142:145], v[196:199], v[62:65]
	v_mfma_f32_16x16x32_bf16 v[58:61], v[154:157], v[196:199], v[58:61]
	v_mfma_f32_16x16x32_bf16 v[46:49], v[142:145], v[204:207], v[46:49]
	v_mfma_f32_16x16x32_bf16 v[42:45], v[154:157], v[204:207], v[42:45]
	v_mfma_f32_16x16x32_bf16 v[28:31], v[142:145], v[212:215], v[28:31]
	v_mfma_f32_16x16x32_bf16 v[24:27], v[154:157], v[212:215], v[24:27]
	v_mfma_f32_16x16x32_bf16 v[12:15], v[142:145], v[220:223], v[12:15]
	v_mfma_f32_16x16x32_bf16 v[8:11], v[154:157], v[220:223], v[8:11]
	v_mfma_f32_16x16x32_bf16 v[62:65], v[150:153], v[200:203], v[62:65]
	v_mfma_f32_16x16x32_bf16 v[58:61], v[158:161], v[200:203], v[58:61]
	v_mfma_f32_16x16x32_bf16 v[46:49], v[150:153], v[208:211], v[46:49]
	v_mfma_f32_16x16x32_bf16 v[42:45], v[158:161], v[208:211], v[42:45]
	v_mfma_f32_16x16x32_bf16 v[28:31], v[150:153], v[216:219], v[28:31]
	v_mfma_f32_16x16x32_bf16 v[24:27], v[158:161], v[216:219], v[24:27]
	v_mfma_f32_16x16x32_bf16 v[12:15], v[150:153], v[224:227], v[12:15]
	v_mfma_f32_16x16x32_bf16 v[8:11], v[158:161], v[224:227], v[8:11]
	v_mfma_f32_16x16x32_bf16 v[54:57], v[170:173], v[196:199], v[54:57]
	v_mfma_f32_16x16x32_bf16 v[50:53], v[178:181], v[196:199], v[50:53]
	v_mfma_f32_16x16x32_bf16 v[38:41], v[170:173], v[204:207], v[38:41]
	v_mfma_f32_16x16x32_bf16 v[34:37], v[178:181], v[204:207], v[34:37]
	v_mfma_f32_16x16x32_bf16 v[20:23], v[170:173], v[212:215], v[20:23]
	v_mfma_f32_16x16x32_bf16 v[16:19], v[178:181], v[212:215], v[16:19]
	v_mfma_f32_16x16x32_bf16 v[4:7], v[170:173], v[220:223], v[4:7]
	v_mfma_f32_16x16x32_bf16 v[0:3], v[178:181], v[220:223], v[0:3]
	v_mfma_f32_16x16x32_bf16 v[54:57], v[174:177], v[200:203], v[54:57]
	v_mfma_f32_16x16x32_bf16 v[50:53], v[182:185], v[200:203], v[50:53]
	v_mfma_f32_16x16x32_bf16 v[38:41], v[174:177], v[208:211], v[38:41]
	v_mfma_f32_16x16x32_bf16 v[34:37], v[182:185], v[208:211], v[34:37]
	v_mfma_f32_16x16x32_bf16 v[20:23], v[174:177], v[216:219], v[20:23]
	v_mfma_f32_16x16x32_bf16 v[16:19], v[182:185], v[216:219], v[16:19]
	v_mfma_f32_16x16x32_bf16 v[4:7], v[174:177], v[224:227], v[4:7]
	v_mfma_f32_16x16x32_bf16 v[0:3], v[182:185], v[224:227], v[0:3]
	s_barrier
	s_add_i32 s49, 0, 0x18000
	v_add_u32_e32 v149, s49, v146
	s_add_i32 s61, 0, 0x1c000
	ds_read_b128 v[142:145], v149
	ds_read_b128 v[150:153], v149 offset:1024
	ds_read_b128 v[154:157], v149 offset:2048
	ds_read_b128 v[158:161], v149 offset:3072
	v_add_u32_e32 v149, s61, v146
	ds_read_b128 v[170:173], v149
	ds_read_b128 v[174:177], v149 offset:1024
	ds_read_b128 v[178:181], v149 offset:2048
	ds_read_b128 v[182:185], v149 offset:3072
	s_add_u32 s46, s46, s8
	s_addc_u32 s47, s47, 0
	s_mov_b32 m0, s80
	v_lshl_add_u64 v[240:241], s[46:47], 0, v[130:131]
	ds_read_b128 v[196:199], v148 offset:32768
	ds_read_b128 v[200:203], v148 offset:33792
	ds_read_b128 v[204:207], v148 offset:34816
	ds_read_b128 v[208:211], v148 offset:35840
	ds_read_b128 v[212:215], v148 offset:36864
	ds_read_b128 v[216:219], v148 offset:37888
	ds_read_b128 v[220:223], v148 offset:38912
	ds_read_b128 v[224:227], v148 offset:39936
	global_load_lds_dwordx4 v[240:241], off
	v_lshl_add_u64 v[240:241], s[46:47], 0, v[134:135]
	s_mov_b32 m0, s81
	s_nop 0
	global_load_lds_dwordx4 v[240:241], off
	s_waitcnt vmcnt(8)
	s_waitcnt lgkmcnt(0)
	s_barrier
	v_mfma_f32_16x16x32_bf16 v[126:129], v[142:145], v[196:199], v[126:129]
	v_mfma_f32_16x16x32_bf16 v[122:125], v[154:157], v[196:199], v[122:125]
	v_mfma_f32_16x16x32_bf16 v[110:113], v[142:145], v[204:207], v[110:113]
	v_mfma_f32_16x16x32_bf16 v[106:109], v[154:157], v[204:207], v[106:109]
	v_mfma_f32_16x16x32_bf16 v[94:97], v[142:145], v[212:215], v[94:97]
	v_mfma_f32_16x16x32_bf16 v[90:93], v[154:157], v[212:215], v[90:93]
	v_mfma_f32_16x16x32_bf16 v[78:81], v[142:145], v[220:223], v[78:81]
	v_mfma_f32_16x16x32_bf16 v[74:77], v[154:157], v[220:223], v[74:77]
	v_mfma_f32_16x16x32_bf16 v[126:129], v[150:153], v[200:203], v[126:129]
	v_mfma_f32_16x16x32_bf16 v[122:125], v[158:161], v[200:203], v[122:125]
	v_mfma_f32_16x16x32_bf16 v[110:113], v[150:153], v[208:211], v[110:113]
	v_mfma_f32_16x16x32_bf16 v[106:109], v[158:161], v[208:211], v[106:109]
	v_mfma_f32_16x16x32_bf16 v[94:97], v[150:153], v[216:219], v[94:97]
	v_mfma_f32_16x16x32_bf16 v[90:93], v[158:161], v[216:219], v[90:93]
	v_mfma_f32_16x16x32_bf16 v[78:81], v[150:153], v[224:227], v[78:81]
	v_mfma_f32_16x16x32_bf16 v[74:77], v[158:161], v[224:227], v[74:77]
	v_mfma_f32_16x16x32_bf16 v[118:121], v[170:173], v[196:199], v[118:121]
	v_mfma_f32_16x16x32_bf16 v[114:117], v[178:181], v[196:199], v[114:117]
	v_mfma_f32_16x16x32_bf16 v[102:105], v[170:173], v[204:207], v[102:105]
	v_mfma_f32_16x16x32_bf16 v[98:101], v[178:181], v[204:207], v[98:101]
	v_mfma_f32_16x16x32_bf16 v[86:89], v[170:173], v[212:215], v[86:89]
	v_mfma_f32_16x16x32_bf16 v[82:85], v[178:181], v[212:215], v[82:85]
	v_mfma_f32_16x16x32_bf16 v[70:73], v[170:173], v[220:223], v[70:73]
	v_mfma_f32_16x16x32_bf16 v[66:69], v[178:181], v[220:223], v[66:69]
	v_mfma_f32_16x16x32_bf16 v[118:121], v[174:177], v[200:203], v[118:121]
	v_mfma_f32_16x16x32_bf16 v[114:117], v[182:185], v[200:203], v[114:117]
	v_mfma_f32_16x16x32_bf16 v[102:105], v[174:177], v[208:211], v[102:105]
	v_mfma_f32_16x16x32_bf16 v[98:101], v[182:185], v[208:211], v[98:101]
	v_mfma_f32_16x16x32_bf16 v[86:89], v[174:177], v[216:219], v[86:89]
	v_mfma_f32_16x16x32_bf16 v[82:85], v[182:185], v[216:219], v[82:85]
	v_mfma_f32_16x16x32_bf16 v[70:73], v[174:177], v[224:227], v[70:73]
	v_mfma_f32_16x16x32_bf16 v[66:69], v[182:185], v[224:227], v[66:69]
	s_barrier
; #define PG8_STAGE(bufoff, gbase, voff) do { _Pragma("unroll") for (int _i = 0; _i < 2; ++_i) \
;         __builtin_amdgcn_global_load_lds((const unsigned*)((const char*)(gbase) + (voff)[_i]), (PG8_LAS unsigned*)(lds + (bufoff) + ldsw + _i * 8192), 16, 0, 0); } while (0)
; #define PG8_LDA(dst, b, h) do { _Pragma("unroll") for (int m = 0; m < 4; ++m) _Pragma("unroll") for (int k = 0; k < 2; ++k) dst[m][k] = *(const PG8_LAS bf16x8*)(lds + PG8_SA(b, h) + aoff + m * 2048 + k * 1024); } while (0)
; #define PG8_MMA(ai, bj, At, Bt) do { __builtin_amdgcn_s_setprio(1); _Pragma("unroll") for (int m = 0; m < 4; ++m) _Pragma("unroll") for (int n = 0; n < 2; ++n) _Pragma("unroll") for (int k = 0; k < 2; ++k) \
;         acc[ai][bj][m][n] = __builtin_amdgcn_mfma_f32_16x16x32_bf16(Bt[n][k], At[m][k], acc[ai][bj][m][n], 0, 0, 0); __builtin_amdgcn_s_setprio(0); } while (0)
; #define PG8_WAIT_V(n) asm volatile("s_waitcnt vmcnt(" #n ")" ::: "memory")
; #define PG8_WAIT_L(n) asm volatile("s_waitcnt lgkmcnt(" #n ")" ::: "memory")
; #define PG8_BAR __builtin_amdgcn_s_barrier()
; #define PG8_SCHED __builtin_amdgcn_sched_barrier(0)
; template <class Epi, class Sched, bool ALIGN_EPI = false, bool SP2 = false>
; __device__ __forceinline__ void gemm_phase(PG8_LAS unsigned char* lds, const Gemm g, const Sched& S, const Epi& E) {
;     ...
;             PG8_LDA(At, 1, 1); PG8_STAGE(PG8_SB(1, 0), b3, voffB); PG8_STAGE(PG8_SB(1, 1), b3 + hstep, voffB); PG8_STAGE(PG8_SA(1, 0), a3, voffA);
;             PG8_WAIT_V(8); PG8_WAIT_L(0); PG8_BAR; PG8_MMA(1, 0, At, B0); PG8_MMA(1, 1, At, B1); PG8_BAR; PG8_SCHED;
;     ...
;         if constexpr (ALIGN_EPI) { if (wr == 0) PG8_BAR; }
	s_add_i32 s46, s49, s51
	v_lshl_add_u64 v[228:229], v[228:229], 0, s[34:35]
	s_mov_b32 m0, s46
	ds_read_b128 v[196:199], v148 offset:49152
	ds_read_b128 v[200:203], v148 offset:50176
	ds_read_b128 v[204:207], v148 offset:51200
	ds_read_b128 v[208:211], v148 offset:52224
	ds_read_b128 v[212:215], v148 offset:53248
	ds_read_b128 v[216:219], v148 offset:54272
	ds_read_b128 v[220:223], v148 offset:55296
	ds_read_b128 v[224:227], v148 offset:56320
	global_load_lds_dwordx4 v[228:229], off
	v_lshl_add_u64 v[228:229], v[230:231], 0, s[34:35]
	s_add_i32 m0, s46, 0x2000
	s_add_i32 s46, s61, s51
	global_load_lds_dwordx4 v[228:229], off
	v_lshl_add_u64 v[228:229], v[232:233], 0, s[34:35]
	s_mov_b32 m0, s46
	s_nop 0
	global_load_lds_dwordx4 v[228:229], off
	v_lshl_add_u64 v[228:229], v[234:235], 0, s[34:35]
	s_add_i32 m0, s46, 0x2000
	s_nop 0
	global_load_lds_dwordx4 v[228:229], off
	v_lshl_add_u64 v[228:229], v[236:237], 0, s[34:35]
	s_mov_b32 m0, s83
	s_nop 0
	global_load_lds_dwordx4 v[228:229], off
	v_lshl_add_u64 v[228:229], v[238:239], 0, s[34:35]
	s_mov_b32 m0, s84
	s_nop 0
	global_load_lds_dwordx4 v[228:229], off
	s_waitcnt vmcnt(8)
	s_waitcnt lgkmcnt(0)
	s_barrier
	v_mfma_f32_16x16x32_bf16 v[62:65], v[142:145], v[196:199], v[62:65]
	v_mfma_f32_16x16x32_bf16 v[58:61], v[154:157], v[196:199], v[58:61]
	v_mfma_f32_16x16x32_bf16 v[46:49], v[142:145], v[204:207], v[46:49]
	v_mfma_f32_16x16x32_bf16 v[42:45], v[154:157], v[204:207], v[42:45]
	v_mfma_f32_16x16x32_bf16 v[28:31], v[142:145], v[212:215], v[28:31]
	v_mfma_f32_16x16x32_bf16 v[24:27], v[154:157], v[212:215], v[24:27]
	v_mfma_f32_16x16x32_bf16 v[12:15], v[142:145], v[220:223], v[12:15]
	v_mfma_f32_16x16x32_bf16 v[8:11], v[154:157], v[220:223], v[8:11]
	v_mfma_f32_16x16x32_bf16 v[62:65], v[150:153], v[200:203], v[62:65]
	v_mfma_f32_16x16x32_bf16 v[58:61], v[158:161], v[200:203], v[58:61]
	v_mfma_f32_16x16x32_bf16 v[46:49], v[150:153], v[208:211], v[46:49]
	v_mfma_f32_16x16x32_bf16 v[42:45], v[158:161], v[208:211], v[42:45]
	v_mfma_f32_16x16x32_bf16 v[28:31], v[150:153], v[216:219], v[28:31]
	v_mfma_f32_16x16x32_bf16 v[24:27], v[158:161], v[216:219], v[24:27]
	v_mfma_f32_16x16x32_bf16 v[12:15], v[150:153], v[224:227], v[12:15]
	v_mfma_f32_16x16x32_bf16 v[8:11], v[158:161], v[224:227], v[8:11]
	v_mfma_f32_16x16x32_bf16 v[54:57], v[170:173], v[196:199], v[54:57]
	v_mfma_f32_16x16x32_bf16 v[50:53], v[178:181], v[196:199], v[50:53]
	v_mfma_f32_16x16x32_bf16 v[38:41], v[170:173], v[204:207], v[38:41]
	v_mfma_f32_16x16x32_bf16 v[34:37], v[178:181], v[204:207], v[34:37]
	v_mfma_f32_16x16x32_bf16 v[20:23], v[170:173], v[212:215], v[20:23]
	v_mfma_f32_16x16x32_bf16 v[16:19], v[178:181], v[212:215], v[16:19]
	v_mfma_f32_16x16x32_bf16 v[4:7], v[170:173], v[220:223], v[4:7]
	v_mfma_f32_16x16x32_bf16 v[0:3], v[178:181], v[220:223], v[0:3]
	v_mfma_f32_16x16x32_bf16 v[54:57], v[174:177], v[200:203], v[54:57]
	v_mfma_f32_16x16x32_bf16 v[50:53], v[182:185], v[200:203], v[50:53]
	v_mfma_f32_16x16x32_bf16 v[38:41], v[174:177], v[208:211], v[38:41]
	v_mfma_f32_16x16x32_bf16 v[34:37], v[182:185], v[208:211], v[34:37]
	v_mfma_f32_16x16x32_bf16 v[20:23], v[174:177], v[216:219], v[20:23]
	v_mfma_f32_16x16x32_bf16 v[16:19], v[182:185], v[216:219], v[16:19]
	v_mfma_f32_16x16x32_bf16 v[4:7], v[174:177], v[224:227], v[4:7]
	v_mfma_f32_16x16x32_bf16 v[0:3], v[182:185], v[224:227], v[0:3]
	s_barrier
	s_add_u32 s0, s0, 0x100
	s_addc_u32 s9, s9, 0
	s_add_u32 s44, s44, 0x100
	s_addc_u32 s45, s45, 0
	s_cmp_ge_u32 s48, s85
	s_mov_b32 s46, s48
	s_cbranch_scc0 .LBB0_546
	s_and_b64 vcc, exec, s[40:41]
	s_cbranch_vccz .LBB0_549
	s_barrier

; #define PG8_STAGE(bufoff, gbase, voff) do { _Pragma("unroll") for (int _i = 0; _i < 2; ++_i) \
;         __builtin_amdgcn_global_load_lds((const unsigned*)((const char*)(gbase) + (voff)[_i]), (PG8_LAS unsigned*)(lds + (bufoff) + ldsw + _i * 8192), 16, 0, 0); } while (0)
; #define PG8_LDA(dst, b, h) do { _Pragma("unroll") for (int m = 0; m < 4; ++m) _Pragma("unroll") for (int k = 0; k < 2; ++k) dst[m][k] = *(const PG8_LAS bf16x8*)(lds + PG8_SA(b, h) + aoff + m * 2048 + k * 1024); } while (0)
; #define PG8_LDB(dst, b, h) do { _Pragma("unroll") for (int n = 0; n < 2; ++n) _Pragma("unroll") for (int k = 0; k < 2; ++k) dst[n][k] = *(const PG8_LAS bf16x8*)(lds + PG8_SB(b, h) + boff + n * 2048 + k * 1024); } while (0)
; #define PG8_MMA(ai, bj, At, Bt) do { __builtin_amdgcn_s_setprio(1); _Pragma("unroll") for (int m = 0; m < 4; ++m) _Pragma("unroll") for (int n = 0; n < 2; ++n) _Pragma("unroll") for (int k = 0; k < 2; ++k) \
;         acc[ai][bj][m][n] = __builtin_amdgcn_mfma_f32_16x16x32_bf16(Bt[n][k], At[m][k], acc[ai][bj][m][n], 0, 0, 0); __builtin_amdgcn_s_setprio(0); } while (0)
; #define PG8_WAIT_V(n) asm volatile("s_waitcnt vmcnt(" #n ")" ::: "memory")
; #define PG8_WAIT_L(n) asm volatile("s_waitcnt lgkmcnt(" #n ")" ::: "memory")
; template <class Epi, class Sched, bool ALIGN_EPI = false, bool SP2 = false>
; __device__ __forceinline__ void gemm_phase(PG8_LAS unsigned char* lds, const Gemm g, const Sched& S, const Epi& E) {
;     ...
;             const bool last = (t == nt - 2);
;             const char* a1 = cA + (size_t)(t + 1) * kstep;
;             const char* a2 = last ? nA : cA + (size_t)(t + 2) * kstep; const char* b2 = last ? nB : cB + (size_t)(t + 2) * kstep;
;             const char* a3 = a2 + kstep; const char* b3 = b2 + kstep;
;             if (last && has_next) S.a_ready(nxt);
;             if constexpr (SP2) {
;             PG8_LDB(B0, 0, 0); PG8_LDB(B1, 0, 1); PG8_SCHED; PG8_LDA(At, 0, 0); PG8_STAGE(PG8_SA(1, 1), a1 + hstep, voffA);
;             PG8_WAIT_V(8); PG8_WAIT_L(0); PG8_BAR; PG8_MMA(0, 0, At, B0); PG8_MMA(0, 1, At, B1); PG8_BAR; PG8_SCHED;
;             PG8_LDA(At, 0, 1); PG8_STAGE(PG8_SB(0, 0), b2, voffB); PG8_STAGE(PG8_SB(0, 1), b2 + hstep, voffB); PG8_STAGE(PG8_SA(0, 0), a2, voffA);
;             PG8_WAIT_V(8); PG8_WAIT_L(0); PG8_BAR; PG8_MMA(1, 0, At, B0); PG8_MMA(1, 1, At, B1); PG8_BAR; PG8_SCHED;
.LBB0_580:
	s_add_u32 s48, s46, 0xfffc0080
	s_addc_u32 s49, s47, -1
	s_add_i32 s82, 0, 0x10000
	s_cmp_eq_u32 s81, 12
	s_cselect_b32 s51, s9, s49
	s_cselect_b32 s50, s66, s48
	v_add_u32_e32 v151, s82, v145
	s_cselect_b32 s49, s7, s80
	s_cselect_b32 s48, s67, s79
	s_add_i32 s84, 0, 0x14000
	ds_read_b128 v[170:173], v151
	ds_read_b128 v[174:177], v151 offset:1024
	ds_read_b128 v[178:181], v151 offset:2048
	ds_read_b128 v[182:185], v151 offset:3072
	v_add_u32_e32 v151, s84, v145
	ds_read_b128 v[196:199], v151
	ds_read_b128 v[200:203], v151 offset:1024
	ds_read_b128 v[204:207], v151 offset:2048
	ds_read_b128 v[208:211], v151 offset:3072
	v_lshl_add_u64 v[160:161], s[46:47], 0, v[142:143]
	s_add_i32 m0, s71, 0xc000
	ds_read_b128 v[212:215], v149
	ds_read_b128 v[216:219], v149 offset:1024
	ds_read_b128 v[220:223], v149 offset:2048
	ds_read_b128 v[224:227], v149 offset:3072
	ds_read_b128 v[228:231], v149 offset:4096
	ds_read_b128 v[232:235], v149 offset:5120
	ds_read_b128 v[236:239], v149 offset:6144
	ds_read_b128 v[240:243], v149 offset:7168
	global_load_lds_dwordx4 v[160:161], off
	v_lshl_add_u64 v[160:161], s[46:47], 0, v[140:141]
	s_add_i32 m0, s71, 0xe000
	s_nop 0
	global_load_lds_dwordx4 v[160:161], off
	s_waitcnt vmcnt(8)
	s_waitcnt lgkmcnt(0)
	s_barrier
	v_mfma_f32_16x16x32_bf16 v[126:129], v[170:173], v[212:215], v[126:129]
	v_mfma_f32_16x16x32_bf16 v[122:125], v[178:181], v[212:215], v[122:125]
	v_mfma_f32_16x16x32_bf16 v[110:113], v[170:173], v[220:223], v[110:113]
	v_mfma_f32_16x16x32_bf16 v[106:109], v[178:181], v[220:223], v[106:109]
	v_mfma_f32_16x16x32_bf16 v[94:97], v[170:173], v[228:231], v[94:97]
	v_mfma_f32_16x16x32_bf16 v[90:93], v[178:181], v[228:231], v[90:93]
	v_mfma_f32_16x16x32_bf16 v[78:81], v[170:173], v[236:239], v[78:81]
	v_mfma_f32_16x16x32_bf16 v[74:77], v[178:181], v[236:239], v[74:77]
	v_mfma_f32_16x16x32_bf16 v[126:129], v[174:177], v[216:219], v[126:129]
	v_mfma_f32_16x16x32_bf16 v[122:125], v[182:185], v[216:219], v[122:125]
	v_mfma_f32_16x16x32_bf16 v[110:113], v[174:177], v[224:227], v[110:113]
	v_mfma_f32_16x16x32_bf16 v[106:109], v[182:185], v[224:227], v[106:109]
	v_mfma_f32_16x16x32_bf16 v[94:97], v[174:177], v[232:235], v[94:97]
	v_mfma_f32_16x16x32_bf16 v[90:93], v[182:185], v[232:235], v[90:93]
	v_mfma_f32_16x16x32_bf16 v[78:81], v[174:177], v[240:243], v[78:81]
	v_mfma_f32_16x16x32_bf16 v[74:77], v[182:185], v[240:243], v[74:77]
	v_mfma_f32_16x16x32_bf16 v[118:121], v[196:199], v[212:215], v[118:121]
	v_mfma_f32_16x16x32_bf16 v[114:117], v[204:207], v[212:215], v[114:117]
	v_mfma_f32_16x16x32_bf16 v[102:105], v[196:199], v[220:223], v[102:105]
	v_mfma_f32_16x16x32_bf16 v[98:101], v[204:207], v[220:223], v[98:101]
	v_mfma_f32_16x16x32_bf16 v[86:89], v[196:199], v[228:231], v[86:89]
	v_mfma_f32_16x16x32_bf16 v[82:85], v[204:207], v[228:231], v[82:85]
	v_mfma_f32_16x16x32_bf16 v[70:73], v[196:199], v[236:239], v[70:73]
	v_mfma_f32_16x16x32_bf16 v[66:69], v[204:207], v[236:239], v[66:69]
	v_mfma_f32_16x16x32_bf16 v[118:121], v[200:203], v[216:219], v[118:121]
	v_mfma_f32_16x16x32_bf16 v[114:117], v[208:211], v[216:219], v[114:117]
	v_mfma_f32_16x16x32_bf16 v[102:105], v[200:203], v[224:227], v[102:105]
	v_mfma_f32_16x16x32_bf16 v[98:101], v[208:211], v[224:227], v[98:101]
	v_mfma_f32_16x16x32_bf16 v[86:89], v[200:203], v[232:235], v[86:89]
	v_mfma_f32_16x16x32_bf16 v[82:85], v[208:211], v[232:235], v[82:85]
	v_mfma_f32_16x16x32_bf16 v[70:73], v[200:203], v[240:243], v[70:73]
	v_mfma_f32_16x16x32_bf16 v[66:69], v[208:211], v[240:243], v[66:69]
	s_barrier
	s_add_i32 s82, s82, s69
	v_lshl_add_u64 v[160:161], s[48:49], 0, v[134:135]
	s_mov_b32 m0, s82
	ds_read_b128 v[212:215], v149 offset:16384
	ds_read_b128 v[216:219], v149 offset:17408
	ds_read_b128 v[220:223], v149 offset:18432
	ds_read_b128 v[224:227], v149 offset:19456
	ds_read_b128 v[228:231], v149 offset:20480
	ds_read_b128 v[232:235], v149 offset:21504
	ds_read_b128 v[236:239], v149 offset:22528
	ds_read_b128 v[240:243], v149 offset:23552
	global_load_lds_dwordx4 v[160:161], off
	s_add_i32 m0, s82, 0x2000
	s_add_u32 s82, s48, 0x40000
	v_lshl_add_u64 v[244:245], s[48:49], 0, v[130:131]
	s_addc_u32 s83, s49, 0
	s_add_i32 s84, s84, s69
	global_load_lds_dwordx4 v[244:245], off
	v_lshl_add_u64 v[246:247], s[82:83], 0, v[134:135]
	s_mov_b32 m0, s84
	v_lshl_add_u64 v[248:249], s[50:51], 0, v[132:133]
	global_load_lds_dwordx4 v[246:247], off
	v_lshl_add_u64 v[246:247], s[82:83], 0, v[130:131]
	s_add_i32 m0, s84, 0x2000
	s_nop 0
	global_load_lds_dwordx4 v[246:247], off
	v_lshl_add_u64 v[246:247], s[50:51], 0, v[136:137]
	s_mov_b32 m0, s71
	s_nop 0
	global_load_lds_dwordx4 v[246:247], off
	s_mov_b32 m0, s72
	s_nop 0
	global_load_lds_dwordx4 v[248:249], off
	s_waitcnt vmcnt(8)
	s_waitcnt lgkmcnt(0)
	s_barrier
; #define PG8_STAGE(bufoff, gbase, voff) do { _Pragma("unroll") for (int _i = 0; _i < 2; ++_i) \
;         __builtin_amdgcn_global_load_lds((const unsigned*)((const char*)(gbase) + (voff)[_i]), (PG8_LAS unsigned*)(lds + (bufoff) + ldsw + _i * 8192), 16, 0, 0); } while (0)
; #define PG8_LDA(dst, b, h) do { _Pragma("unroll") for (int m = 0; m < 4; ++m) _Pragma("unroll") for (int k = 0; k < 2; ++k) dst[m][k] = *(const PG8_LAS bf16x8*)(lds + PG8_SA(b, h) + aoff + m * 2048 + k * 1024); } while (0)
; #define PG8_LDB(dst, b, h) do { _Pragma("unroll") for (int n = 0; n < 2; ++n) _Pragma("unroll") for (int k = 0; k < 2; ++k) dst[n][k] = *(const PG8_LAS bf16x8*)(lds + PG8_SB(b, h) + boff + n * 2048 + k * 1024); } while (0)
; #define PG8_MMA(ai, bj, At, Bt) do { __builtin_amdgcn_s_setprio(1); _Pragma("unroll") for (int m = 0; m < 4; ++m) _Pragma("unroll") for (int n = 0; n < 2; ++n) _Pragma("unroll") for (int k = 0; k < 2; ++k) \
;         acc[ai][bj][m][n] = __builtin_amdgcn_mfma_f32_16x16x32_bf16(Bt[n][k], At[m][k], acc[ai][bj][m][n], 0, 0, 0); __builtin_amdgcn_s_setprio(0); } while (0)
; #define PG8_WAIT_V(n) asm volatile("s_waitcnt vmcnt(" #n ")" ::: "memory")
; #define PG8_WAIT_L(n) asm volatile("s_waitcnt lgkmcnt(" #n ")" ::: "memory")
; #define PG8_BAR __builtin_amdgcn_s_barrier()
; #define PG8_SCHED __builtin_amdgcn_sched_barrier(0)
; template <class Epi, class Sched, bool ALIGN_EPI = false, bool SP2 = false>
; __device__ __forceinline__ void gemm_phase(PG8_LAS unsigned char* lds, const Gemm g, const Sched& S, const Epi& E) {
;     ...
;             PG8_WAIT_V(8); PG8_WAIT_L(0); PG8_BAR; PG8_MMA(1, 0, At, B0); PG8_MMA(1, 1, At, B1); PG8_BAR; PG8_SCHED;
;             PG8_LDB(B0, 1, 0); PG8_LDB(B1, 1, 1); PG8_SCHED; PG8_LDA(At, 1, 0); PG8_STAGE(PG8_SA(0, 1), a2 + hstep, voffA);
;             PG8_WAIT_V(8); PG8_WAIT_L(0); PG8_BAR; PG8_MMA(0, 0, At, B0); PG8_MMA(0, 1, At, B1); PG8_BAR; PG8_SCHED;
	v_mfma_f32_16x16x32_bf16 v[62:65], v[170:173], v[212:215], v[62:65]
	v_mfma_f32_16x16x32_bf16 v[58:61], v[178:181], v[212:215], v[58:61]
	v_mfma_f32_16x16x32_bf16 v[46:49], v[170:173], v[220:223], v[46:49]
	v_mfma_f32_16x16x32_bf16 v[42:45], v[178:181], v[220:223], v[42:45]
	v_mfma_f32_16x16x32_bf16 v[28:31], v[170:173], v[228:231], v[28:31]
	v_mfma_f32_16x16x32_bf16 v[24:27], v[178:181], v[228:231], v[24:27]
	v_mfma_f32_16x16x32_bf16 v[12:15], v[170:173], v[236:239], v[12:15]
	v_mfma_f32_16x16x32_bf16 v[8:11], v[178:181], v[236:239], v[8:11]
	v_mfma_f32_16x16x32_bf16 v[62:65], v[174:177], v[216:219], v[62:65]
	v_mfma_f32_16x16x32_bf16 v[58:61], v[182:185], v[216:219], v[58:61]
	v_mfma_f32_16x16x32_bf16 v[46:49], v[174:177], v[224:227], v[46:49]
	v_mfma_f32_16x16x32_bf16 v[42:45], v[182:185], v[224:227], v[42:45]
	v_mfma_f32_16x16x32_bf16 v[28:31], v[174:177], v[232:235], v[28:31]
	v_mfma_f32_16x16x32_bf16 v[24:27], v[182:185], v[232:235], v[24:27]
	v_mfma_f32_16x16x32_bf16 v[12:15], v[174:177], v[240:243], v[12:15]
	v_mfma_f32_16x16x32_bf16 v[8:11], v[182:185], v[240:243], v[8:11]
	v_mfma_f32_16x16x32_bf16 v[54:57], v[196:199], v[212:215], v[54:57]
	v_mfma_f32_16x16x32_bf16 v[50:53], v[204:207], v[212:215], v[50:53]
	v_mfma_f32_16x16x32_bf16 v[38:41], v[196:199], v[220:223], v[38:41]
	v_mfma_f32_16x16x32_bf16 v[34:37], v[204:207], v[220:223], v[34:37]
	v_mfma_f32_16x16x32_bf16 v[20:23], v[196:199], v[228:231], v[20:23]
	v_mfma_f32_16x16x32_bf16 v[16:19], v[204:207], v[228:231], v[16:19]
	v_mfma_f32_16x16x32_bf16 v[4:7], v[196:199], v[236:239], v[4:7]
	v_mfma_f32_16x16x32_bf16 v[0:3], v[204:207], v[236:239], v[0:3]
	v_mfma_f32_16x16x32_bf16 v[54:57], v[200:203], v[216:219], v[54:57]
	v_mfma_f32_16x16x32_bf16 v[50:53], v[208:211], v[216:219], v[50:53]
	v_mfma_f32_16x16x32_bf16 v[38:41], v[200:203], v[224:227], v[38:41]
	v_mfma_f32_16x16x32_bf16 v[34:37], v[208:211], v[224:227], v[34:37]
	v_mfma_f32_16x16x32_bf16 v[20:23], v[200:203], v[232:235], v[20:23]
	v_mfma_f32_16x16x32_bf16 v[16:19], v[208:211], v[232:235], v[16:19]
	v_mfma_f32_16x16x32_bf16 v[4:7], v[200:203], v[240:243], v[4:7]
	v_mfma_f32_16x16x32_bf16 v[0:3], v[208:211], v[240:243], v[0:3]
	s_barrier
	s_add_i32 s82, 0, 0x18000
	v_add_u32_e32 v151, s82, v145
	s_add_i32 s83, 0, 0x1c000
	ds_read_b128 v[170:173], v151
	ds_read_b128 v[174:177], v151 offset:1024
	ds_read_b128 v[178:181], v151 offset:2048
	ds_read_b128 v[182:185], v151 offset:3072
	v_add_u32_e32 v151, s83, v145
	ds_read_b128 v[196:199], v151
	ds_read_b128 v[200:203], v151 offset:1024
	ds_read_b128 v[204:207], v151 offset:2048
	ds_read_b128 v[208:211], v151 offset:3072
	s_add_u32 s50, s50, 0x40000
	s_addc_u32 s51, s51, 0
	s_mov_b32 m0, s73
	v_lshl_add_u64 v[250:251], s[50:51], 0, v[136:137]
	ds_read_b128 v[212:215], v149 offset:32768
	ds_read_b128 v[216:219], v149 offset:33792
	ds_read_b128 v[220:223], v149 offset:34816
	ds_read_b128 v[224:227], v149 offset:35840
	ds_read_b128 v[228:231], v149 offset:36864
	ds_read_b128 v[232:235], v149 offset:37888
	ds_read_b128 v[236:239], v149 offset:38912
	ds_read_b128 v[240:243], v149 offset:39936
	global_load_lds_dwordx4 v[250:251], off
	v_lshl_add_u64 v[250:251], s[50:51], 0, v[132:133]
	s_mov_b32 m0, s76
	s_nop 0
	global_load_lds_dwordx4 v[250:251], off
	s_waitcnt vmcnt(8)
	s_waitcnt lgkmcnt(0)
	s_barrier
	v_mfma_f32_16x16x32_bf16 v[126:129], v[170:173], v[212:215], v[126:129]
	v_mfma_f32_16x16x32_bf16 v[122:125], v[178:181], v[212:215], v[122:125]
	v_mfma_f32_16x16x32_bf16 v[110:113], v[170:173], v[220:223], v[110:113]
	v_mfma_f32_16x16x32_bf16 v[106:109], v[178:181], v[220:223], v[106:109]
	v_mfma_f32_16x16x32_bf16 v[94:97], v[170:173], v[228:231], v[94:97]
	v_mfma_f32_16x16x32_bf16 v[90:93], v[178:181], v[228:231], v[90:93]
	v_mfma_f32_16x16x32_bf16 v[78:81], v[170:173], v[236:239], v[78:81]
	v_mfma_f32_16x16x32_bf16 v[74:77], v[178:181], v[236:239], v[74:77]
	v_mfma_f32_16x16x32_bf16 v[126:129], v[174:177], v[216:219], v[126:129]
	v_mfma_f32_16x16x32_bf16 v[122:125], v[182:185], v[216:219], v[122:125]
	v_mfma_f32_16x16x32_bf16 v[110:113], v[174:177], v[224:227], v[110:113]
	v_mfma_f32_16x16x32_bf16 v[106:109], v[182:185], v[224:227], v[106:109]
	v_mfma_f32_16x16x32_bf16 v[94:97], v[174:177], v[232:235], v[94:97]
	v_mfma_f32_16x16x32_bf16 v[90:93], v[182:185], v[232:235], v[90:93]
	v_mfma_f32_16x16x32_bf16 v[78:81], v[174:177], v[240:243], v[78:81]
	v_mfma_f32_16x16x32_bf16 v[74:77], v[182:185], v[240:243], v[74:77]
	v_mfma_f32_16x16x32_bf16 v[118:121], v[196:199], v[212:215], v[118:121]
	v_mfma_f32_16x16x32_bf16 v[114:117], v[204:207], v[212:215], v[114:117]
	v_mfma_f32_16x16x32_bf16 v[102:105], v[196:199], v[220:223], v[102:105]
	v_mfma_f32_16x16x32_bf16 v[98:101], v[204:207], v[220:223], v[98:101]
	v_mfma_f32_16x16x32_bf16 v[86:89], v[196:199], v[228:231], v[86:89]
	v_mfma_f32_16x16x32_bf16 v[82:85], v[204:207], v[228:231], v[82:85]
	v_mfma_f32_16x16x32_bf16 v[70:73], v[196:199], v[236:239], v[70:73]
	v_mfma_f32_16x16x32_bf16 v[66:69], v[204:207], v[236:239], v[66:69]
	v_mfma_f32_16x16x32_bf16 v[118:121], v[200:203], v[216:219], v[118:121]
	v_mfma_f32_16x16x32_bf16 v[114:117], v[208:211], v[216:219], v[114:117]
	v_mfma_f32_16x16x32_bf16 v[102:105], v[200:203], v[224:227], v[102:105]
	v_mfma_f32_16x16x32_bf16 v[98:101], v[208:211], v[224:227], v[98:101]
	v_mfma_f32_16x16x32_bf16 v[86:89], v[200:203], v[232:235], v[86:89]
	v_mfma_f32_16x16x32_bf16 v[82:85], v[208:211], v[232:235], v[82:85]
	v_mfma_f32_16x16x32_bf16 v[70:73], v[200:203], v[240:243], v[70:73]
	v_mfma_f32_16x16x32_bf16 v[66:69], v[208:211], v[240:243], v[66:69]
	s_barrier
; #define PG8_STAGE(bufoff, gbase, voff) do { _Pragma("unroll") for (int _i = 0; _i < 2; ++_i) \
;         __builtin_amdgcn_global_load_lds((const unsigned*)((const char*)(gbase) + (voff)[_i]), (PG8_LAS unsigned*)(lds + (bufoff) + ldsw + _i * 8192), 16, 0, 0); } while (0)
; #define PG8_LDA(dst, b, h) do { _Pragma("unroll") for (int m = 0; m < 4; ++m) _Pragma("unroll") for (int k = 0; k < 2; ++k) dst[m][k] = *(const PG8_LAS bf16x8*)(lds + PG8_SA(b, h) + aoff + m * 2048 + k * 1024); } while (0)
; #define PG8_MMA(ai, bj, At, Bt) do { __builtin_amdgcn_s_setprio(1); _Pragma("unroll") for (int m = 0; m < 4; ++m) _Pragma("unroll") for (int n = 0; n < 2; ++n) _Pragma("unroll") for (int k = 0; k < 2; ++k) \
;         acc[ai][bj][m][n] = __builtin_amdgcn_mfma_f32_16x16x32_bf16(Bt[n][k], At[m][k], acc[ai][bj][m][n], 0, 0, 0); __builtin_amdgcn_s_setprio(0); } while (0)
; #define PG8_WAIT_V(n) asm volatile("s_waitcnt vmcnt(" #n ")" ::: "memory")
; #define PG8_WAIT_L(n) asm volatile("s_waitcnt lgkmcnt(" #n ")" ::: "memory")
; #define PG8_BAR __builtin_amdgcn_s_barrier()
; #define PG8_SCHED __builtin_amdgcn_sched_barrier(0)
; template <class Epi, class Sched, bool ALIGN_EPI = false, bool SP2 = false>
; __device__ __forceinline__ void gemm_phase(PG8_LAS unsigned char* lds, const Gemm g, const Sched& S, const Epi& E) {
;     ...
;             PG8_LDA(At, 1, 1); PG8_STAGE(PG8_SB(1, 0), b3, voffB); PG8_STAGE(PG8_SB(1, 1), b3 + hstep, voffB); PG8_STAGE(PG8_SA(1, 0), a3, voffA);
;             PG8_WAIT_V(8); PG8_WAIT_L(0); PG8_BAR; PG8_MMA(1, 0, At, B0); PG8_MMA(1, 1, At, B1); PG8_BAR; PG8_SCHED;
;     ...
;         if constexpr (ALIGN_EPI) { if (wr == 0) PG8_BAR; }
	s_add_i32 s50, s82, s69
	v_lshl_add_u64 v[160:161], v[160:161], 0, s[34:35]
	s_mov_b32 m0, s50
	ds_read_b128 v[212:215], v149 offset:49152
	ds_read_b128 v[216:219], v149 offset:50176
	ds_read_b128 v[220:223], v149 offset:51200
	ds_read_b128 v[224:227], v149 offset:52224
	ds_read_b128 v[228:231], v149 offset:53248
	ds_read_b128 v[232:235], v149 offset:54272
	ds_read_b128 v[236:239], v149 offset:55296
	ds_read_b128 v[240:243], v149 offset:56320
	global_load_lds_dwordx4 v[160:161], off
	s_add_i32 m0, s50, 0x2000
	s_add_u32 s48, s48, 0x40080
	v_lshl_add_u64 v[160:161], v[244:245], 0, s[34:35]
	s_addc_u32 s49, s49, 0
	s_add_i32 s50, s83, s69
	global_load_lds_dwordx4 v[160:161], off
	v_lshl_add_u64 v[160:161], s[48:49], 0, v[134:135]
	s_mov_b32 m0, s50
	s_nop 0
	global_load_lds_dwordx4 v[160:161], off
	v_lshl_add_u64 v[160:161], s[48:49], 0, v[130:131]
	s_add_i32 m0, s50, 0x2000
	s_nop 0
	global_load_lds_dwordx4 v[160:161], off
	v_lshl_add_u64 v[160:161], v[246:247], 0, s[34:35]
	s_mov_b32 m0, s77
	s_nop 0
	global_load_lds_dwordx4 v[160:161], off
	v_lshl_add_u64 v[160:161], v[248:249], 0, s[34:35]
	s_mov_b32 m0, s78
	s_nop 0
	global_load_lds_dwordx4 v[160:161], off
	s_waitcnt vmcnt(8)
	s_waitcnt lgkmcnt(0)
	s_barrier
	v_mfma_f32_16x16x32_bf16 v[62:65], v[170:173], v[212:215], v[62:65]
	v_mfma_f32_16x16x32_bf16 v[58:61], v[178:181], v[212:215], v[58:61]
	v_mfma_f32_16x16x32_bf16 v[46:49], v[170:173], v[220:223], v[46:49]
	v_mfma_f32_16x16x32_bf16 v[42:45], v[178:181], v[220:223], v[42:45]
	v_mfma_f32_16x16x32_bf16 v[28:31], v[170:173], v[228:231], v[28:31]
	v_mfma_f32_16x16x32_bf16 v[24:27], v[178:181], v[228:231], v[24:27]
	v_mfma_f32_16x16x32_bf16 v[12:15], v[170:173], v[236:239], v[12:15]
	v_mfma_f32_16x16x32_bf16 v[8:11], v[178:181], v[236:239], v[8:11]
	v_mfma_f32_16x16x32_bf16 v[62:65], v[174:177], v[216:219], v[62:65]
	v_mfma_f32_16x16x32_bf16 v[58:61], v[182:185], v[216:219], v[58:61]
	v_mfma_f32_16x16x32_bf16 v[46:49], v[174:177], v[224:227], v[46:49]
	v_mfma_f32_16x16x32_bf16 v[42:45], v[182:185], v[224:227], v[42:45]
	v_mfma_f32_16x16x32_bf16 v[28:31], v[174:177], v[232:235], v[28:31]
	v_mfma_f32_16x16x32_bf16 v[24:27], v[182:185], v[232:235], v[24:27]
	v_mfma_f32_16x16x32_bf16 v[12:15], v[174:177], v[240:243], v[12:15]
	v_mfma_f32_16x16x32_bf16 v[8:11], v[182:185], v[240:243], v[8:11]
	v_mfma_f32_16x16x32_bf16 v[54:57], v[196:199], v[212:215], v[54:57]
	v_mfma_f32_16x16x32_bf16 v[50:53], v[204:207], v[212:215], v[50:53]
	v_mfma_f32_16x16x32_bf16 v[38:41], v[196:199], v[220:223], v[38:41]
	v_mfma_f32_16x16x32_bf16 v[34:37], v[204:207], v[220:223], v[34:37]
	v_mfma_f32_16x16x32_bf16 v[20:23], v[196:199], v[228:231], v[20:23]
	v_mfma_f32_16x16x32_bf16 v[16:19], v[204:207], v[228:231], v[16:19]
	v_mfma_f32_16x16x32_bf16 v[4:7], v[196:199], v[236:239], v[4:7]
	v_mfma_f32_16x16x32_bf16 v[0:3], v[204:207], v[236:239], v[0:3]
	v_mfma_f32_16x16x32_bf16 v[54:57], v[200:203], v[216:219], v[54:57]
	v_mfma_f32_16x16x32_bf16 v[50:53], v[208:211], v[216:219], v[50:53]
	v_mfma_f32_16x16x32_bf16 v[38:41], v[200:203], v[224:227], v[38:41]
	v_mfma_f32_16x16x32_bf16 v[34:37], v[208:211], v[224:227], v[34:37]
	v_mfma_f32_16x16x32_bf16 v[20:23], v[200:203], v[232:235], v[20:23]
	v_mfma_f32_16x16x32_bf16 v[16:19], v[208:211], v[232:235], v[16:19]
	v_mfma_f32_16x16x32_bf16 v[4:7], v[200:203], v[240:243], v[4:7]
	v_mfma_f32_16x16x32_bf16 v[0:3], v[208:211], v[240:243], v[0:3]
	s_barrier
	s_add_i32 s81, s81, 2
	s_add_u32 s79, s79, 0x100
	s_addc_u32 s80, s80, 0
	s_add_u32 s46, s46, 0x100
	s_addc_u32 s47, s47, 0
	s_cmp_gt_u32 s81, 13
	s_cbranch_scc0 .LBB0_580
	s_and_b64 vcc, exec, s[4:5]
	s_cbranch_vccz .LBB0_583
	s_barrier
